# GEMM K-loops: s_setprio 1 moved before the barrier that starts an MFMA block, s_setprio 0 after the barrier that ends it, duplicate lgkmcnt(0) after the barrier dropped (no scalar instructions left be
# speedup vs baseline: 1.0563x; 1.0030x over previous
; #define PG8_STAGE(bufoff, gbase, voff) do { _Pragma("unroll") for (int _i = 0; _i < 2; ++_i) \
;         __builtin_amdgcn_global_load_lds((const unsigned*)((const char*)(gbase) + (voff)[_i]), (PG8_LAS unsigned*)(lds + (bufoff) + ldsw + _i * 8192), 16, 0, 0); } while (0)
; #define PG8_LDA(dst, b, h) do { _Pragma("unroll") for (int m = 0; m < 4; ++m) _Pragma("unroll") for (int k = 0; k < 2; ++k) dst[m][k] = *(const PG8_LAS bf16x8*)(lds + PG8_SA(b, h) + aoff + m * 2048 + k * 1024); } while (0)
; #define PG8_LDB(dst, b, h) do { _Pragma("unroll") for (int n = 0; n < 2; ++n) _Pragma("unroll") for (int k = 0; k < 2; ++k) dst[n][k] = *(const PG8_LAS bf16x8*)(lds + PG8_SB(b, h) + boff + n * 2048 + k * 1024); } while (0)
; #define PG8_MMA(ai, bj, At, Bt) do { __builtin_amdgcn_s_setprio(1); _Pragma("unroll") for (int m = 0; m < 4; ++m) _Pragma("unroll") for (int n = 0; n < 2; ++n) _Pragma("unroll") for (int k = 0; k < 2; ++k) \
;         acc[ai][bj][m][n] = __builtin_amdgcn_mfma_f32_16x16x32_bf16(Bt[n][k], At[m][k], acc[ai][bj][m][n], 0, 0, 0); __builtin_amdgcn_s_setprio(0); } while (0)
; #define PG8_WAIT_V(n) asm volatile("s_waitcnt vmcnt(" #n ")" ::: "memory")
; #define PG8_WAIT_L(n) asm volatile("s_waitcnt lgkmcnt(" #n ")" ::: "memory")
; #define PG8_BAR __builtin_amdgcn_s_barrier()
; #define PG8_SCHED __builtin_amdgcn_sched_barrier(0)
; template <class Epi, class Sched, bool ALIGN_EPI = false, bool SP2 = false>
; __device__ __forceinline__ void gemm_phase(PG8_LAS unsigned char* lds, const Gemm g, const Sched& S, const Epi& E) {
;     ...
;             PG8_LDB(B0, 0, 0); PG8_LDB(B1, 0, 1); PG8_SCHED; PG8_LDA(At, 0, 0); PG8_STAGE(PG8_SA(1, 1), a1 + hstep, voffA);
;             PG8_WAIT_V(8); PG8_WAIT_L(0); PG8_BAR; PG8_MMA(0, 0, At, B0); PG8_MMA(0, 1, At, B1); PG8_BAR; PG8_SCHED;
;             PG8_LDA(At, 0, 1); PG8_STAGE(PG8_SB(0, 0), b2, voffB); PG8_STAGE(PG8_SB(0, 1), b2 + hstep, voffB); PG8_STAGE(PG8_SA(0, 0), a2, voffA);
;             PG8_WAIT_V(8); PG8_WAIT_L(0); PG8_BAR; PG8_MMA(1, 0, At, B0); PG8_MMA(1, 1, At, B1); PG8_BAR; PG8_SCHED;
.LBB0_162:
	s_add_u32 s10, s44, 0xfffc0080
	s_addc_u32 s11, s45, -1
	s_add_i32 s60, 16, 0x10000
	s_cmp_eq_u32 s59, 12
	s_cselect_b32 s49, s27, s11
	s_cselect_b32 s48, s34, s10
	s_cselect_b32 s47, s25, s58
	s_cselect_b32 s46, s35, s57
	s_add_i32 s10, 16, 0x14000
	v_add_u32_e32 v102, s60, v183
	v_add_u32_e32 v180, s10, v183
	ds_read_b128 v[90:93], v102
	ds_read_b128 v[94:97], v102 offset:1024
	ds_read_b128 v[98:101], v102 offset:2048
	ds_read_b128 v[102:105], v102 offset:3072
	ds_read_b128 v[158:161], v180
	ds_read_b128 v[176:179], v180 offset:1024
	ds_read_b128 v[186:189], v180 offset:2048
	ds_read_b128 v[190:193], v180 offset:3072
	v_lshl_add_u64 v[180:181], s[44:45], 0, v[156:157]
	s_add_i32 m0, s7, 0xc000
	ds_read_b128 v[194:197], v185
	ds_read_b128 v[198:201], v185 offset:1024
	ds_read_b128 v[202:205], v185 offset:2048
	ds_read_b128 v[206:209], v185 offset:3072
	ds_read_b128 v[210:213], v185 offset:4096
	ds_read_b128 v[214:217], v185 offset:5120
	ds_read_b128 v[218:221], v185 offset:6144
	ds_read_b128 v[222:225], v185 offset:7168
	global_load_lds_dwordx4 v[180:181], off
	v_lshl_add_u64 v[180:181], s[44:45], 0, v[154:155]
	s_add_i32 m0, s7, 0xe000
	s_nop 0
	global_load_lds_dwordx4 v[180:181], off
	s_waitcnt vmcnt(8)
	s_waitcnt lgkmcnt(0)
	s_setprio 1
	s_barrier
	v_mfma_f32_16x16x32_bf16 v[142:145], v[90:93], v[194:197], v[142:145]
	v_mfma_f32_16x16x32_bf16 v[138:141], v[98:101], v[194:197], v[138:141]
	v_mfma_f32_16x16x32_bf16 v[126:129], v[90:93], v[202:205], v[126:129]
	v_mfma_f32_16x16x32_bf16 v[122:125], v[98:101], v[202:205], v[122:125]
	v_mfma_f32_16x16x32_bf16 v[110:113], v[90:93], v[210:213], v[110:113]
	v_mfma_f32_16x16x32_bf16 v[106:109], v[98:101], v[210:213], v[106:109]
	v_mfma_f32_16x16x32_bf16 v[78:81], v[90:93], v[218:221], v[78:81]
	v_mfma_f32_16x16x32_bf16 v[74:77], v[98:101], v[218:221], v[74:77]
	v_mfma_f32_16x16x32_bf16 v[142:145], v[94:97], v[198:201], v[142:145]
	v_mfma_f32_16x16x32_bf16 v[138:141], v[102:105], v[198:201], v[138:141]
	v_mfma_f32_16x16x32_bf16 v[126:129], v[94:97], v[206:209], v[126:129]
	v_mfma_f32_16x16x32_bf16 v[122:125], v[102:105], v[206:209], v[122:125]
	v_mfma_f32_16x16x32_bf16 v[110:113], v[94:97], v[214:217], v[110:113]
	v_mfma_f32_16x16x32_bf16 v[106:109], v[102:105], v[214:217], v[106:109]
	v_mfma_f32_16x16x32_bf16 v[78:81], v[94:97], v[222:225], v[78:81]
	v_mfma_f32_16x16x32_bf16 v[74:77], v[102:105], v[222:225], v[74:77]
	s_setprio 0
	s_setprio 1
	v_mfma_f32_16x16x32_bf16 v[134:137], v[158:161], v[194:197], v[134:137]
	v_mfma_f32_16x16x32_bf16 v[130:133], v[186:189], v[194:197], v[130:133]
	v_mfma_f32_16x16x32_bf16 v[118:121], v[158:161], v[202:205], v[118:121]
	v_mfma_f32_16x16x32_bf16 v[114:117], v[186:189], v[202:205], v[114:117]
	v_mfma_f32_16x16x32_bf16 v[86:89], v[158:161], v[210:213], v[86:89]
	v_mfma_f32_16x16x32_bf16 v[82:85], v[186:189], v[210:213], v[82:85]
	v_mfma_f32_16x16x32_bf16 v[70:73], v[158:161], v[218:221], v[70:73]
	v_mfma_f32_16x16x32_bf16 v[66:69], v[186:189], v[218:221], v[66:69]
	v_mfma_f32_16x16x32_bf16 v[134:137], v[176:179], v[198:201], v[134:137]
	v_mfma_f32_16x16x32_bf16 v[130:133], v[190:193], v[198:201], v[130:133]
	v_mfma_f32_16x16x32_bf16 v[118:121], v[176:179], v[206:209], v[118:121]
	v_mfma_f32_16x16x32_bf16 v[114:117], v[190:193], v[206:209], v[114:117]
	v_mfma_f32_16x16x32_bf16 v[86:89], v[176:179], v[214:217], v[86:89]
	v_mfma_f32_16x16x32_bf16 v[82:85], v[190:193], v[214:217], v[82:85]
	v_mfma_f32_16x16x32_bf16 v[70:73], v[176:179], v[222:225], v[70:73]
	v_mfma_f32_16x16x32_bf16 v[66:69], v[190:193], v[222:225], v[66:69]
	s_barrier
	s_setprio 0
	s_add_i32 s11, s60, s6
	v_lshl_add_u64 v[180:181], s[46:47], 0, v[0:1]
	s_mov_b32 m0, s11
	ds_read_b128 v[194:197], v185 offset:16384
	ds_read_b128 v[198:201], v185 offset:17408
	ds_read_b128 v[202:205], v185 offset:18432
	ds_read_b128 v[206:209], v185 offset:19456
	ds_read_b128 v[210:213], v185 offset:20480
	ds_read_b128 v[214:217], v185 offset:21504
	ds_read_b128 v[218:221], v185 offset:22528
	ds_read_b128 v[222:225], v185 offset:23552
	global_load_lds_dwordx4 v[180:181], off
	s_add_i32 m0, s11, 0x2000
	s_add_u32 s60, s46, 0x40000
	v_lshl_add_u64 v[226:227], s[46:47], 0, v[146:147]
	s_addc_u32 s61, s47, 0
	s_add_i32 s10, s10, s6
	global_load_lds_dwordx4 v[226:227], off
	v_lshl_add_u64 v[238:239], s[60:61], 0, v[0:1]
	s_mov_b32 m0, s10
	v_lshl_add_u64 v[240:241], s[48:49], 0, v[148:149]
	global_load_lds_dwordx4 v[238:239], off
	v_lshl_add_u64 v[238:239], s[60:61], 0, v[146:147]
	s_add_i32 m0, s10, 0x2000
	s_nop 0
	global_load_lds_dwordx4 v[238:239], off
	v_lshl_add_u64 v[238:239], s[48:49], 0, v[150:151]
	s_mov_b32 m0, s7
	s_nop 0
	global_load_lds_dwordx4 v[238:239], off
	s_mov_b32 m0, s8
	s_nop 0
	global_load_lds_dwordx4 v[240:241], off
	s_waitcnt vmcnt(8)
	s_waitcnt lgkmcnt(0)
	s_setprio 1
	s_barrier
; #define PG8_STAGE(bufoff, gbase, voff) do { _Pragma("unroll") for (int _i = 0; _i < 2; ++_i) \
;         __builtin_amdgcn_global_load_lds((const unsigned*)((const char*)(gbase) + (voff)[_i]), (PG8_LAS unsigned*)(lds + (bufoff) + ldsw + _i * 8192), 16, 0, 0); } while (0)
; #define PG8_LDA(dst, b, h) do { _Pragma("unroll") for (int m = 0; m < 4; ++m) _Pragma("unroll") for (int k = 0; k < 2; ++k) dst[m][k] = *(const PG8_LAS bf16x8*)(lds + PG8_SA(b, h) + aoff + m * 2048 + k * 1024); } while (0)
; #define PG8_LDB(dst, b, h) do { _Pragma("unroll") for (int n = 0; n < 2; ++n) _Pragma("unroll") for (int k = 0; k < 2; ++k) dst[n][k] = *(const PG8_LAS bf16x8*)(lds + PG8_SB(b, h) + boff + n * 2048 + k * 1024); } while (0)
; #define PG8_MMA(ai, bj, At, Bt) do { __builtin_amdgcn_s_setprio(1); _Pragma("unroll") for (int m = 0; m < 4; ++m) _Pragma("unroll") for (int n = 0; n < 2; ++n) _Pragma("unroll") for (int k = 0; k < 2; ++k) \
;         acc[ai][bj][m][n] = __builtin_amdgcn_mfma_f32_16x16x32_bf16(Bt[n][k], At[m][k], acc[ai][bj][m][n], 0, 0, 0); __builtin_amdgcn_s_setprio(0); } while (0)
; #define PG8_WAIT_V(n) asm volatile("s_waitcnt vmcnt(" #n ")" ::: "memory")
; #define PG8_WAIT_L(n) asm volatile("s_waitcnt lgkmcnt(" #n ")" ::: "memory")
; #define PG8_BAR __builtin_amdgcn_s_barrier()
; #define PG8_SCHED __builtin_amdgcn_sched_barrier(0)
; template <class Epi, class Sched, bool ALIGN_EPI = false, bool SP2 = false>
; __device__ __forceinline__ void gemm_phase(PG8_LAS unsigned char* lds, const Gemm g, const Sched& S, const Epi& E) {
;     ...
;             PG8_WAIT_V(8); PG8_WAIT_L(0); PG8_BAR; PG8_MMA(1, 0, At, B0); PG8_MMA(1, 1, At, B1); PG8_BAR; PG8_SCHED;
;             PG8_LDB(B0, 1, 0); PG8_LDB(B1, 1, 1); PG8_SCHED; PG8_LDA(At, 1, 0); PG8_STAGE(PG8_SA(0, 1), a2 + hstep, voffA);
;             PG8_WAIT_V(8); PG8_WAIT_L(0); PG8_BAR; PG8_MMA(0, 0, At, B0); PG8_MMA(0, 1, At, B1); PG8_BAR; PG8_SCHED;
	v_mfma_f32_16x16x32_bf16 v[62:65], v[90:93], v[194:197], v[62:65]
	v_mfma_f32_16x16x32_bf16 v[58:61], v[98:101], v[194:197], v[58:61]
	v_mfma_f32_16x16x32_bf16 v[46:49], v[90:93], v[202:205], v[46:49]
	v_mfma_f32_16x16x32_bf16 v[42:45], v[98:101], v[202:205], v[42:45]
	v_mfma_f32_16x16x32_bf16 v[30:33], v[90:93], v[210:213], v[30:33]
	v_mfma_f32_16x16x32_bf16 v[26:29], v[98:101], v[210:213], v[26:29]
	v_mfma_f32_16x16x32_bf16 v[14:17], v[90:93], v[218:221], v[14:17]
	v_mfma_f32_16x16x32_bf16 v[10:13], v[98:101], v[218:221], v[10:13]
	v_mfma_f32_16x16x32_bf16 v[62:65], v[94:97], v[198:201], v[62:65]
	v_mfma_f32_16x16x32_bf16 v[58:61], v[102:105], v[198:201], v[58:61]
	v_mfma_f32_16x16x32_bf16 v[46:49], v[94:97], v[206:209], v[46:49]
	v_mfma_f32_16x16x32_bf16 v[42:45], v[102:105], v[206:209], v[42:45]
	v_mfma_f32_16x16x32_bf16 v[30:33], v[94:97], v[214:217], v[30:33]
	v_mfma_f32_16x16x32_bf16 v[26:29], v[102:105], v[214:217], v[26:29]
	v_mfma_f32_16x16x32_bf16 v[14:17], v[94:97], v[222:225], v[14:17]
	v_mfma_f32_16x16x32_bf16 v[10:13], v[102:105], v[222:225], v[10:13]
	s_setprio 0
	s_setprio 1
	v_mfma_f32_16x16x32_bf16 v[54:57], v[158:161], v[194:197], v[54:57]
	v_mfma_f32_16x16x32_bf16 v[50:53], v[186:189], v[194:197], v[50:53]
	v_mfma_f32_16x16x32_bf16 v[38:41], v[158:161], v[202:205], v[38:41]
	v_mfma_f32_16x16x32_bf16 v[34:37], v[186:189], v[202:205], v[34:37]
	v_mfma_f32_16x16x32_bf16 v[22:25], v[158:161], v[210:213], v[22:25]
	v_mfma_f32_16x16x32_bf16 v[18:21], v[186:189], v[210:213], v[18:21]
	v_mfma_f32_16x16x32_bf16 v[6:9], v[158:161], v[218:221], v[6:9]
	v_mfma_f32_16x16x32_bf16 v[2:5], v[186:189], v[218:221], v[2:5]
	v_mfma_f32_16x16x32_bf16 v[54:57], v[176:179], v[198:201], v[54:57]
	v_mfma_f32_16x16x32_bf16 v[50:53], v[190:193], v[198:201], v[50:53]
	v_mfma_f32_16x16x32_bf16 v[38:41], v[176:179], v[206:209], v[38:41]
	v_mfma_f32_16x16x32_bf16 v[34:37], v[190:193], v[206:209], v[34:37]
	v_mfma_f32_16x16x32_bf16 v[22:25], v[176:179], v[214:217], v[22:25]
	v_mfma_f32_16x16x32_bf16 v[18:21], v[190:193], v[214:217], v[18:21]
	v_mfma_f32_16x16x32_bf16 v[6:9], v[176:179], v[222:225], v[6:9]
	v_mfma_f32_16x16x32_bf16 v[2:5], v[190:193], v[222:225], v[2:5]
	s_barrier
	s_setprio 0
	s_add_i32 s10, 16, 0x18000
	s_add_i32 s11, 16, 0x1c000
	v_add_u32_e32 v102, s10, v183
	v_add_u32_e32 v190, s11, v183
	ds_read_b128 v[90:93], v102
	ds_read_b128 v[94:97], v102 offset:1024
	ds_read_b128 v[98:101], v102 offset:2048
	ds_read_b128 v[102:105], v102 offset:3072
	ds_read_b128 v[158:161], v190
	ds_read_b128 v[176:179], v190 offset:1024
	ds_read_b128 v[186:189], v190 offset:2048
	ds_read_b128 v[190:193], v190 offset:3072
	s_add_u32 s48, s48, 0x40000
	s_addc_u32 s49, s49, 0
	s_mov_b32 m0, s9
	v_lshl_add_u64 v[242:243], s[48:49], 0, v[150:151]
	ds_read_b128 v[194:197], v185 offset:32768
	ds_read_b128 v[198:201], v185 offset:33792
	ds_read_b128 v[202:205], v185 offset:34816
	ds_read_b128 v[206:209], v185 offset:35840
	ds_read_b128 v[210:213], v185 offset:36864
	ds_read_b128 v[214:217], v185 offset:37888
	ds_read_b128 v[218:221], v185 offset:38912
	ds_read_b128 v[222:225], v185 offset:39936
	global_load_lds_dwordx4 v[242:243], off
	v_lshl_add_u64 v[242:243], s[48:49], 0, v[148:149]
	s_mov_b32 m0, s50
	s_nop 0
	global_load_lds_dwordx4 v[242:243], off
	s_waitcnt vmcnt(8)
	s_waitcnt lgkmcnt(0)
	s_setprio 1
	s_barrier
	v_mfma_f32_16x16x32_bf16 v[142:145], v[90:93], v[194:197], v[142:145]
	v_mfma_f32_16x16x32_bf16 v[138:141], v[98:101], v[194:197], v[138:141]
	v_mfma_f32_16x16x32_bf16 v[126:129], v[90:93], v[202:205], v[126:129]
	v_mfma_f32_16x16x32_bf16 v[122:125], v[98:101], v[202:205], v[122:125]
	v_mfma_f32_16x16x32_bf16 v[110:113], v[90:93], v[210:213], v[110:113]
	v_mfma_f32_16x16x32_bf16 v[106:109], v[98:101], v[210:213], v[106:109]
	v_mfma_f32_16x16x32_bf16 v[78:81], v[90:93], v[218:221], v[78:81]
	v_mfma_f32_16x16x32_bf16 v[74:77], v[98:101], v[218:221], v[74:77]
	v_mfma_f32_16x16x32_bf16 v[142:145], v[94:97], v[198:201], v[142:145]
	v_mfma_f32_16x16x32_bf16 v[138:141], v[102:105], v[198:201], v[138:141]
	v_mfma_f32_16x16x32_bf16 v[126:129], v[94:97], v[206:209], v[126:129]
	v_mfma_f32_16x16x32_bf16 v[122:125], v[102:105], v[206:209], v[122:125]
	v_mfma_f32_16x16x32_bf16 v[110:113], v[94:97], v[214:217], v[110:113]
	v_mfma_f32_16x16x32_bf16 v[106:109], v[102:105], v[214:217], v[106:109]
	v_mfma_f32_16x16x32_bf16 v[78:81], v[94:97], v[222:225], v[78:81]
	v_mfma_f32_16x16x32_bf16 v[74:77], v[102:105], v[222:225], v[74:77]
	s_setprio 0
	s_setprio 1
	v_mfma_f32_16x16x32_bf16 v[134:137], v[158:161], v[194:197], v[134:137]
	v_mfma_f32_16x16x32_bf16 v[130:133], v[186:189], v[194:197], v[130:133]
	v_mfma_f32_16x16x32_bf16 v[118:121], v[158:161], v[202:205], v[118:121]
	v_mfma_f32_16x16x32_bf16 v[114:117], v[186:189], v[202:205], v[114:117]
	v_mfma_f32_16x16x32_bf16 v[86:89], v[158:161], v[210:213], v[86:89]
	v_mfma_f32_16x16x32_bf16 v[82:85], v[186:189], v[210:213], v[82:85]
	v_mfma_f32_16x16x32_bf16 v[70:73], v[158:161], v[218:221], v[70:73]
	v_mfma_f32_16x16x32_bf16 v[66:69], v[186:189], v[218:221], v[66:69]
	v_mfma_f32_16x16x32_bf16 v[134:137], v[176:179], v[198:201], v[134:137]
	v_mfma_f32_16x16x32_bf16 v[130:133], v[190:193], v[198:201], v[130:133]
	v_mfma_f32_16x16x32_bf16 v[118:121], v[176:179], v[206:209], v[118:121]
	v_mfma_f32_16x16x32_bf16 v[114:117], v[190:193], v[206:209], v[114:117]
	v_mfma_f32_16x16x32_bf16 v[86:89], v[176:179], v[214:217], v[86:89]
	v_mfma_f32_16x16x32_bf16 v[82:85], v[190:193], v[214:217], v[82:85]
	v_mfma_f32_16x16x32_bf16 v[70:73], v[176:179], v[222:225], v[70:73]
	v_mfma_f32_16x16x32_bf16 v[66:69], v[190:193], v[222:225], v[66:69]
	s_barrier
; #define PG8_STAGE(bufoff, gbase, voff) do { _Pragma("unroll") for (int _i = 0; _i < 2; ++_i) \
;         __builtin_amdgcn_global_load_lds((const unsigned*)((const char*)(gbase) + (voff)[_i]), (PG8_LAS unsigned*)(lds + (bufoff) + ldsw + _i * 8192), 16, 0, 0); } while (0)
; #define PG8_LDA(dst, b, h) do { _Pragma("unroll") for (int m = 0; m < 4; ++m) _Pragma("unroll") for (int k = 0; k < 2; ++k) dst[m][k] = *(const PG8_LAS bf16x8*)(lds + PG8_SA(b, h) + aoff + m * 2048 + k * 1024); } while (0)
; #define PG8_MMA(ai, bj, At, Bt) do { __builtin_amdgcn_s_setprio(1); _Pragma("unroll") for (int m = 0; m < 4; ++m) _Pragma("unroll") for (int n = 0; n < 2; ++n) _Pragma("unroll") for (int k = 0; k < 2; ++k) \
;         acc[ai][bj][m][n] = __builtin_amdgcn_mfma_f32_16x16x32_bf16(Bt[n][k], At[m][k], acc[ai][bj][m][n], 0, 0, 0); __builtin_amdgcn_s_setprio(0); } while (0)
; #define PG8_WAIT_V(n) asm volatile("s_waitcnt vmcnt(" #n ")" ::: "memory")
; #define PG8_WAIT_L(n) asm volatile("s_waitcnt lgkmcnt(" #n ")" ::: "memory")
; #define PG8_BAR __builtin_amdgcn_s_barrier()
; #define PG8_SCHED __builtin_amdgcn_sched_barrier(0)
; template <class Epi, class Sched, bool ALIGN_EPI = false, bool SP2 = false>
; __device__ __forceinline__ void gemm_phase(PG8_LAS unsigned char* lds, const Gemm g, const Sched& S, const Epi& E) {
;     ...
;             PG8_WAIT_V(8); PG8_WAIT_L(0); PG8_BAR; PG8_MMA(0, 0, At, B0); PG8_MMA(0, 1, At, B1); PG8_BAR; PG8_SCHED;
;             PG8_LDA(At, 1, 1); PG8_STAGE(PG8_SB(1, 0), b3, voffB); PG8_STAGE(PG8_SB(1, 1), b3 + hstep, voffB); PG8_STAGE(PG8_SA(1, 0), a3, voffA);
;             PG8_WAIT_V(8); PG8_WAIT_L(0); PG8_BAR; PG8_MMA(1, 0, At, B0); PG8_MMA(1, 1, At, B1); PG8_BAR; PG8_SCHED;
;     ...
;         if constexpr (ALIGN_EPI) { if (wr == 0) PG8_BAR; }
	s_setprio 0
	s_add_i32 s10, s10, s6
	v_lshl_add_u64 v[180:181], v[180:181], 0, s[28:29]
	s_mov_b32 m0, s10
	ds_read_b128 v[194:197], v185 offset:49152
	ds_read_b128 v[198:201], v185 offset:50176
	ds_read_b128 v[202:205], v185 offset:51200
	ds_read_b128 v[206:209], v185 offset:52224
	ds_read_b128 v[210:213], v185 offset:53248
	ds_read_b128 v[214:217], v185 offset:54272
	ds_read_b128 v[218:221], v185 offset:55296
	ds_read_b128 v[222:225], v185 offset:56320
	global_load_lds_dwordx4 v[180:181], off
	s_add_i32 m0, s10, 0x2000
	s_add_u32 s46, s46, 0x40080
	v_lshl_add_u64 v[180:181], v[226:227], 0, s[28:29]
	s_addc_u32 s47, s47, 0
	s_add_i32 s10, s11, s6
	global_load_lds_dwordx4 v[180:181], off
	v_lshl_add_u64 v[180:181], s[46:47], 0, v[0:1]
	s_mov_b32 m0, s10
	s_nop 0
	global_load_lds_dwordx4 v[180:181], off
	v_lshl_add_u64 v[180:181], s[46:47], 0, v[146:147]
	s_add_i32 m0, s10, 0x2000
	s_nop 0
	global_load_lds_dwordx4 v[180:181], off
	v_lshl_add_u64 v[180:181], v[238:239], 0, s[28:29]
	s_mov_b32 m0, s52
	s_nop 0
	global_load_lds_dwordx4 v[180:181], off
	v_lshl_add_u64 v[180:181], v[240:241], 0, s[28:29]
	s_mov_b32 m0, s53
	s_nop 0
	global_load_lds_dwordx4 v[180:181], off
	s_waitcnt vmcnt(8)
	s_waitcnt lgkmcnt(0)
	s_setprio 1
	s_barrier
	v_mfma_f32_16x16x32_bf16 v[62:65], v[90:93], v[194:197], v[62:65]
	v_mfma_f32_16x16x32_bf16 v[58:61], v[98:101], v[194:197], v[58:61]
	v_mfma_f32_16x16x32_bf16 v[46:49], v[90:93], v[202:205], v[46:49]
	v_mfma_f32_16x16x32_bf16 v[42:45], v[98:101], v[202:205], v[42:45]
	v_mfma_f32_16x16x32_bf16 v[30:33], v[90:93], v[210:213], v[30:33]
	v_mfma_f32_16x16x32_bf16 v[26:29], v[98:101], v[210:213], v[26:29]
	v_mfma_f32_16x16x32_bf16 v[14:17], v[90:93], v[218:221], v[14:17]
	v_mfma_f32_16x16x32_bf16 v[10:13], v[98:101], v[218:221], v[10:13]
	v_mfma_f32_16x16x32_bf16 v[62:65], v[94:97], v[198:201], v[62:65]
	v_mfma_f32_16x16x32_bf16 v[58:61], v[102:105], v[198:201], v[58:61]
	v_mfma_f32_16x16x32_bf16 v[46:49], v[94:97], v[206:209], v[46:49]
	v_mfma_f32_16x16x32_bf16 v[42:45], v[102:105], v[206:209], v[42:45]
	v_mfma_f32_16x16x32_bf16 v[30:33], v[94:97], v[214:217], v[30:33]
	v_mfma_f32_16x16x32_bf16 v[26:29], v[102:105], v[214:217], v[26:29]
	v_mfma_f32_16x16x32_bf16 v[14:17], v[94:97], v[222:225], v[14:17]
	v_mfma_f32_16x16x32_bf16 v[10:13], v[102:105], v[222:225], v[10:13]
	s_setprio 0
	s_setprio 1
	v_mfma_f32_16x16x32_bf16 v[54:57], v[158:161], v[194:197], v[54:57]
	v_mfma_f32_16x16x32_bf16 v[50:53], v[186:189], v[194:197], v[50:53]
	v_mfma_f32_16x16x32_bf16 v[38:41], v[158:161], v[202:205], v[38:41]
	v_mfma_f32_16x16x32_bf16 v[34:37], v[186:189], v[202:205], v[34:37]
	v_mfma_f32_16x16x32_bf16 v[22:25], v[158:161], v[210:213], v[22:25]
	v_mfma_f32_16x16x32_bf16 v[18:21], v[186:189], v[210:213], v[18:21]
	v_mfma_f32_16x16x32_bf16 v[6:9], v[158:161], v[218:221], v[6:9]
	v_mfma_f32_16x16x32_bf16 v[2:5], v[186:189], v[218:221], v[2:5]
	v_mfma_f32_16x16x32_bf16 v[54:57], v[176:179], v[198:201], v[54:57]
	v_mfma_f32_16x16x32_bf16 v[50:53], v[190:193], v[198:201], v[50:53]
	v_mfma_f32_16x16x32_bf16 v[38:41], v[176:179], v[206:209], v[38:41]
	v_mfma_f32_16x16x32_bf16 v[34:37], v[190:193], v[206:209], v[34:37]
	v_mfma_f32_16x16x32_bf16 v[22:25], v[176:179], v[214:217], v[22:25]
	v_mfma_f32_16x16x32_bf16 v[18:21], v[190:193], v[214:217], v[18:21]
	v_mfma_f32_16x16x32_bf16 v[6:9], v[176:179], v[222:225], v[6:9]
	v_mfma_f32_16x16x32_bf16 v[2:5], v[190:193], v[222:225], v[2:5]
	s_barrier
	s_setprio 0
	s_add_i32 s59, s59, 2
	s_add_u32 s57, s57, 0x100
	s_addc_u32 s58, s58, 0
	s_add_u32 s44, s44, 0x100
	s_addc_u32 s45, s45, 0
	s_cmp_gt_u32 s59, 13
	s_cbranch_scc0 .LBB0_162
	s_and_b64 vcc, exec, s[22:23]
	s_cbranch_vccz .LBB0_165
	s_barrier

; #define PG8_STAGE(bufoff, gbase, voff) do { _Pragma("unroll") for (int _i = 0; _i < 2; ++_i) \
;         __builtin_amdgcn_global_load_lds((const unsigned*)((const char*)(gbase) + (voff)[_i]), (PG8_LAS unsigned*)(lds + (bufoff) + ldsw + _i * 8192), 16, 0, 0); } while (0)
; #define PG8_LDA(dst, b, h) do { _Pragma("unroll") for (int m = 0; m < 4; ++m) _Pragma("unroll") for (int k = 0; k < 2; ++k) dst[m][k] = *(const PG8_LAS bf16x8*)(lds + PG8_SA(b, h) + aoff + m * 2048 + k * 1024); } while (0)
; #define PG8_LDB(dst, b, h) do { _Pragma("unroll") for (int n = 0; n < 2; ++n) _Pragma("unroll") for (int k = 0; k < 2; ++k) dst[n][k] = *(const PG8_LAS bf16x8*)(lds + PG8_SB(b, h) + boff + n * 2048 + k * 1024); } while (0)
; #define PG8_MMA(ai, bj, At, Bt) do { __builtin_amdgcn_s_setprio(1); _Pragma("unroll") for (int m = 0; m < 4; ++m) _Pragma("unroll") for (int n = 0; n < 2; ++n) _Pragma("unroll") for (int k = 0; k < 2; ++k) \
;         acc[ai][bj][m][n] = __builtin_amdgcn_mfma_f32_16x16x32_bf16(Bt[n][k], At[m][k], acc[ai][bj][m][n], 0, 0, 0); __builtin_amdgcn_s_setprio(0); } while (0)
; #define PG8_WAIT_V(n) asm volatile("s_waitcnt vmcnt(" #n ")" ::: "memory")
; #define PG8_WAIT_L(n) asm volatile("s_waitcnt lgkmcnt(" #n ")" ::: "memory")
; #define PG8_BAR __builtin_amdgcn_s_barrier()
; #define PG8_SCHED __builtin_amdgcn_sched_barrier(0)
; template <class Epi, class Sched, bool ALIGN_EPI = false, bool SP2 = false>
; __device__ __forceinline__ void gemm_phase(PG8_LAS unsigned char* lds, const Gemm g, const Sched& S, const Epi& E) {
;     ...
;             PG8_LDB(B0, 0, 0); PG8_LDB(B1, 0, 1); PG8_SCHED; PG8_LDA(At, 0, 0); PG8_STAGE(PG8_SA(1, 1), a1 + hstep, voffA);
;             PG8_WAIT_V(8); PG8_WAIT_L(0); PG8_BAR; PG8_MMA(0, 0, At, B0); PG8_MMA(0, 1, At, B1); PG8_BAR; PG8_SCHED;
;             PG8_LDA(At, 0, 1); PG8_STAGE(PG8_SB(0, 0), b2, voffB); PG8_STAGE(PG8_SB(0, 1), b2 + hstep, voffB); PG8_STAGE(PG8_SA(0, 0), a2, voffA);
;             PG8_WAIT_V(8); PG8_WAIT_L(0); PG8_BAR; PG8_MMA(1, 0, At, B0); PG8_MMA(1, 1, At, B1); PG8_BAR; PG8_SCHED;
.LBB0_243:
	s_add_u32 s10, s46, 0xfffc0080
	s_addc_u32 s11, s47, -1
	s_add_i32 s58, 16, 0x10000
	s_cmp_eq_u32 s57, 12
	s_cselect_b32 s51, s34, s11
	s_cselect_b32 s50, s35, s10
	s_cselect_b32 s49, s27, s56
	s_cselect_b32 s48, s41, s55
	s_add_i32 s10, 16, 0x14000
	v_add_u32_e32 v156, s58, v141
	v_add_u32_e32 v160, s10, v141
	ds_read_b128 v[144:147], v156
	ds_read_b128 v[148:151], v156 offset:1024
	ds_read_b128 v[152:155], v156 offset:2048
	ds_read_b128 v[156:159], v156 offset:3072
	ds_read_b128 v[176:179], v160
	ds_read_b128 v[180:183], v160 offset:1024
	ds_read_b128 v[184:187], v160 offset:2048
	ds_read_b128 v[188:191], v160 offset:3072
	v_lshl_add_u64 v[160:161], s[46:47], 0, v[138:139]
	s_add_i32 m0, s4, 0xc000
	ds_read_b128 v[192:195], v143
	ds_read_b128 v[196:199], v143 offset:1024
	ds_read_b128 v[200:203], v143 offset:2048
	ds_read_b128 v[204:207], v143 offset:3072
	ds_read_b128 v[208:211], v143 offset:4096
	ds_read_b128 v[212:215], v143 offset:5120
	ds_read_b128 v[216:219], v143 offset:6144
	ds_read_b128 v[220:223], v143 offset:7168
	global_load_lds_dwordx4 v[160:161], off
	v_lshl_add_u64 v[160:161], s[46:47], 0, v[136:137]
	s_add_i32 m0, s4, 0xe000
	s_nop 0
	global_load_lds_dwordx4 v[160:161], off
	s_waitcnt vmcnt(8)
	s_waitcnt lgkmcnt(0)
	s_setprio 1
	s_barrier
	v_mfma_f32_16x16x32_bf16 v[126:129], v[144:147], v[192:195], v[126:129]
	v_mfma_f32_16x16x32_bf16 v[122:125], v[152:155], v[192:195], v[122:125]
	v_mfma_f32_16x16x32_bf16 v[118:121], v[144:147], v[200:203], v[118:121]
	v_mfma_f32_16x16x32_bf16 v[114:117], v[152:155], v[200:203], v[114:117]
	v_mfma_f32_16x16x32_bf16 v[102:105], v[144:147], v[208:211], v[102:105]
	v_mfma_f32_16x16x32_bf16 v[98:101], v[152:155], v[208:211], v[98:101]
	v_mfma_f32_16x16x32_bf16 v[86:89], v[144:147], v[216:219], v[86:89]
	v_mfma_f32_16x16x32_bf16 v[82:85], v[152:155], v[216:219], v[82:85]
	v_mfma_f32_16x16x32_bf16 v[126:129], v[148:151], v[196:199], v[126:129]
	v_mfma_f32_16x16x32_bf16 v[122:125], v[156:159], v[196:199], v[122:125]
	v_mfma_f32_16x16x32_bf16 v[118:121], v[148:151], v[204:207], v[118:121]
	v_mfma_f32_16x16x32_bf16 v[114:117], v[156:159], v[204:207], v[114:117]
	v_mfma_f32_16x16x32_bf16 v[102:105], v[148:151], v[212:215], v[102:105]
	v_mfma_f32_16x16x32_bf16 v[98:101], v[156:159], v[212:215], v[98:101]
	v_mfma_f32_16x16x32_bf16 v[86:89], v[148:151], v[220:223], v[86:89]
	v_mfma_f32_16x16x32_bf16 v[82:85], v[156:159], v[220:223], v[82:85]
	s_setprio 0
	s_setprio 1
	v_mfma_f32_16x16x32_bf16 v[110:113], v[176:179], v[192:195], v[110:113]
	v_mfma_f32_16x16x32_bf16 v[106:109], v[184:187], v[192:195], v[106:109]
	v_mfma_f32_16x16x32_bf16 v[94:97], v[176:179], v[200:203], v[94:97]
	v_mfma_f32_16x16x32_bf16 v[90:93], v[184:187], v[200:203], v[90:93]
	v_mfma_f32_16x16x32_bf16 v[78:81], v[176:179], v[208:211], v[78:81]
	v_mfma_f32_16x16x32_bf16 v[74:77], v[184:187], v[208:211], v[74:77]
	v_mfma_f32_16x16x32_bf16 v[70:73], v[176:179], v[216:219], v[70:73]
	v_mfma_f32_16x16x32_bf16 v[66:69], v[184:187], v[216:219], v[66:69]
	v_mfma_f32_16x16x32_bf16 v[110:113], v[180:183], v[196:199], v[110:113]
	v_mfma_f32_16x16x32_bf16 v[106:109], v[188:191], v[196:199], v[106:109]
	v_mfma_f32_16x16x32_bf16 v[94:97], v[180:183], v[204:207], v[94:97]
	v_mfma_f32_16x16x32_bf16 v[90:93], v[188:191], v[204:207], v[90:93]
	v_mfma_f32_16x16x32_bf16 v[78:81], v[180:183], v[212:215], v[78:81]
	v_mfma_f32_16x16x32_bf16 v[74:77], v[188:191], v[212:215], v[74:77]
	v_mfma_f32_16x16x32_bf16 v[70:73], v[180:183], v[220:223], v[70:73]
	v_mfma_f32_16x16x32_bf16 v[66:69], v[188:191], v[220:223], v[66:69]
	s_barrier
	s_setprio 0
	s_add_i32 s11, s58, s3
	v_lshl_add_u64 v[160:161], s[48:49], 0, v[0:1]
	s_mov_b32 m0, s11
	ds_read_b128 v[192:195], v143 offset:16384
	ds_read_b128 v[196:199], v143 offset:17408
	ds_read_b128 v[200:203], v143 offset:18432
	ds_read_b128 v[204:207], v143 offset:19456
	ds_read_b128 v[208:211], v143 offset:20480
	ds_read_b128 v[212:215], v143 offset:21504
	ds_read_b128 v[216:219], v143 offset:22528
	ds_read_b128 v[220:223], v143 offset:23552
	global_load_lds_dwordx4 v[160:161], off
	s_add_i32 m0, s11, 0x2000
	s_add_u32 s58, s48, 0x40000
	v_lshl_add_u64 v[224:225], s[48:49], 0, v[130:131]
	s_addc_u32 s59, s49, 0
	s_add_i32 s10, s10, s3
	global_load_lds_dwordx4 v[224:225], off
	v_lshl_add_u64 v[226:227], s[58:59], 0, v[0:1]
	s_mov_b32 m0, s10
	v_lshl_add_u64 v[238:239], s[50:51], 0, v[132:133]
	global_load_lds_dwordx4 v[226:227], off
	v_lshl_add_u64 v[226:227], s[58:59], 0, v[130:131]
	s_add_i32 m0, s10, 0x2000
	s_nop 0
	global_load_lds_dwordx4 v[226:227], off
	v_lshl_add_u64 v[226:227], s[50:51], 0, v[134:135]
	s_mov_b32 m0, s4
	s_nop 0
	global_load_lds_dwordx4 v[226:227], off
	s_mov_b32 m0, s5
	s_nop 0
	global_load_lds_dwordx4 v[238:239], off
	s_waitcnt vmcnt(8)
	s_waitcnt lgkmcnt(0)
	s_setprio 1
	s_barrier
; #define PG8_STAGE(bufoff, gbase, voff) do { _Pragma("unroll") for (int _i = 0; _i < 2; ++_i) \
;         __builtin_amdgcn_global_load_lds((const unsigned*)((const char*)(gbase) + (voff)[_i]), (PG8_LAS unsigned*)(lds + (bufoff) + ldsw + _i * 8192), 16, 0, 0); } while (0)
; #define PG8_LDA(dst, b, h) do { _Pragma("unroll") for (int m = 0; m < 4; ++m) _Pragma("unroll") for (int k = 0; k < 2; ++k) dst[m][k] = *(const PG8_LAS bf16x8*)(lds + PG8_SA(b, h) + aoff + m * 2048 + k * 1024); } while (0)
; #define PG8_LDB(dst, b, h) do { _Pragma("unroll") for (int n = 0; n < 2; ++n) _Pragma("unroll") for (int k = 0; k < 2; ++k) dst[n][k] = *(const PG8_LAS bf16x8*)(lds + PG8_SB(b, h) + boff + n * 2048 + k * 1024); } while (0)
; #define PG8_MMA(ai, bj, At, Bt) do { __builtin_amdgcn_s_setprio(1); _Pragma("unroll") for (int m = 0; m < 4; ++m) _Pragma("unroll") for (int n = 0; n < 2; ++n) _Pragma("unroll") for (int k = 0; k < 2; ++k) \
;         acc[ai][bj][m][n] = __builtin_amdgcn_mfma_f32_16x16x32_bf16(Bt[n][k], At[m][k], acc[ai][bj][m][n], 0, 0, 0); __builtin_amdgcn_s_setprio(0); } while (0)
; #define PG8_WAIT_V(n) asm volatile("s_waitcnt vmcnt(" #n ")" ::: "memory")
; #define PG8_WAIT_L(n) asm volatile("s_waitcnt lgkmcnt(" #n ")" ::: "memory")
; #define PG8_BAR __builtin_amdgcn_s_barrier()
; #define PG8_SCHED __builtin_amdgcn_sched_barrier(0)
; template <class Epi, class Sched, bool ALIGN_EPI = false, bool SP2 = false>
; __device__ __forceinline__ void gemm_phase(PG8_LAS unsigned char* lds, const Gemm g, const Sched& S, const Epi& E) {
;     ...
;             PG8_WAIT_V(8); PG8_WAIT_L(0); PG8_BAR; PG8_MMA(1, 0, At, B0); PG8_MMA(1, 1, At, B1); PG8_BAR; PG8_SCHED;
;             PG8_LDB(B0, 1, 0); PG8_LDB(B1, 1, 1); PG8_SCHED; PG8_LDA(At, 1, 0); PG8_STAGE(PG8_SA(0, 1), a2 + hstep, voffA);
;             PG8_WAIT_V(8); PG8_WAIT_L(0); PG8_BAR; PG8_MMA(0, 0, At, B0); PG8_MMA(0, 1, At, B1); PG8_BAR; PG8_SCHED;
	v_mfma_f32_16x16x32_bf16 v[62:65], v[144:147], v[192:195], v[62:65]
	v_mfma_f32_16x16x32_bf16 v[58:61], v[152:155], v[192:195], v[58:61]
	v_mfma_f32_16x16x32_bf16 v[54:57], v[144:147], v[200:203], v[54:57]
	v_mfma_f32_16x16x32_bf16 v[50:53], v[152:155], v[200:203], v[50:53]
	v_mfma_f32_16x16x32_bf16 v[38:41], v[144:147], v[208:211], v[38:41]
	v_mfma_f32_16x16x32_bf16 v[34:37], v[152:155], v[208:211], v[34:37]
	v_mfma_f32_16x16x32_bf16 v[22:25], v[144:147], v[216:219], v[22:25]
	v_mfma_f32_16x16x32_bf16 v[18:21], v[152:155], v[216:219], v[18:21]
	v_mfma_f32_16x16x32_bf16 v[62:65], v[148:151], v[196:199], v[62:65]
	v_mfma_f32_16x16x32_bf16 v[58:61], v[156:159], v[196:199], v[58:61]
	v_mfma_f32_16x16x32_bf16 v[54:57], v[148:151], v[204:207], v[54:57]
	v_mfma_f32_16x16x32_bf16 v[50:53], v[156:159], v[204:207], v[50:53]
	v_mfma_f32_16x16x32_bf16 v[38:41], v[148:151], v[212:215], v[38:41]
	v_mfma_f32_16x16x32_bf16 v[34:37], v[156:159], v[212:215], v[34:37]
	v_mfma_f32_16x16x32_bf16 v[22:25], v[148:151], v[220:223], v[22:25]
	v_mfma_f32_16x16x32_bf16 v[18:21], v[156:159], v[220:223], v[18:21]
	s_setprio 0
	s_setprio 1
	v_mfma_f32_16x16x32_bf16 v[46:49], v[176:179], v[192:195], v[46:49]
	v_mfma_f32_16x16x32_bf16 v[42:45], v[184:187], v[192:195], v[42:45]
	v_mfma_f32_16x16x32_bf16 v[30:33], v[176:179], v[200:203], v[30:33]
	v_mfma_f32_16x16x32_bf16 v[26:29], v[184:187], v[200:203], v[26:29]
	v_mfma_f32_16x16x32_bf16 v[14:17], v[176:179], v[208:211], v[14:17]
	v_mfma_f32_16x16x32_bf16 v[10:13], v[184:187], v[208:211], v[10:13]
	v_mfma_f32_16x16x32_bf16 v[6:9], v[176:179], v[216:219], v[6:9]
	v_mfma_f32_16x16x32_bf16 v[2:5], v[184:187], v[216:219], v[2:5]
	v_mfma_f32_16x16x32_bf16 v[46:49], v[180:183], v[196:199], v[46:49]
	v_mfma_f32_16x16x32_bf16 v[42:45], v[188:191], v[196:199], v[42:45]
	v_mfma_f32_16x16x32_bf16 v[30:33], v[180:183], v[204:207], v[30:33]
	v_mfma_f32_16x16x32_bf16 v[26:29], v[188:191], v[204:207], v[26:29]
	v_mfma_f32_16x16x32_bf16 v[14:17], v[180:183], v[212:215], v[14:17]
	v_mfma_f32_16x16x32_bf16 v[10:13], v[188:191], v[212:215], v[10:13]
	v_mfma_f32_16x16x32_bf16 v[6:9], v[180:183], v[220:223], v[6:9]
	v_mfma_f32_16x16x32_bf16 v[2:5], v[188:191], v[220:223], v[2:5]
	s_barrier
	s_setprio 0
	s_add_i32 s10, 16, 0x18000
	s_add_i32 s11, 16, 0x1c000
	v_add_u32_e32 v156, s10, v141
	v_add_u32_e32 v188, s11, v141
	ds_read_b128 v[144:147], v156
	ds_read_b128 v[148:151], v156 offset:1024
	ds_read_b128 v[152:155], v156 offset:2048
	ds_read_b128 v[156:159], v156 offset:3072
	ds_read_b128 v[176:179], v188
	ds_read_b128 v[180:183], v188 offset:1024
	ds_read_b128 v[184:187], v188 offset:2048
	ds_read_b128 v[188:191], v188 offset:3072
	s_add_u32 s50, s50, 0x40000
	s_addc_u32 s51, s51, 0
	s_mov_b32 m0, s6
	v_lshl_add_u64 v[240:241], s[50:51], 0, v[134:135]
	ds_read_b128 v[192:195], v143 offset:32768
	ds_read_b128 v[196:199], v143 offset:33792
	ds_read_b128 v[200:203], v143 offset:34816
	ds_read_b128 v[204:207], v143 offset:35840
	ds_read_b128 v[208:211], v143 offset:36864
	ds_read_b128 v[212:215], v143 offset:37888
	ds_read_b128 v[216:219], v143 offset:38912
	ds_read_b128 v[220:223], v143 offset:39936
	global_load_lds_dwordx4 v[240:241], off
	v_lshl_add_u64 v[240:241], s[50:51], 0, v[132:133]
	s_mov_b32 m0, s7
	s_nop 0
	global_load_lds_dwordx4 v[240:241], off
	s_waitcnt vmcnt(8)
	s_waitcnt lgkmcnt(0)
	s_setprio 1
	s_barrier
	v_mfma_f32_16x16x32_bf16 v[126:129], v[144:147], v[192:195], v[126:129]
	v_mfma_f32_16x16x32_bf16 v[122:125], v[152:155], v[192:195], v[122:125]
	v_mfma_f32_16x16x32_bf16 v[118:121], v[144:147], v[200:203], v[118:121]
	v_mfma_f32_16x16x32_bf16 v[114:117], v[152:155], v[200:203], v[114:117]
	v_mfma_f32_16x16x32_bf16 v[102:105], v[144:147], v[208:211], v[102:105]
	v_mfma_f32_16x16x32_bf16 v[98:101], v[152:155], v[208:211], v[98:101]
	v_mfma_f32_16x16x32_bf16 v[86:89], v[144:147], v[216:219], v[86:89]
	v_mfma_f32_16x16x32_bf16 v[82:85], v[152:155], v[216:219], v[82:85]
	v_mfma_f32_16x16x32_bf16 v[126:129], v[148:151], v[196:199], v[126:129]
	v_mfma_f32_16x16x32_bf16 v[122:125], v[156:159], v[196:199], v[122:125]
	v_mfma_f32_16x16x32_bf16 v[118:121], v[148:151], v[204:207], v[118:121]
	v_mfma_f32_16x16x32_bf16 v[114:117], v[156:159], v[204:207], v[114:117]
	v_mfma_f32_16x16x32_bf16 v[102:105], v[148:151], v[212:215], v[102:105]
	v_mfma_f32_16x16x32_bf16 v[98:101], v[156:159], v[212:215], v[98:101]
	v_mfma_f32_16x16x32_bf16 v[86:89], v[148:151], v[220:223], v[86:89]
	v_mfma_f32_16x16x32_bf16 v[82:85], v[156:159], v[220:223], v[82:85]
	s_setprio 0
	s_setprio 1
	v_mfma_f32_16x16x32_bf16 v[110:113], v[176:179], v[192:195], v[110:113]
	v_mfma_f32_16x16x32_bf16 v[106:109], v[184:187], v[192:195], v[106:109]
	v_mfma_f32_16x16x32_bf16 v[94:97], v[176:179], v[200:203], v[94:97]
	v_mfma_f32_16x16x32_bf16 v[90:93], v[184:187], v[200:203], v[90:93]
	v_mfma_f32_16x16x32_bf16 v[78:81], v[176:179], v[208:211], v[78:81]
	v_mfma_f32_16x16x32_bf16 v[74:77], v[184:187], v[208:211], v[74:77]
	v_mfma_f32_16x16x32_bf16 v[70:73], v[176:179], v[216:219], v[70:73]
	v_mfma_f32_16x16x32_bf16 v[66:69], v[184:187], v[216:219], v[66:69]
	v_mfma_f32_16x16x32_bf16 v[110:113], v[180:183], v[196:199], v[110:113]
	v_mfma_f32_16x16x32_bf16 v[106:109], v[188:191], v[196:199], v[106:109]
	v_mfma_f32_16x16x32_bf16 v[94:97], v[180:183], v[204:207], v[94:97]
	v_mfma_f32_16x16x32_bf16 v[90:93], v[188:191], v[204:207], v[90:93]
	v_mfma_f32_16x16x32_bf16 v[78:81], v[180:183], v[212:215], v[78:81]
	v_mfma_f32_16x16x32_bf16 v[74:77], v[188:191], v[212:215], v[74:77]
	v_mfma_f32_16x16x32_bf16 v[70:73], v[180:183], v[220:223], v[70:73]
	v_mfma_f32_16x16x32_bf16 v[66:69], v[188:191], v[220:223], v[66:69]
	s_barrier
; #define PG8_STAGE(bufoff, gbase, voff) do { _Pragma("unroll") for (int _i = 0; _i < 2; ++_i) \
;         __builtin_amdgcn_global_load_lds((const unsigned*)((const char*)(gbase) + (voff)[_i]), (PG8_LAS unsigned*)(lds + (bufoff) + ldsw + _i * 8192), 16, 0, 0); } while (0)
; #define PG8_LDA(dst, b, h) do { _Pragma("unroll") for (int m = 0; m < 4; ++m) _Pragma("unroll") for (int k = 0; k < 2; ++k) dst[m][k] = *(const PG8_LAS bf16x8*)(lds + PG8_SA(b, h) + aoff + m * 2048 + k * 1024); } while (0)
; #define PG8_MMA(ai, bj, At, Bt) do { __builtin_amdgcn_s_setprio(1); _Pragma("unroll") for (int m = 0; m < 4; ++m) _Pragma("unroll") for (int n = 0; n < 2; ++n) _Pragma("unroll") for (int k = 0; k < 2; ++k) \
;         acc[ai][bj][m][n] = __builtin_amdgcn_mfma_f32_16x16x32_bf16(Bt[n][k], At[m][k], acc[ai][bj][m][n], 0, 0, 0); __builtin_amdgcn_s_setprio(0); } while (0)
; #define PG8_WAIT_V(n) asm volatile("s_waitcnt vmcnt(" #n ")" ::: "memory")
; #define PG8_WAIT_L(n) asm volatile("s_waitcnt lgkmcnt(" #n ")" ::: "memory")
; #define PG8_BAR __builtin_amdgcn_s_barrier()
; #define PG8_SCHED __builtin_amdgcn_sched_barrier(0)
; template <class Epi, class Sched, bool ALIGN_EPI = false, bool SP2 = false>
; __device__ __forceinline__ void gemm_phase(PG8_LAS unsigned char* lds, const Gemm g, const Sched& S, const Epi& E) {
;     ...
;             PG8_WAIT_V(8); PG8_WAIT_L(0); PG8_BAR; PG8_MMA(0, 0, At, B0); PG8_MMA(0, 1, At, B1); PG8_BAR; PG8_SCHED;
;             PG8_LDA(At, 1, 1); PG8_STAGE(PG8_SB(1, 0), b3, voffB); PG8_STAGE(PG8_SB(1, 1), b3 + hstep, voffB); PG8_STAGE(PG8_SA(1, 0), a3, voffA);
;             PG8_WAIT_V(8); PG8_WAIT_L(0); PG8_BAR; PG8_MMA(1, 0, At, B0); PG8_MMA(1, 1, At, B1); PG8_BAR; PG8_SCHED;
;     ...
;         if constexpr (ALIGN_EPI) { if (wr == 0) PG8_BAR; }
	s_setprio 0
	s_add_i32 s10, s10, s3
	v_lshl_add_u64 v[160:161], v[160:161], 0, s[28:29]
	s_mov_b32 m0, s10
	ds_read_b128 v[192:195], v143 offset:49152
	ds_read_b128 v[196:199], v143 offset:50176
	ds_read_b128 v[200:203], v143 offset:51200
	ds_read_b128 v[204:207], v143 offset:52224
	ds_read_b128 v[208:211], v143 offset:53248
	ds_read_b128 v[212:215], v143 offset:54272
	ds_read_b128 v[216:219], v143 offset:55296
	ds_read_b128 v[220:223], v143 offset:56320
	global_load_lds_dwordx4 v[160:161], off
	s_add_i32 m0, s10, 0x2000
	s_add_u32 s48, s48, 0x40080
	v_lshl_add_u64 v[160:161], v[224:225], 0, s[28:29]
	s_addc_u32 s49, s49, 0
	s_add_i32 s10, s11, s3
	global_load_lds_dwordx4 v[160:161], off
	v_lshl_add_u64 v[160:161], s[48:49], 0, v[0:1]
	s_mov_b32 m0, s10
	s_nop 0
	global_load_lds_dwordx4 v[160:161], off
	v_lshl_add_u64 v[160:161], s[48:49], 0, v[130:131]
	s_add_i32 m0, s10, 0x2000
	s_nop 0
	global_load_lds_dwordx4 v[160:161], off
	v_lshl_add_u64 v[160:161], v[226:227], 0, s[28:29]
	s_mov_b32 m0, s8
	s_nop 0
	global_load_lds_dwordx4 v[160:161], off
	v_lshl_add_u64 v[160:161], v[238:239], 0, s[28:29]
	s_mov_b32 m0, s9
	s_nop 0
	global_load_lds_dwordx4 v[160:161], off
	s_waitcnt vmcnt(8)
	s_waitcnt lgkmcnt(0)
	s_setprio 1
	s_barrier
	v_mfma_f32_16x16x32_bf16 v[62:65], v[144:147], v[192:195], v[62:65]
	v_mfma_f32_16x16x32_bf16 v[58:61], v[152:155], v[192:195], v[58:61]
	v_mfma_f32_16x16x32_bf16 v[54:57], v[144:147], v[200:203], v[54:57]
	v_mfma_f32_16x16x32_bf16 v[50:53], v[152:155], v[200:203], v[50:53]
	v_mfma_f32_16x16x32_bf16 v[38:41], v[144:147], v[208:211], v[38:41]
	v_mfma_f32_16x16x32_bf16 v[34:37], v[152:155], v[208:211], v[34:37]
	v_mfma_f32_16x16x32_bf16 v[22:25], v[144:147], v[216:219], v[22:25]
	v_mfma_f32_16x16x32_bf16 v[18:21], v[152:155], v[216:219], v[18:21]
	v_mfma_f32_16x16x32_bf16 v[62:65], v[148:151], v[196:199], v[62:65]
	v_mfma_f32_16x16x32_bf16 v[58:61], v[156:159], v[196:199], v[58:61]
	v_mfma_f32_16x16x32_bf16 v[54:57], v[148:151], v[204:207], v[54:57]
	v_mfma_f32_16x16x32_bf16 v[50:53], v[156:159], v[204:207], v[50:53]
	v_mfma_f32_16x16x32_bf16 v[38:41], v[148:151], v[212:215], v[38:41]
	v_mfma_f32_16x16x32_bf16 v[34:37], v[156:159], v[212:215], v[34:37]
	v_mfma_f32_16x16x32_bf16 v[22:25], v[148:151], v[220:223], v[22:25]
	v_mfma_f32_16x16x32_bf16 v[18:21], v[156:159], v[220:223], v[18:21]
	s_setprio 0
	s_setprio 1
	v_mfma_f32_16x16x32_bf16 v[46:49], v[176:179], v[192:195], v[46:49]
	v_mfma_f32_16x16x32_bf16 v[42:45], v[184:187], v[192:195], v[42:45]
	v_mfma_f32_16x16x32_bf16 v[30:33], v[176:179], v[200:203], v[30:33]
	v_mfma_f32_16x16x32_bf16 v[26:29], v[184:187], v[200:203], v[26:29]
	v_mfma_f32_16x16x32_bf16 v[14:17], v[176:179], v[208:211], v[14:17]
	v_mfma_f32_16x16x32_bf16 v[10:13], v[184:187], v[208:211], v[10:13]
	v_mfma_f32_16x16x32_bf16 v[6:9], v[176:179], v[216:219], v[6:9]
	v_mfma_f32_16x16x32_bf16 v[2:5], v[184:187], v[216:219], v[2:5]
	v_mfma_f32_16x16x32_bf16 v[46:49], v[180:183], v[196:199], v[46:49]
	v_mfma_f32_16x16x32_bf16 v[42:45], v[188:191], v[196:199], v[42:45]
	v_mfma_f32_16x16x32_bf16 v[30:33], v[180:183], v[204:207], v[30:33]
	v_mfma_f32_16x16x32_bf16 v[26:29], v[188:191], v[204:207], v[26:29]
	v_mfma_f32_16x16x32_bf16 v[14:17], v[180:183], v[212:215], v[14:17]
	v_mfma_f32_16x16x32_bf16 v[10:13], v[188:191], v[212:215], v[10:13]
	v_mfma_f32_16x16x32_bf16 v[6:9], v[180:183], v[220:223], v[6:9]
	v_mfma_f32_16x16x32_bf16 v[2:5], v[188:191], v[220:223], v[2:5]
	s_barrier
	s_setprio 0
	s_add_i32 s57, s57, 2
	s_add_u32 s55, s55, 0x100
	s_addc_u32 s56, s56, 0
	s_add_u32 s46, s46, 0x100
	s_addc_u32 s47, s47, 0
	s_cmp_gt_u32 s57, 13
	s_cbranch_scc0 .LBB0_243
	s_and_b64 vcc, exec, s[24:25]
	s_cbranch_vccz .LBB0_246
	s_barrier

; #define PG8_STAGE(bufoff, gbase, voff) do { _Pragma("unroll") for (int _i = 0; _i < 2; ++_i) \
;         __builtin_amdgcn_global_load_lds((const unsigned*)((const char*)(gbase) + (voff)[_i]), (PG8_LAS unsigned*)(lds + (bufoff) + ldsw + _i * 8192), 16, 0, 0); } while (0)
; #define PG8_LDA(dst, b, h) do { _Pragma("unroll") for (int m = 0; m < 4; ++m) _Pragma("unroll") for (int k = 0; k < 2; ++k) dst[m][k] = *(const PG8_LAS bf16x8*)(lds + PG8_SA(b, h) + aoff + m * 2048 + k * 1024); } while (0)
; #define PG8_LDB(dst, b, h) do { _Pragma("unroll") for (int n = 0; n < 2; ++n) _Pragma("unroll") for (int k = 0; k < 2; ++k) dst[n][k] = *(const PG8_LAS bf16x8*)(lds + PG8_SB(b, h) + boff + n * 2048 + k * 1024); } while (0)
; #define PG8_MMA(ai, bj, At, Bt) do { __builtin_amdgcn_s_setprio(1); _Pragma("unroll") for (int m = 0; m < 4; ++m) _Pragma("unroll") for (int n = 0; n < 2; ++n) _Pragma("unroll") for (int k = 0; k < 2; ++k) \
;         acc[ai][bj][m][n] = __builtin_amdgcn_mfma_f32_16x16x32_bf16(Bt[n][k], At[m][k], acc[ai][bj][m][n], 0, 0, 0); __builtin_amdgcn_s_setprio(0); } while (0)
; #define PG8_WAIT_V(n) asm volatile("s_waitcnt vmcnt(" #n ")" ::: "memory")
; #define PG8_WAIT_L(n) asm volatile("s_waitcnt lgkmcnt(" #n ")" ::: "memory")
; #define PG8_BAR __builtin_amdgcn_s_barrier()
; #define PG8_SCHED __builtin_amdgcn_sched_barrier(0)
; template <class Epi, class Sched, bool ALIGN_EPI = false, bool SP2 = false>
; __device__ __forceinline__ void gemm_phase(PG8_LAS unsigned char* lds, const Gemm g, const Sched& S, const Epi& E) {
;     ...
;             PG8_LDB(B0, 0, 0); PG8_LDB(B1, 0, 1); PG8_SCHED; PG8_LDA(At, 0, 0); PG8_STAGE(PG8_SA(1, 1), a1 + hstep, voffA);
;             PG8_WAIT_V(8); PG8_WAIT_L(0); PG8_BAR; PG8_MMA(0, 0, At, B0); PG8_MMA(0, 1, At, B1); PG8_BAR; PG8_SCHED;
;             PG8_LDA(At, 0, 1); PG8_STAGE(PG8_SB(0, 0), b2, voffB); PG8_STAGE(PG8_SB(0, 1), b2 + hstep, voffB); PG8_STAGE(PG8_SA(0, 0), a2, voffA);
;             PG8_WAIT_V(8); PG8_WAIT_L(0); PG8_BAR; PG8_MMA(1, 0, At, B0); PG8_MMA(1, 1, At, B1); PG8_BAR; PG8_SCHED;
.LBB0_915:
	s_add_u32 s10, s42, 0xfffc0080
	s_addc_u32 s11, s43, -1
	s_add_i32 s35, 16, 0x10000
	s_cmp_eq_u32 s34, 12
	s_cselect_b32 s73, s0, s11
	s_cselect_b32 s72, s8, s10
	s_cselect_b32 s69, s9, s27
	s_cselect_b32 s68, s23, s25
	s_add_i32 s45, 16, 0x14000
	v_add_u32_e32 v78, s35, v197
	v_add_u32_e32 v94, s45, v197
	ds_read_b128 v[58:61], v78
	ds_read_b128 v[62:65], v78 offset:1024
	ds_read_b128 v[74:77], v78 offset:2048
	ds_read_b128 v[78:81], v78 offset:3072
	ds_read_b128 v[82:85], v94
	ds_read_b128 v[86:89], v94 offset:1024
	ds_read_b128 v[90:93], v94 offset:2048
	ds_read_b128 v[94:97], v94 offset:3072
	v_lshl_add_u64 v[194:195], s[42:43], 0, v[184:185]
	s_add_i32 m0, s77, 0xc000
	ds_read_b128 v[186:189], v199
	ds_read_b128 v[190:193], v199 offset:1024
	ds_read_b128 v[200:203], v199 offset:2048
	ds_read_b128 v[204:207], v199 offset:3072
	ds_read_b128 v[208:211], v199 offset:4096
	ds_read_b128 v[212:215], v199 offset:5120
	ds_read_b128 v[216:219], v199 offset:6144
	ds_read_b128 v[220:223], v199 offset:7168
	global_load_lds_dwordx4 v[194:195], off
	v_lshl_add_u64 v[194:195], s[42:43], 0, v[182:183]
	s_add_i32 m0, s77, 0xe000
	s_nop 0
	global_load_lds_dwordx4 v[194:195], off
	s_waitcnt vmcnt(8)
	s_waitcnt lgkmcnt(0)
	s_setprio 1
	s_barrier
	v_mfma_f32_16x16x32_bf16 v[158:161], v[58:61], v[186:189], v[158:161]
	v_mfma_f32_16x16x32_bf16 v[154:157], v[74:77], v[186:189], v[154:157]
	v_mfma_f32_16x16x32_bf16 v[142:145], v[58:61], v[200:203], v[142:145]
	v_mfma_f32_16x16x32_bf16 v[138:141], v[74:77], v[200:203], v[138:141]
	v_mfma_f32_16x16x32_bf16 v[126:129], v[58:61], v[208:211], v[126:129]
	v_mfma_f32_16x16x32_bf16 v[122:125], v[74:77], v[208:211], v[122:125]
	v_mfma_f32_16x16x32_bf16 v[110:113], v[58:61], v[216:219], v[110:113]
	v_mfma_f32_16x16x32_bf16 v[106:109], v[74:77], v[216:219], v[106:109]
	v_mfma_f32_16x16x32_bf16 v[158:161], v[62:65], v[190:193], v[158:161]
	v_mfma_f32_16x16x32_bf16 v[154:157], v[78:81], v[190:193], v[154:157]
	v_mfma_f32_16x16x32_bf16 v[142:145], v[62:65], v[204:207], v[142:145]
	v_mfma_f32_16x16x32_bf16 v[138:141], v[78:81], v[204:207], v[138:141]
	v_mfma_f32_16x16x32_bf16 v[126:129], v[62:65], v[212:215], v[126:129]
	v_mfma_f32_16x16x32_bf16 v[122:125], v[78:81], v[212:215], v[122:125]
	v_mfma_f32_16x16x32_bf16 v[110:113], v[62:65], v[220:223], v[110:113]
	v_mfma_f32_16x16x32_bf16 v[106:109], v[78:81], v[220:223], v[106:109]
	s_setprio 0
	s_setprio 1
	v_mfma_f32_16x16x32_bf16 v[150:153], v[82:85], v[186:189], v[150:153]
	v_mfma_f32_16x16x32_bf16 v[146:149], v[90:93], v[186:189], v[146:149]
	v_mfma_f32_16x16x32_bf16 v[134:137], v[82:85], v[200:203], v[134:137]
	v_mfma_f32_16x16x32_bf16 v[130:133], v[90:93], v[200:203], v[130:133]
	v_mfma_f32_16x16x32_bf16 v[118:121], v[82:85], v[208:211], v[118:121]
	v_mfma_f32_16x16x32_bf16 v[114:117], v[90:93], v[208:211], v[114:117]
	v_mfma_f32_16x16x32_bf16 v[102:105], v[82:85], v[216:219], v[102:105]
	v_mfma_f32_16x16x32_bf16 v[98:101], v[90:93], v[216:219], v[98:101]
	v_mfma_f32_16x16x32_bf16 v[150:153], v[86:89], v[190:193], v[150:153]
	v_mfma_f32_16x16x32_bf16 v[146:149], v[94:97], v[190:193], v[146:149]
	v_mfma_f32_16x16x32_bf16 v[134:137], v[86:89], v[204:207], v[134:137]
	v_mfma_f32_16x16x32_bf16 v[130:133], v[94:97], v[204:207], v[130:133]
	v_mfma_f32_16x16x32_bf16 v[118:121], v[86:89], v[212:215], v[118:121]
	v_mfma_f32_16x16x32_bf16 v[114:117], v[94:97], v[212:215], v[114:117]
	v_mfma_f32_16x16x32_bf16 v[102:105], v[86:89], v[220:223], v[102:105]
	v_mfma_f32_16x16x32_bf16 v[98:101], v[94:97], v[220:223], v[98:101]
	s_barrier
	s_setprio 0
	s_add_i32 s10, s35, s76
	v_lshl_add_u64 v[194:195], s[68:69], 0, v[0:1]
	s_mov_b32 m0, s10
	ds_read_b128 v[186:189], v199 offset:16384
	ds_read_b128 v[190:193], v199 offset:17408
	ds_read_b128 v[200:203], v199 offset:18432
	ds_read_b128 v[204:207], v199 offset:19456
	ds_read_b128 v[208:211], v199 offset:20480
	ds_read_b128 v[212:215], v199 offset:21504
	ds_read_b128 v[216:219], v199 offset:22528
	ds_read_b128 v[220:223], v199 offset:23552
	global_load_lds_dwordx4 v[194:195], off
	s_add_i32 m0, s10, 0x2000
	s_add_u32 s10, s68, 0x40000
	v_lshl_add_u64 v[224:225], s[68:69], 0, v[180:181]
	s_addc_u32 s11, s69, 0
	s_add_i32 s35, s45, s76
	global_load_lds_dwordx4 v[224:225], off
	v_lshl_add_u64 v[226:227], s[10:11], 0, v[0:1]
	s_mov_b32 m0, s35
	v_lshl_add_u64 v[238:239], s[72:73], 0, v[178:179]
	global_load_lds_dwordx4 v[226:227], off
	v_lshl_add_u64 v[226:227], s[10:11], 0, v[180:181]
	s_add_i32 m0, s35, 0x2000
	s_nop 0
	global_load_lds_dwordx4 v[226:227], off
	v_lshl_add_u64 v[226:227], s[72:73], 0, v[176:177]
	s_mov_b32 m0, s77
	s_nop 0
	global_load_lds_dwordx4 v[226:227], off
	s_mov_b32 m0, s2
	s_nop 0
	global_load_lds_dwordx4 v[238:239], off
	s_waitcnt vmcnt(8)
	s_waitcnt lgkmcnt(0)
	s_setprio 1
	s_barrier
; #define PG8_STAGE(bufoff, gbase, voff) do { _Pragma("unroll") for (int _i = 0; _i < 2; ++_i) \
;         __builtin_amdgcn_global_load_lds((const unsigned*)((const char*)(gbase) + (voff)[_i]), (PG8_LAS unsigned*)(lds + (bufoff) + ldsw + _i * 8192), 16, 0, 0); } while (0)
; #define PG8_LDA(dst, b, h) do { _Pragma("unroll") for (int m = 0; m < 4; ++m) _Pragma("unroll") for (int k = 0; k < 2; ++k) dst[m][k] = *(const PG8_LAS bf16x8*)(lds + PG8_SA(b, h) + aoff + m * 2048 + k * 1024); } while (0)
; #define PG8_LDB(dst, b, h) do { _Pragma("unroll") for (int n = 0; n < 2; ++n) _Pragma("unroll") for (int k = 0; k < 2; ++k) dst[n][k] = *(const PG8_LAS bf16x8*)(lds + PG8_SB(b, h) + boff + n * 2048 + k * 1024); } while (0)
; #define PG8_MMA(ai, bj, At, Bt) do { __builtin_amdgcn_s_setprio(1); _Pragma("unroll") for (int m = 0; m < 4; ++m) _Pragma("unroll") for (int n = 0; n < 2; ++n) _Pragma("unroll") for (int k = 0; k < 2; ++k) \
;         acc[ai][bj][m][n] = __builtin_amdgcn_mfma_f32_16x16x32_bf16(Bt[n][k], At[m][k], acc[ai][bj][m][n], 0, 0, 0); __builtin_amdgcn_s_setprio(0); } while (0)
; #define PG8_WAIT_V(n) asm volatile("s_waitcnt vmcnt(" #n ")" ::: "memory")
; #define PG8_WAIT_L(n) asm volatile("s_waitcnt lgkmcnt(" #n ")" ::: "memory")
; #define PG8_BAR __builtin_amdgcn_s_barrier()
; #define PG8_SCHED __builtin_amdgcn_sched_barrier(0)
; template <class Epi, class Sched, bool ALIGN_EPI = false, bool SP2 = false>
; __device__ __forceinline__ void gemm_phase(PG8_LAS unsigned char* lds, const Gemm g, const Sched& S, const Epi& E) {
;     ...
;             PG8_WAIT_V(8); PG8_WAIT_L(0); PG8_BAR; PG8_MMA(1, 0, At, B0); PG8_MMA(1, 1, At, B1); PG8_BAR; PG8_SCHED;
;             PG8_LDB(B0, 1, 0); PG8_LDB(B1, 1, 1); PG8_SCHED; PG8_LDA(At, 1, 0); PG8_STAGE(PG8_SA(0, 1), a2 + hstep, voffA);
;             PG8_WAIT_V(8); PG8_WAIT_L(0); PG8_BAR; PG8_MMA(0, 0, At, B0); PG8_MMA(0, 1, At, B1); PG8_BAR; PG8_SCHED;
	v_mfma_f32_16x16x32_bf16 v[70:73], v[58:61], v[186:189], v[70:73]
	v_mfma_f32_16x16x32_bf16 v[66:69], v[74:77], v[186:189], v[66:69]
	v_mfma_f32_16x16x32_bf16 v[46:49], v[58:61], v[200:203], v[46:49]
	v_mfma_f32_16x16x32_bf16 v[42:45], v[74:77], v[200:203], v[42:45]
	v_mfma_f32_16x16x32_bf16 v[30:33], v[58:61], v[208:211], v[30:33]
	v_mfma_f32_16x16x32_bf16 v[26:29], v[74:77], v[208:211], v[26:29]
	v_mfma_f32_16x16x32_bf16 v[14:17], v[58:61], v[216:219], v[14:17]
	v_mfma_f32_16x16x32_bf16 v[10:13], v[74:77], v[216:219], v[10:13]
	v_mfma_f32_16x16x32_bf16 v[70:73], v[62:65], v[190:193], v[70:73]
	v_mfma_f32_16x16x32_bf16 v[66:69], v[78:81], v[190:193], v[66:69]
	v_mfma_f32_16x16x32_bf16 v[46:49], v[62:65], v[204:207], v[46:49]
	v_mfma_f32_16x16x32_bf16 v[42:45], v[78:81], v[204:207], v[42:45]
	v_mfma_f32_16x16x32_bf16 v[30:33], v[62:65], v[212:215], v[30:33]
	v_mfma_f32_16x16x32_bf16 v[26:29], v[78:81], v[212:215], v[26:29]
	v_mfma_f32_16x16x32_bf16 v[14:17], v[62:65], v[220:223], v[14:17]
	v_mfma_f32_16x16x32_bf16 v[10:13], v[78:81], v[220:223], v[10:13]
	s_setprio 0
	s_setprio 1
	v_mfma_f32_16x16x32_bf16 v[54:57], v[82:85], v[186:189], v[54:57]
	v_mfma_f32_16x16x32_bf16 v[50:53], v[90:93], v[186:189], v[50:53]
	v_mfma_f32_16x16x32_bf16 v[38:41], v[82:85], v[200:203], v[38:41]
	v_mfma_f32_16x16x32_bf16 v[34:37], v[90:93], v[200:203], v[34:37]
	v_mfma_f32_16x16x32_bf16 v[22:25], v[82:85], v[208:211], v[22:25]
	v_mfma_f32_16x16x32_bf16 v[18:21], v[90:93], v[208:211], v[18:21]
	v_mfma_f32_16x16x32_bf16 v[6:9], v[82:85], v[216:219], v[6:9]
	v_mfma_f32_16x16x32_bf16 v[2:5], v[90:93], v[216:219], v[2:5]
	v_mfma_f32_16x16x32_bf16 v[54:57], v[86:89], v[190:193], v[54:57]
	v_mfma_f32_16x16x32_bf16 v[50:53], v[94:97], v[190:193], v[50:53]
	v_mfma_f32_16x16x32_bf16 v[38:41], v[86:89], v[204:207], v[38:41]
	v_mfma_f32_16x16x32_bf16 v[34:37], v[94:97], v[204:207], v[34:37]
	v_mfma_f32_16x16x32_bf16 v[22:25], v[86:89], v[212:215], v[22:25]
	v_mfma_f32_16x16x32_bf16 v[18:21], v[94:97], v[212:215], v[18:21]
	v_mfma_f32_16x16x32_bf16 v[6:9], v[86:89], v[220:223], v[6:9]
	v_mfma_f32_16x16x32_bf16 v[2:5], v[94:97], v[220:223], v[2:5]
	s_barrier
	s_setprio 0
	s_add_i32 s35, 16, 0x18000
	s_add_i32 s45, 16, 0x1c000
	v_add_u32_e32 v78, s35, v197
	v_add_u32_e32 v94, s45, v197
	ds_read_b128 v[58:61], v78
	ds_read_b128 v[62:65], v78 offset:1024
	ds_read_b128 v[74:77], v78 offset:2048
	ds_read_b128 v[78:81], v78 offset:3072
	ds_read_b128 v[82:85], v94
	ds_read_b128 v[86:89], v94 offset:1024
	ds_read_b128 v[90:93], v94 offset:2048
	ds_read_b128 v[94:97], v94 offset:3072
	s_add_u32 s10, s72, 0x40000
	s_addc_u32 s11, s73, 0
	s_mov_b32 m0, s3
	v_lshl_add_u64 v[240:241], s[10:11], 0, v[176:177]
	ds_read_b128 v[186:189], v199 offset:32768
	ds_read_b128 v[190:193], v199 offset:33792
	ds_read_b128 v[200:203], v199 offset:34816
	ds_read_b128 v[204:207], v199 offset:35840
	ds_read_b128 v[208:211], v199 offset:36864
	ds_read_b128 v[212:215], v199 offset:37888
	ds_read_b128 v[216:219], v199 offset:38912
	ds_read_b128 v[220:223], v199 offset:39936
	global_load_lds_dwordx4 v[240:241], off
	v_lshl_add_u64 v[240:241], s[10:11], 0, v[178:179]
	s_mov_b32 m0, s78
	s_nop 0
	global_load_lds_dwordx4 v[240:241], off
	s_waitcnt vmcnt(8)
	s_waitcnt lgkmcnt(0)
	s_setprio 1
	s_barrier
	v_mfma_f32_16x16x32_bf16 v[158:161], v[58:61], v[186:189], v[158:161]
	v_mfma_f32_16x16x32_bf16 v[154:157], v[74:77], v[186:189], v[154:157]
	v_mfma_f32_16x16x32_bf16 v[142:145], v[58:61], v[200:203], v[142:145]
	v_mfma_f32_16x16x32_bf16 v[138:141], v[74:77], v[200:203], v[138:141]
	v_mfma_f32_16x16x32_bf16 v[126:129], v[58:61], v[208:211], v[126:129]
	v_mfma_f32_16x16x32_bf16 v[122:125], v[74:77], v[208:211], v[122:125]
	v_mfma_f32_16x16x32_bf16 v[110:113], v[58:61], v[216:219], v[110:113]
	v_mfma_f32_16x16x32_bf16 v[106:109], v[74:77], v[216:219], v[106:109]
	v_mfma_f32_16x16x32_bf16 v[158:161], v[62:65], v[190:193], v[158:161]
	v_mfma_f32_16x16x32_bf16 v[154:157], v[78:81], v[190:193], v[154:157]
	v_mfma_f32_16x16x32_bf16 v[142:145], v[62:65], v[204:207], v[142:145]
	v_mfma_f32_16x16x32_bf16 v[138:141], v[78:81], v[204:207], v[138:141]
	v_mfma_f32_16x16x32_bf16 v[126:129], v[62:65], v[212:215], v[126:129]
	v_mfma_f32_16x16x32_bf16 v[122:125], v[78:81], v[212:215], v[122:125]
	v_mfma_f32_16x16x32_bf16 v[110:113], v[62:65], v[220:223], v[110:113]
	v_mfma_f32_16x16x32_bf16 v[106:109], v[78:81], v[220:223], v[106:109]
	s_setprio 0
	s_setprio 1
	v_mfma_f32_16x16x32_bf16 v[150:153], v[82:85], v[186:189], v[150:153]
	v_mfma_f32_16x16x32_bf16 v[146:149], v[90:93], v[186:189], v[146:149]
	v_mfma_f32_16x16x32_bf16 v[134:137], v[82:85], v[200:203], v[134:137]
	v_mfma_f32_16x16x32_bf16 v[130:133], v[90:93], v[200:203], v[130:133]
	v_mfma_f32_16x16x32_bf16 v[118:121], v[82:85], v[208:211], v[118:121]
	v_mfma_f32_16x16x32_bf16 v[114:117], v[90:93], v[208:211], v[114:117]
	v_mfma_f32_16x16x32_bf16 v[102:105], v[82:85], v[216:219], v[102:105]
	v_mfma_f32_16x16x32_bf16 v[98:101], v[90:93], v[216:219], v[98:101]
	v_mfma_f32_16x16x32_bf16 v[150:153], v[86:89], v[190:193], v[150:153]
	v_mfma_f32_16x16x32_bf16 v[146:149], v[94:97], v[190:193], v[146:149]
	v_mfma_f32_16x16x32_bf16 v[134:137], v[86:89], v[204:207], v[134:137]
	v_mfma_f32_16x16x32_bf16 v[130:133], v[94:97], v[204:207], v[130:133]
	v_mfma_f32_16x16x32_bf16 v[118:121], v[86:89], v[212:215], v[118:121]
	v_mfma_f32_16x16x32_bf16 v[114:117], v[94:97], v[212:215], v[114:117]
	v_mfma_f32_16x16x32_bf16 v[102:105], v[86:89], v[220:223], v[102:105]
	v_mfma_f32_16x16x32_bf16 v[98:101], v[94:97], v[220:223], v[98:101]
	s_barrier
; #define PG8_STAGE(bufoff, gbase, voff) do { _Pragma("unroll") for (int _i = 0; _i < 2; ++_i) \
;         __builtin_amdgcn_global_load_lds((const unsigned*)((const char*)(gbase) + (voff)[_i]), (PG8_LAS unsigned*)(lds + (bufoff) + ldsw + _i * 8192), 16, 0, 0); } while (0)
; #define PG8_LDA(dst, b, h) do { _Pragma("unroll") for (int m = 0; m < 4; ++m) _Pragma("unroll") for (int k = 0; k < 2; ++k) dst[m][k] = *(const PG8_LAS bf16x8*)(lds + PG8_SA(b, h) + aoff + m * 2048 + k * 1024); } while (0)
; #define PG8_MMA(ai, bj, At, Bt) do { __builtin_amdgcn_s_setprio(1); _Pragma("unroll") for (int m = 0; m < 4; ++m) _Pragma("unroll") for (int n = 0; n < 2; ++n) _Pragma("unroll") for (int k = 0; k < 2; ++k) \
;         acc[ai][bj][m][n] = __builtin_amdgcn_mfma_f32_16x16x32_bf16(Bt[n][k], At[m][k], acc[ai][bj][m][n], 0, 0, 0); __builtin_amdgcn_s_setprio(0); } while (0)
; #define PG8_WAIT_V(n) asm volatile("s_waitcnt vmcnt(" #n ")" ::: "memory")
; #define PG8_WAIT_L(n) asm volatile("s_waitcnt lgkmcnt(" #n ")" ::: "memory")
; #define PG8_BAR __builtin_amdgcn_s_barrier()
; #define PG8_SCHED __builtin_amdgcn_sched_barrier(0)
; template <class Epi, class Sched, bool ALIGN_EPI = false, bool SP2 = false>
; __device__ __forceinline__ void gemm_phase(PG8_LAS unsigned char* lds, const Gemm g, const Sched& S, const Epi& E) {
;     ...
;             PG8_WAIT_V(8); PG8_WAIT_L(0); PG8_BAR; PG8_MMA(0, 0, At, B0); PG8_MMA(0, 1, At, B1); PG8_BAR; PG8_SCHED;
;             PG8_LDA(At, 1, 1); PG8_STAGE(PG8_SB(1, 0), b3, voffB); PG8_STAGE(PG8_SB(1, 1), b3 + hstep, voffB); PG8_STAGE(PG8_SA(1, 0), a3, voffA);
;             PG8_WAIT_V(8); PG8_WAIT_L(0); PG8_BAR; PG8_MMA(1, 0, At, B0); PG8_MMA(1, 1, At, B1); PG8_BAR; PG8_SCHED;
;     ...
;         if constexpr (ALIGN_EPI) { if (wr == 0) PG8_BAR; }
	s_setprio 0
	s_add_i32 s10, s35, s76
	v_lshl_add_u64 v[194:195], v[194:195], 0, s[28:29]
	s_mov_b32 m0, s10
	ds_read_b128 v[186:189], v199 offset:49152
	ds_read_b128 v[190:193], v199 offset:50176
	ds_read_b128 v[200:203], v199 offset:51200
	ds_read_b128 v[204:207], v199 offset:52224
	ds_read_b128 v[208:211], v199 offset:53248
	ds_read_b128 v[212:215], v199 offset:54272
	ds_read_b128 v[216:219], v199 offset:55296
	ds_read_b128 v[220:223], v199 offset:56320
	global_load_lds_dwordx4 v[194:195], off
	s_add_i32 m0, s10, 0x2000
	s_add_u32 s10, s68, 0x40080
	v_lshl_add_u64 v[194:195], v[224:225], 0, s[28:29]
	s_addc_u32 s11, s69, 0
	s_add_i32 s35, s45, s76
	global_load_lds_dwordx4 v[194:195], off
	v_lshl_add_u64 v[194:195], s[10:11], 0, v[0:1]
	s_mov_b32 m0, s35
	s_nop 0
	global_load_lds_dwordx4 v[194:195], off
	v_lshl_add_u64 v[194:195], s[10:11], 0, v[180:181]
	s_add_i32 m0, s35, 0x2000
	s_nop 0
	global_load_lds_dwordx4 v[194:195], off
	v_lshl_add_u64 v[194:195], v[226:227], 0, s[28:29]
	s_mov_b32 m0, s94
	s_nop 0
	global_load_lds_dwordx4 v[194:195], off
	v_lshl_add_u64 v[194:195], v[238:239], 0, s[28:29]
	s_mov_b32 m0, s95
	s_nop 0
	global_load_lds_dwordx4 v[194:195], off
	s_waitcnt vmcnt(8)
	s_waitcnt lgkmcnt(0)
	s_setprio 1
	s_barrier
	v_mfma_f32_16x16x32_bf16 v[70:73], v[58:61], v[186:189], v[70:73]
	v_mfma_f32_16x16x32_bf16 v[66:69], v[74:77], v[186:189], v[66:69]
	v_mfma_f32_16x16x32_bf16 v[46:49], v[58:61], v[200:203], v[46:49]
	v_mfma_f32_16x16x32_bf16 v[42:45], v[74:77], v[200:203], v[42:45]
	v_mfma_f32_16x16x32_bf16 v[30:33], v[58:61], v[208:211], v[30:33]
	v_mfma_f32_16x16x32_bf16 v[26:29], v[74:77], v[208:211], v[26:29]
	v_mfma_f32_16x16x32_bf16 v[14:17], v[58:61], v[216:219], v[14:17]
	v_mfma_f32_16x16x32_bf16 v[10:13], v[74:77], v[216:219], v[10:13]
	v_mfma_f32_16x16x32_bf16 v[70:73], v[62:65], v[190:193], v[70:73]
	v_mfma_f32_16x16x32_bf16 v[66:69], v[78:81], v[190:193], v[66:69]
	v_mfma_f32_16x16x32_bf16 v[46:49], v[62:65], v[204:207], v[46:49]
	v_mfma_f32_16x16x32_bf16 v[42:45], v[78:81], v[204:207], v[42:45]
	v_mfma_f32_16x16x32_bf16 v[30:33], v[62:65], v[212:215], v[30:33]
	v_mfma_f32_16x16x32_bf16 v[26:29], v[78:81], v[212:215], v[26:29]
	v_mfma_f32_16x16x32_bf16 v[14:17], v[62:65], v[220:223], v[14:17]
	v_mfma_f32_16x16x32_bf16 v[10:13], v[78:81], v[220:223], v[10:13]
	s_setprio 0
	s_setprio 1
	v_mfma_f32_16x16x32_bf16 v[54:57], v[82:85], v[186:189], v[54:57]
	v_mfma_f32_16x16x32_bf16 v[50:53], v[90:93], v[186:189], v[50:53]
	v_mfma_f32_16x16x32_bf16 v[38:41], v[82:85], v[200:203], v[38:41]
	v_mfma_f32_16x16x32_bf16 v[34:37], v[90:93], v[200:203], v[34:37]
	v_mfma_f32_16x16x32_bf16 v[22:25], v[82:85], v[208:211], v[22:25]
	v_mfma_f32_16x16x32_bf16 v[18:21], v[90:93], v[208:211], v[18:21]
	v_mfma_f32_16x16x32_bf16 v[6:9], v[82:85], v[216:219], v[6:9]
	v_mfma_f32_16x16x32_bf16 v[2:5], v[90:93], v[216:219], v[2:5]
	v_mfma_f32_16x16x32_bf16 v[54:57], v[86:89], v[190:193], v[54:57]
	v_mfma_f32_16x16x32_bf16 v[50:53], v[94:97], v[190:193], v[50:53]
	v_mfma_f32_16x16x32_bf16 v[38:41], v[86:89], v[204:207], v[38:41]
	v_mfma_f32_16x16x32_bf16 v[34:37], v[94:97], v[204:207], v[34:37]
	v_mfma_f32_16x16x32_bf16 v[22:25], v[86:89], v[212:215], v[22:25]
	v_mfma_f32_16x16x32_bf16 v[18:21], v[94:97], v[212:215], v[18:21]
	v_mfma_f32_16x16x32_bf16 v[6:9], v[86:89], v[220:223], v[6:9]
	v_mfma_f32_16x16x32_bf16 v[2:5], v[94:97], v[220:223], v[2:5]
	s_barrier
	s_setprio 0
	s_add_i32 s34, s34, 2
	s_add_u32 s25, s25, 0x100
	s_addc_u32 s27, s27, 0
	s_add_u32 s42, s42, 0x100
	s_addc_u32 s43, s43, 0
	s_cmp_gt_u32 s34, 13
	s_cbranch_scc0 .LBB0_915
	s_and_b64 vcc, exec, s[20:21]
	s_cbranch_vccz .LBB0_918
	s_barrier

; #define PG8_STAGE(bufoff, gbase, voff) do { _Pragma("unroll") for (int _i = 0; _i < 2; ++_i) \
;         __builtin_amdgcn_global_load_lds((const unsigned*)((const char*)(gbase) + (voff)[_i]), (PG8_LAS unsigned*)(lds + (bufoff) + ldsw + _i * 8192), 16, 0, 0); } while (0)
; #define PG8_LDA(dst, b, h) do { _Pragma("unroll") for (int m = 0; m < 4; ++m) _Pragma("unroll") for (int k = 0; k < 2; ++k) dst[m][k] = *(const PG8_LAS bf16x8*)(lds + PG8_SA(b, h) + aoff + m * 2048 + k * 1024); } while (0)
; #define PG8_LDB(dst, b, h) do { _Pragma("unroll") for (int n = 0; n < 2; ++n) _Pragma("unroll") for (int k = 0; k < 2; ++k) dst[n][k] = *(const PG8_LAS bf16x8*)(lds + PG8_SB(b, h) + boff + n * 2048 + k * 1024); } while (0)
; #define PG8_MMA(ai, bj, At, Bt) do { __builtin_amdgcn_s_setprio(1); _Pragma("unroll") for (int m = 0; m < 4; ++m) _Pragma("unroll") for (int n = 0; n < 2; ++n) _Pragma("unroll") for (int k = 0; k < 2; ++k) \
;         acc[ai][bj][m][n] = __builtin_amdgcn_mfma_f32_16x16x32_bf16(Bt[n][k], At[m][k], acc[ai][bj][m][n], 0, 0, 0); __builtin_amdgcn_s_setprio(0); } while (0)
; #define PG8_WAIT_V(n) asm volatile("s_waitcnt vmcnt(" #n ")" ::: "memory")
; #define PG8_WAIT_L(n) asm volatile("s_waitcnt lgkmcnt(" #n ")" ::: "memory")
; #define PG8_BAR __builtin_amdgcn_s_barrier()
; #define PG8_SCHED __builtin_amdgcn_sched_barrier(0)
; template <class Epi, class Sched, bool ALIGN_EPI = false, bool SP2 = false>
; __device__ __forceinline__ void gemm_phase(PG8_LAS unsigned char* lds, const Gemm g, const Sched& S, const Epi& E) {
;     ...
;             PG8_LDB(B0, 0, 0); PG8_LDB(B1, 0, 1); PG8_SCHED; PG8_LDA(At, 0, 0); PG8_STAGE(PG8_SA(1, 1), a1 + hstep, voffA);
;             PG8_WAIT_V(8); PG8_WAIT_L(0); PG8_BAR; PG8_MMA(0, 0, At, B0); PG8_MMA(0, 1, At, B1); PG8_BAR; PG8_SCHED;
;             PG8_LDA(At, 0, 1); PG8_STAGE(PG8_SB(0, 0), b2, voffB); PG8_STAGE(PG8_SB(0, 1), b2 + hstep, voffB); PG8_STAGE(PG8_SA(0, 0), a2, voffA);
;             PG8_WAIT_V(8); PG8_WAIT_L(0); PG8_BAR; PG8_MMA(1, 0, At, B0); PG8_MMA(1, 1, At, B1); PG8_BAR; PG8_SCHED;
.LBB0_1033:
	s_add_u32 s10, s50, 0xfffc0080
	s_addc_u32 s11, s51, -1
	s_add_i32 s69, 16, 0x10000
	s_cmp_eq_u32 s68, 12
	s_cselect_b32 s61, s34, s11
	s_cselect_b32 s60, s35, s10
	s_cselect_b32 s59, s27, s67
	s_cselect_b32 s58, s43, s66
	s_add_i32 s72, 16, 0x14000
	v_add_u32_e32 v142, s69, v177
	v_add_u32_e32 v188, s72, v177
	ds_read_b128 v[130:133], v142
	ds_read_b128 v[134:137], v142 offset:1024
	ds_read_b128 v[138:141], v142 offset:2048
	ds_read_b128 v[142:145], v142 offset:3072
	ds_read_b128 v[158:161], v188
	ds_read_b128 v[180:183], v188 offset:1024
	ds_read_b128 v[184:187], v188 offset:2048
	ds_read_b128 v[188:191], v188 offset:3072
	v_lshl_add_u64 v[224:225], s[50:51], 0, v[156:157]
	s_add_i32 m0, s9, 0xc000
	ds_read_b128 v[192:195], v179
	ds_read_b128 v[196:199], v179 offset:1024
	ds_read_b128 v[200:203], v179 offset:2048
	ds_read_b128 v[204:207], v179 offset:3072
	ds_read_b128 v[208:211], v179 offset:4096
	ds_read_b128 v[212:215], v179 offset:5120
	ds_read_b128 v[216:219], v179 offset:6144
	ds_read_b128 v[220:223], v179 offset:7168
	global_load_lds_dwordx4 v[224:225], off
	v_lshl_add_u64 v[224:225], s[50:51], 0, v[154:155]
	s_add_i32 m0, s9, 0xe000
	s_nop 0
	global_load_lds_dwordx4 v[224:225], off
	s_waitcnt vmcnt(8)
	s_waitcnt lgkmcnt(0)
	s_setprio 1
	s_barrier
	v_mfma_f32_16x16x32_bf16 v[126:129], v[130:133], v[192:195], v[126:129]
	v_mfma_f32_16x16x32_bf16 v[122:125], v[138:141], v[192:195], v[122:125]
	v_mfma_f32_16x16x32_bf16 v[110:113], v[130:133], v[200:203], v[110:113]
	v_mfma_f32_16x16x32_bf16 v[106:109], v[138:141], v[200:203], v[106:109]
	v_mfma_f32_16x16x32_bf16 v[94:97], v[130:133], v[208:211], v[94:97]
	v_mfma_f32_16x16x32_bf16 v[90:93], v[138:141], v[208:211], v[90:93]
	v_mfma_f32_16x16x32_bf16 v[78:81], v[130:133], v[216:219], v[78:81]
	v_mfma_f32_16x16x32_bf16 v[74:77], v[138:141], v[216:219], v[74:77]
	v_mfma_f32_16x16x32_bf16 v[126:129], v[134:137], v[196:199], v[126:129]
	v_mfma_f32_16x16x32_bf16 v[122:125], v[142:145], v[196:199], v[122:125]
	v_mfma_f32_16x16x32_bf16 v[110:113], v[134:137], v[204:207], v[110:113]
	v_mfma_f32_16x16x32_bf16 v[106:109], v[142:145], v[204:207], v[106:109]
	v_mfma_f32_16x16x32_bf16 v[94:97], v[134:137], v[212:215], v[94:97]
	v_mfma_f32_16x16x32_bf16 v[90:93], v[142:145], v[212:215], v[90:93]
	v_mfma_f32_16x16x32_bf16 v[78:81], v[134:137], v[220:223], v[78:81]
	v_mfma_f32_16x16x32_bf16 v[74:77], v[142:145], v[220:223], v[74:77]
	s_setprio 0
	s_setprio 1
	v_mfma_f32_16x16x32_bf16 v[118:121], v[158:161], v[192:195], v[118:121]
	v_mfma_f32_16x16x32_bf16 v[114:117], v[184:187], v[192:195], v[114:117]
	v_mfma_f32_16x16x32_bf16 v[102:105], v[158:161], v[200:203], v[102:105]
	v_mfma_f32_16x16x32_bf16 v[98:101], v[184:187], v[200:203], v[98:101]
	v_mfma_f32_16x16x32_bf16 v[86:89], v[158:161], v[208:211], v[86:89]
	v_mfma_f32_16x16x32_bf16 v[82:85], v[184:187], v[208:211], v[82:85]
	v_mfma_f32_16x16x32_bf16 v[70:73], v[158:161], v[216:219], v[70:73]
	v_mfma_f32_16x16x32_bf16 v[66:69], v[184:187], v[216:219], v[66:69]
	v_mfma_f32_16x16x32_bf16 v[118:121], v[180:183], v[196:199], v[118:121]
	v_mfma_f32_16x16x32_bf16 v[114:117], v[188:191], v[196:199], v[114:117]
	v_mfma_f32_16x16x32_bf16 v[102:105], v[180:183], v[204:207], v[102:105]
	v_mfma_f32_16x16x32_bf16 v[98:101], v[188:191], v[204:207], v[98:101]
	v_mfma_f32_16x16x32_bf16 v[86:89], v[180:183], v[212:215], v[86:89]
	v_mfma_f32_16x16x32_bf16 v[82:85], v[188:191], v[212:215], v[82:85]
	v_mfma_f32_16x16x32_bf16 v[70:73], v[180:183], v[220:223], v[70:73]
	v_mfma_f32_16x16x32_bf16 v[66:69], v[188:191], v[220:223], v[66:69]
	s_barrier
	s_setprio 0
	s_add_i32 s10, s69, s6
	v_lshl_add_u64 v[224:225], s[58:59], 0, v[0:1]
	s_mov_b32 m0, s10
	ds_read_b128 v[192:195], v179 offset:16384
	ds_read_b128 v[196:199], v179 offset:17408
	ds_read_b128 v[200:203], v179 offset:18432
	ds_read_b128 v[204:207], v179 offset:19456
	ds_read_b128 v[208:211], v179 offset:20480
	ds_read_b128 v[212:215], v179 offset:21504
	ds_read_b128 v[216:219], v179 offset:22528
	ds_read_b128 v[220:223], v179 offset:23552
	global_load_lds_dwordx4 v[224:225], off
	s_add_i32 m0, s10, 0x2000
	s_add_u32 s10, s58, 0x40000
	v_lshl_add_u64 v[226:227], s[58:59], 0, v[146:147]
	s_addc_u32 s11, s59, 0
	s_add_i32 s69, s72, s6
	global_load_lds_dwordx4 v[226:227], off
	v_lshl_add_u64 v[238:239], s[10:11], 0, v[0:1]
	s_mov_b32 m0, s69
	v_lshl_add_u64 v[240:241], s[60:61], 0, v[148:149]
	global_load_lds_dwordx4 v[238:239], off
	v_lshl_add_u64 v[238:239], s[10:11], 0, v[146:147]
	s_add_i32 m0, s69, 0x2000
	s_nop 0
	global_load_lds_dwordx4 v[238:239], off
	v_lshl_add_u64 v[238:239], s[60:61], 0, v[150:151]
	s_mov_b32 m0, s9
	s_nop 0
	global_load_lds_dwordx4 v[238:239], off
	s_mov_b32 m0, s54
	s_nop 0
	global_load_lds_dwordx4 v[240:241], off
	s_waitcnt vmcnt(8)
	s_waitcnt lgkmcnt(0)
	s_setprio 1
	s_barrier
; #define PG8_STAGE(bufoff, gbase, voff) do { _Pragma("unroll") for (int _i = 0; _i < 2; ++_i) \
;         __builtin_amdgcn_global_load_lds((const unsigned*)((const char*)(gbase) + (voff)[_i]), (PG8_LAS unsigned*)(lds + (bufoff) + ldsw + _i * 8192), 16, 0, 0); } while (0)
; #define PG8_LDA(dst, b, h) do { _Pragma("unroll") for (int m = 0; m < 4; ++m) _Pragma("unroll") for (int k = 0; k < 2; ++k) dst[m][k] = *(const PG8_LAS bf16x8*)(lds + PG8_SA(b, h) + aoff + m * 2048 + k * 1024); } while (0)
; #define PG8_LDB(dst, b, h) do { _Pragma("unroll") for (int n = 0; n < 2; ++n) _Pragma("unroll") for (int k = 0; k < 2; ++k) dst[n][k] = *(const PG8_LAS bf16x8*)(lds + PG8_SB(b, h) + boff + n * 2048 + k * 1024); } while (0)
; #define PG8_MMA(ai, bj, At, Bt) do { __builtin_amdgcn_s_setprio(1); _Pragma("unroll") for (int m = 0; m < 4; ++m) _Pragma("unroll") for (int n = 0; n < 2; ++n) _Pragma("unroll") for (int k = 0; k < 2; ++k) \
;         acc[ai][bj][m][n] = __builtin_amdgcn_mfma_f32_16x16x32_bf16(Bt[n][k], At[m][k], acc[ai][bj][m][n], 0, 0, 0); __builtin_amdgcn_s_setprio(0); } while (0)
; #define PG8_WAIT_V(n) asm volatile("s_waitcnt vmcnt(" #n ")" ::: "memory")
; #define PG8_WAIT_L(n) asm volatile("s_waitcnt lgkmcnt(" #n ")" ::: "memory")
; #define PG8_BAR __builtin_amdgcn_s_barrier()
; #define PG8_SCHED __builtin_amdgcn_sched_barrier(0)
; template <class Epi, class Sched, bool ALIGN_EPI = false, bool SP2 = false>
; __device__ __forceinline__ void gemm_phase(PG8_LAS unsigned char* lds, const Gemm g, const Sched& S, const Epi& E) {
;     ...
;             PG8_WAIT_V(8); PG8_WAIT_L(0); PG8_BAR; PG8_MMA(1, 0, At, B0); PG8_MMA(1, 1, At, B1); PG8_BAR; PG8_SCHED;
;             PG8_LDB(B0, 1, 0); PG8_LDB(B1, 1, 1); PG8_SCHED; PG8_LDA(At, 1, 0); PG8_STAGE(PG8_SA(0, 1), a2 + hstep, voffA);
;             PG8_WAIT_V(8); PG8_WAIT_L(0); PG8_BAR; PG8_MMA(0, 0, At, B0); PG8_MMA(0, 1, At, B1); PG8_BAR; PG8_SCHED;
	v_mfma_f32_16x16x32_bf16 v[62:65], v[130:133], v[192:195], v[62:65]
	v_mfma_f32_16x16x32_bf16 v[58:61], v[138:141], v[192:195], v[58:61]
	v_mfma_f32_16x16x32_bf16 v[46:49], v[130:133], v[200:203], v[46:49]
	v_mfma_f32_16x16x32_bf16 v[42:45], v[138:141], v[200:203], v[42:45]
	v_mfma_f32_16x16x32_bf16 v[30:33], v[130:133], v[208:211], v[30:33]
	v_mfma_f32_16x16x32_bf16 v[26:29], v[138:141], v[208:211], v[26:29]
	v_mfma_f32_16x16x32_bf16 v[14:17], v[130:133], v[216:219], v[14:17]
	v_mfma_f32_16x16x32_bf16 v[10:13], v[138:141], v[216:219], v[10:13]
	v_mfma_f32_16x16x32_bf16 v[62:65], v[134:137], v[196:199], v[62:65]
	v_mfma_f32_16x16x32_bf16 v[58:61], v[142:145], v[196:199], v[58:61]
	v_mfma_f32_16x16x32_bf16 v[46:49], v[134:137], v[204:207], v[46:49]
	v_mfma_f32_16x16x32_bf16 v[42:45], v[142:145], v[204:207], v[42:45]
	v_mfma_f32_16x16x32_bf16 v[30:33], v[134:137], v[212:215], v[30:33]
	v_mfma_f32_16x16x32_bf16 v[26:29], v[142:145], v[212:215], v[26:29]
	v_mfma_f32_16x16x32_bf16 v[14:17], v[134:137], v[220:223], v[14:17]
	v_mfma_f32_16x16x32_bf16 v[10:13], v[142:145], v[220:223], v[10:13]
	s_setprio 0
	s_setprio 1
	v_mfma_f32_16x16x32_bf16 v[54:57], v[158:161], v[192:195], v[54:57]
	v_mfma_f32_16x16x32_bf16 v[50:53], v[184:187], v[192:195], v[50:53]
	v_mfma_f32_16x16x32_bf16 v[38:41], v[158:161], v[200:203], v[38:41]
	v_mfma_f32_16x16x32_bf16 v[34:37], v[184:187], v[200:203], v[34:37]
	v_mfma_f32_16x16x32_bf16 v[22:25], v[158:161], v[208:211], v[22:25]
	v_mfma_f32_16x16x32_bf16 v[18:21], v[184:187], v[208:211], v[18:21]
	v_mfma_f32_16x16x32_bf16 v[6:9], v[158:161], v[216:219], v[6:9]
	v_mfma_f32_16x16x32_bf16 v[2:5], v[184:187], v[216:219], v[2:5]
	v_mfma_f32_16x16x32_bf16 v[54:57], v[180:183], v[196:199], v[54:57]
	v_mfma_f32_16x16x32_bf16 v[50:53], v[188:191], v[196:199], v[50:53]
	v_mfma_f32_16x16x32_bf16 v[38:41], v[180:183], v[204:207], v[38:41]
	v_mfma_f32_16x16x32_bf16 v[34:37], v[188:191], v[204:207], v[34:37]
	v_mfma_f32_16x16x32_bf16 v[22:25], v[180:183], v[212:215], v[22:25]
	v_mfma_f32_16x16x32_bf16 v[18:21], v[188:191], v[212:215], v[18:21]
	v_mfma_f32_16x16x32_bf16 v[6:9], v[180:183], v[220:223], v[6:9]
	v_mfma_f32_16x16x32_bf16 v[2:5], v[188:191], v[220:223], v[2:5]
	s_barrier
	s_setprio 0
	s_add_i32 s69, 16, 0x18000
	s_add_i32 s72, 16, 0x1c000
	v_add_u32_e32 v142, s69, v177
	v_add_u32_e32 v188, s72, v177
	ds_read_b128 v[130:133], v142
	ds_read_b128 v[134:137], v142 offset:1024
	ds_read_b128 v[138:141], v142 offset:2048
	ds_read_b128 v[142:145], v142 offset:3072
	ds_read_b128 v[158:161], v188
	ds_read_b128 v[180:183], v188 offset:1024
	ds_read_b128 v[184:187], v188 offset:2048
	ds_read_b128 v[188:191], v188 offset:3072
	s_add_u32 s10, s60, 0x40000
	s_addc_u32 s11, s61, 0
	s_mov_b32 m0, s55
	v_lshl_add_u64 v[242:243], s[10:11], 0, v[150:151]
	ds_read_b128 v[192:195], v179 offset:32768
	ds_read_b128 v[196:199], v179 offset:33792
	ds_read_b128 v[200:203], v179 offset:34816
	ds_read_b128 v[204:207], v179 offset:35840
	ds_read_b128 v[208:211], v179 offset:36864
	ds_read_b128 v[212:215], v179 offset:37888
	ds_read_b128 v[216:219], v179 offset:38912
	ds_read_b128 v[220:223], v179 offset:39936
	global_load_lds_dwordx4 v[242:243], off
	v_lshl_add_u64 v[242:243], s[10:11], 0, v[148:149]
	s_mov_b32 m0, s56
	s_nop 0
	global_load_lds_dwordx4 v[242:243], off
	s_waitcnt vmcnt(8)
	s_waitcnt lgkmcnt(0)
	s_setprio 1
	s_barrier
	v_mfma_f32_16x16x32_bf16 v[126:129], v[130:133], v[192:195], v[126:129]
	v_mfma_f32_16x16x32_bf16 v[122:125], v[138:141], v[192:195], v[122:125]
	v_mfma_f32_16x16x32_bf16 v[110:113], v[130:133], v[200:203], v[110:113]
	v_mfma_f32_16x16x32_bf16 v[106:109], v[138:141], v[200:203], v[106:109]
	v_mfma_f32_16x16x32_bf16 v[94:97], v[130:133], v[208:211], v[94:97]
	v_mfma_f32_16x16x32_bf16 v[90:93], v[138:141], v[208:211], v[90:93]
	v_mfma_f32_16x16x32_bf16 v[78:81], v[130:133], v[216:219], v[78:81]
	v_mfma_f32_16x16x32_bf16 v[74:77], v[138:141], v[216:219], v[74:77]
	v_mfma_f32_16x16x32_bf16 v[126:129], v[134:137], v[196:199], v[126:129]
	v_mfma_f32_16x16x32_bf16 v[122:125], v[142:145], v[196:199], v[122:125]
	v_mfma_f32_16x16x32_bf16 v[110:113], v[134:137], v[204:207], v[110:113]
	v_mfma_f32_16x16x32_bf16 v[106:109], v[142:145], v[204:207], v[106:109]
	v_mfma_f32_16x16x32_bf16 v[94:97], v[134:137], v[212:215], v[94:97]
	v_mfma_f32_16x16x32_bf16 v[90:93], v[142:145], v[212:215], v[90:93]
	v_mfma_f32_16x16x32_bf16 v[78:81], v[134:137], v[220:223], v[78:81]
	v_mfma_f32_16x16x32_bf16 v[74:77], v[142:145], v[220:223], v[74:77]
	s_setprio 0
	s_setprio 1
	v_mfma_f32_16x16x32_bf16 v[118:121], v[158:161], v[192:195], v[118:121]
	v_mfma_f32_16x16x32_bf16 v[114:117], v[184:187], v[192:195], v[114:117]
	v_mfma_f32_16x16x32_bf16 v[102:105], v[158:161], v[200:203], v[102:105]
	v_mfma_f32_16x16x32_bf16 v[98:101], v[184:187], v[200:203], v[98:101]
	v_mfma_f32_16x16x32_bf16 v[86:89], v[158:161], v[208:211], v[86:89]
	v_mfma_f32_16x16x32_bf16 v[82:85], v[184:187], v[208:211], v[82:85]
	v_mfma_f32_16x16x32_bf16 v[70:73], v[158:161], v[216:219], v[70:73]
	v_mfma_f32_16x16x32_bf16 v[66:69], v[184:187], v[216:219], v[66:69]
	v_mfma_f32_16x16x32_bf16 v[118:121], v[180:183], v[196:199], v[118:121]
	v_mfma_f32_16x16x32_bf16 v[114:117], v[188:191], v[196:199], v[114:117]
	v_mfma_f32_16x16x32_bf16 v[102:105], v[180:183], v[204:207], v[102:105]
	v_mfma_f32_16x16x32_bf16 v[98:101], v[188:191], v[204:207], v[98:101]
	v_mfma_f32_16x16x32_bf16 v[86:89], v[180:183], v[212:215], v[86:89]
	v_mfma_f32_16x16x32_bf16 v[82:85], v[188:191], v[212:215], v[82:85]
	v_mfma_f32_16x16x32_bf16 v[70:73], v[180:183], v[220:223], v[70:73]
	v_mfma_f32_16x16x32_bf16 v[66:69], v[188:191], v[220:223], v[66:69]
	s_barrier
; #define PG8_STAGE(bufoff, gbase, voff) do { _Pragma("unroll") for (int _i = 0; _i < 2; ++_i) \
;         __builtin_amdgcn_global_load_lds((const unsigned*)((const char*)(gbase) + (voff)[_i]), (PG8_LAS unsigned*)(lds + (bufoff) + ldsw + _i * 8192), 16, 0, 0); } while (0)
; #define PG8_LDA(dst, b, h) do { _Pragma("unroll") for (int m = 0; m < 4; ++m) _Pragma("unroll") for (int k = 0; k < 2; ++k) dst[m][k] = *(const PG8_LAS bf16x8*)(lds + PG8_SA(b, h) + aoff + m * 2048 + k * 1024); } while (0)
; #define PG8_MMA(ai, bj, At, Bt) do { __builtin_amdgcn_s_setprio(1); _Pragma("unroll") for (int m = 0; m < 4; ++m) _Pragma("unroll") for (int n = 0; n < 2; ++n) _Pragma("unroll") for (int k = 0; k < 2; ++k) \
;         acc[ai][bj][m][n] = __builtin_amdgcn_mfma_f32_16x16x32_bf16(Bt[n][k], At[m][k], acc[ai][bj][m][n], 0, 0, 0); __builtin_amdgcn_s_setprio(0); } while (0)
; #define PG8_WAIT_V(n) asm volatile("s_waitcnt vmcnt(" #n ")" ::: "memory")
; #define PG8_WAIT_L(n) asm volatile("s_waitcnt lgkmcnt(" #n ")" ::: "memory")
; #define PG8_BAR __builtin_amdgcn_s_barrier()
; #define PG8_SCHED __builtin_amdgcn_sched_barrier(0)
; template <class Epi, class Sched, bool ALIGN_EPI = false, bool SP2 = false>
; __device__ __forceinline__ void gemm_phase(PG8_LAS unsigned char* lds, const Gemm g, const Sched& S, const Epi& E) {
;     ...
;             PG8_WAIT_V(8); PG8_WAIT_L(0); PG8_BAR; PG8_MMA(0, 0, At, B0); PG8_MMA(0, 1, At, B1); PG8_BAR; PG8_SCHED;
;             PG8_LDA(At, 1, 1); PG8_STAGE(PG8_SB(1, 0), b3, voffB); PG8_STAGE(PG8_SB(1, 1), b3 + hstep, voffB); PG8_STAGE(PG8_SA(1, 0), a3, voffA);
;             PG8_WAIT_V(8); PG8_WAIT_L(0); PG8_BAR; PG8_MMA(1, 0, At, B0); PG8_MMA(1, 1, At, B1); PG8_BAR; PG8_SCHED;
;     ...
;         if constexpr (ALIGN_EPI) { if (wr == 0) PG8_BAR; }
	s_setprio 0
	s_add_i32 s10, s69, s6
	v_lshl_add_u64 v[224:225], v[224:225], 0, s[28:29]
	s_mov_b32 m0, s10
	ds_read_b128 v[192:195], v179 offset:49152
	ds_read_b128 v[196:199], v179 offset:50176
	ds_read_b128 v[200:203], v179 offset:51200
	ds_read_b128 v[204:207], v179 offset:52224
	ds_read_b128 v[208:211], v179 offset:53248
	ds_read_b128 v[212:215], v179 offset:54272
	ds_read_b128 v[216:219], v179 offset:55296
	ds_read_b128 v[220:223], v179 offset:56320
	global_load_lds_dwordx4 v[224:225], off
	s_add_i32 m0, s10, 0x2000
	s_add_u32 s10, s58, 0x40080
	v_lshl_add_u64 v[224:225], v[226:227], 0, s[28:29]
	s_addc_u32 s11, s59, 0
	s_add_i32 s58, s72, s6
	global_load_lds_dwordx4 v[224:225], off
	v_lshl_add_u64 v[224:225], s[10:11], 0, v[0:1]
	s_mov_b32 m0, s58
	s_nop 0
	global_load_lds_dwordx4 v[224:225], off
	v_lshl_add_u64 v[224:225], s[10:11], 0, v[146:147]
	s_add_i32 m0, s58, 0x2000
	s_nop 0
	global_load_lds_dwordx4 v[224:225], off
	v_lshl_add_u64 v[224:225], v[238:239], 0, s[28:29]
	s_mov_b32 m0, s63
	s_nop 0
	global_load_lds_dwordx4 v[224:225], off
	v_lshl_add_u64 v[224:225], v[240:241], 0, s[28:29]
	s_mov_b32 m0, s64
	s_nop 0
	global_load_lds_dwordx4 v[224:225], off
	s_waitcnt vmcnt(8)
	s_waitcnt lgkmcnt(0)
	s_setprio 1
	s_barrier
	v_mfma_f32_16x16x32_bf16 v[62:65], v[130:133], v[192:195], v[62:65]
	v_mfma_f32_16x16x32_bf16 v[58:61], v[138:141], v[192:195], v[58:61]
	v_mfma_f32_16x16x32_bf16 v[46:49], v[130:133], v[200:203], v[46:49]
	v_mfma_f32_16x16x32_bf16 v[42:45], v[138:141], v[200:203], v[42:45]
	v_mfma_f32_16x16x32_bf16 v[30:33], v[130:133], v[208:211], v[30:33]
	v_mfma_f32_16x16x32_bf16 v[26:29], v[138:141], v[208:211], v[26:29]
	v_mfma_f32_16x16x32_bf16 v[14:17], v[130:133], v[216:219], v[14:17]
	v_mfma_f32_16x16x32_bf16 v[10:13], v[138:141], v[216:219], v[10:13]
	v_mfma_f32_16x16x32_bf16 v[62:65], v[134:137], v[196:199], v[62:65]
	v_mfma_f32_16x16x32_bf16 v[58:61], v[142:145], v[196:199], v[58:61]
	v_mfma_f32_16x16x32_bf16 v[46:49], v[134:137], v[204:207], v[46:49]
	v_mfma_f32_16x16x32_bf16 v[42:45], v[142:145], v[204:207], v[42:45]
	v_mfma_f32_16x16x32_bf16 v[30:33], v[134:137], v[212:215], v[30:33]
	v_mfma_f32_16x16x32_bf16 v[26:29], v[142:145], v[212:215], v[26:29]
	v_mfma_f32_16x16x32_bf16 v[14:17], v[134:137], v[220:223], v[14:17]
	v_mfma_f32_16x16x32_bf16 v[10:13], v[142:145], v[220:223], v[10:13]
	s_setprio 0
	s_setprio 1
	v_mfma_f32_16x16x32_bf16 v[54:57], v[158:161], v[192:195], v[54:57]
	v_mfma_f32_16x16x32_bf16 v[50:53], v[184:187], v[192:195], v[50:53]
	v_mfma_f32_16x16x32_bf16 v[38:41], v[158:161], v[200:203], v[38:41]
	v_mfma_f32_16x16x32_bf16 v[34:37], v[184:187], v[200:203], v[34:37]
	v_mfma_f32_16x16x32_bf16 v[22:25], v[158:161], v[208:211], v[22:25]
	v_mfma_f32_16x16x32_bf16 v[18:21], v[184:187], v[208:211], v[18:21]
	v_mfma_f32_16x16x32_bf16 v[6:9], v[158:161], v[216:219], v[6:9]
	v_mfma_f32_16x16x32_bf16 v[2:5], v[184:187], v[216:219], v[2:5]
	v_mfma_f32_16x16x32_bf16 v[54:57], v[180:183], v[196:199], v[54:57]
	v_mfma_f32_16x16x32_bf16 v[50:53], v[188:191], v[196:199], v[50:53]
	v_mfma_f32_16x16x32_bf16 v[38:41], v[180:183], v[204:207], v[38:41]
	v_mfma_f32_16x16x32_bf16 v[34:37], v[188:191], v[204:207], v[34:37]
	v_mfma_f32_16x16x32_bf16 v[22:25], v[180:183], v[212:215], v[22:25]
	v_mfma_f32_16x16x32_bf16 v[18:21], v[188:191], v[212:215], v[18:21]
	v_mfma_f32_16x16x32_bf16 v[6:9], v[180:183], v[220:223], v[6:9]
	v_mfma_f32_16x16x32_bf16 v[2:5], v[188:191], v[220:223], v[2:5]
	s_barrier
	s_setprio 0
	s_add_i32 s68, s68, 2
	s_add_u32 s66, s66, 0x100
	s_addc_u32 s67, s67, 0
	s_add_u32 s50, s50, 0x100
	s_addc_u32 s51, s51, 0
	s_cmp_gt_u32 s68, 13
	s_cbranch_scc0 .LBB0_1033
	s_and_b64 vcc, exec, s[24:25]
	s_cbranch_vccz .LBB0_1036
	s_barrier

; #define PG8_STAGE(bufoff, gbase, voff) do { _Pragma("unroll") for (int _i = 0; _i < 2; ++_i) \
;         __builtin_amdgcn_global_load_lds((const unsigned*)((const char*)(gbase) + (voff)[_i]), (PG8_LAS unsigned*)(lds + (bufoff) + ldsw + _i * 8192), 16, 0, 0); } while (0)
; #define PG8_LDA(dst, b, h) do { _Pragma("unroll") for (int m = 0; m < 4; ++m) _Pragma("unroll") for (int k = 0; k < 2; ++k) dst[m][k] = *(const PG8_LAS bf16x8*)(lds + PG8_SA(b, h) + aoff + m * 2048 + k * 1024); } while (0)
; #define PG8_LDB(dst, b, h) do { _Pragma("unroll") for (int n = 0; n < 2; ++n) _Pragma("unroll") for (int k = 0; k < 2; ++k) dst[n][k] = *(const PG8_LAS bf16x8*)(lds + PG8_SB(b, h) + boff + n * 2048 + k * 1024); } while (0)
; #define PG8_MMA(ai, bj, At, Bt) do { __builtin_amdgcn_s_setprio(1); _Pragma("unroll") for (int m = 0; m < 4; ++m) _Pragma("unroll") for (int n = 0; n < 2; ++n) _Pragma("unroll") for (int k = 0; k < 2; ++k) \
;         acc[ai][bj][m][n] = __builtin_amdgcn_mfma_f32_16x16x32_bf16(Bt[n][k], At[m][k], acc[ai][bj][m][n], 0, 0, 0); __builtin_amdgcn_s_setprio(0); } while (0)
; #define PG8_WAIT_V(n) asm volatile("s_waitcnt vmcnt(" #n ")" ::: "memory")
; #define PG8_WAIT_L(n) asm volatile("s_waitcnt lgkmcnt(" #n ")" ::: "memory")
; #define PG8_BAR __builtin_amdgcn_s_barrier()
; #define PG8_SCHED __builtin_amdgcn_sched_barrier(0)
; template <class Epi, class Sched, bool ALIGN_EPI = false, bool SP2 = false>
; __device__ __forceinline__ void gemm_phase(PG8_LAS unsigned char* lds, const Gemm g, const Sched& S, const Epi& E) {
;     ...
;             PG8_LDB(B0, 0, 0); PG8_LDB(B1, 0, 1); PG8_SCHED; PG8_LDA(At, 0, 0); PG8_STAGE(PG8_SA(1, 1), a1 + hstep, voffA);
;             PG8_WAIT_V(8); PG8_WAIT_L(0); PG8_BAR; PG8_MMA(0, 0, At, B0); PG8_MMA(0, 1, At, B1); PG8_BAR; PG8_SCHED;
;             PG8_LDA(At, 0, 1); PG8_STAGE(PG8_SB(0, 0), b2, voffB); PG8_STAGE(PG8_SB(0, 1), b2 + hstep, voffB); PG8_STAGE(PG8_SA(0, 0), a2, voffA);
;             PG8_WAIT_V(8); PG8_WAIT_L(0); PG8_BAR; PG8_MMA(1, 0, At, B0); PG8_MMA(1, 1, At, B1); PG8_BAR; PG8_SCHED;
.LBB0_1208:
	s_add_u32 s42, s24, 0x100
	s_addc_u32 s43, s25, 0
	s_add_i32 s10, 16, 0x10000
	s_cmp_eq_u32 s73, 40
	s_cselect_b32 s69, s23, s43
	s_cselect_b32 s68, s22, s42
	s_cselect_b32 s45, s27, s72
	s_cselect_b32 s44, s26, s35
	s_add_i32 vcc_lo, 16, 0x14000
	v_add_u32_e32 v78, s10, v197
	v_add_u32_e32 v94, vcc_lo, v197
	ds_read_b128 v[58:61], v78
	ds_read_b128 v[62:65], v78 offset:1024
	ds_read_b128 v[74:77], v78 offset:2048
	ds_read_b128 v[78:81], v78 offset:3072
	ds_read_b128 v[82:85], v94
	ds_read_b128 v[86:89], v94 offset:1024
	ds_read_b128 v[90:93], v94 offset:2048
	ds_read_b128 v[94:97], v94 offset:3072
	v_lshl_add_u64 v[194:195], s[24:25], 0, v[184:185]
	s_add_i32 m0, s95, 0xc000
	ds_read_b128 v[186:189], v199
	ds_read_b128 v[190:193], v199 offset:1024
	ds_read_b128 v[200:203], v199 offset:2048
	ds_read_b128 v[204:207], v199 offset:3072
	ds_read_b128 v[208:211], v199 offset:4096
	ds_read_b128 v[212:215], v199 offset:5120
	ds_read_b128 v[216:219], v199 offset:6144
	ds_read_b128 v[220:223], v199 offset:7168
	global_load_lds_dwordx4 v[194:195], off
	v_lshl_add_u64 v[194:195], s[24:25], 0, v[182:183]
	s_add_i32 m0, s95, 0xe000
	s_nop 0
	global_load_lds_dwordx4 v[194:195], off
	s_waitcnt vmcnt(8)
	s_waitcnt lgkmcnt(0)
	s_setprio 1
	s_barrier
	v_mfma_f32_16x16x32_bf16 v[158:161], v[58:61], v[186:189], v[158:161]
	v_mfma_f32_16x16x32_bf16 v[154:157], v[74:77], v[186:189], v[154:157]
	v_mfma_f32_16x16x32_bf16 v[142:145], v[58:61], v[200:203], v[142:145]
	v_mfma_f32_16x16x32_bf16 v[138:141], v[74:77], v[200:203], v[138:141]
	v_mfma_f32_16x16x32_bf16 v[126:129], v[58:61], v[208:211], v[126:129]
	v_mfma_f32_16x16x32_bf16 v[122:125], v[74:77], v[208:211], v[122:125]
	v_mfma_f32_16x16x32_bf16 v[110:113], v[58:61], v[216:219], v[110:113]
	v_mfma_f32_16x16x32_bf16 v[106:109], v[74:77], v[216:219], v[106:109]
	v_mfma_f32_16x16x32_bf16 v[158:161], v[62:65], v[190:193], v[158:161]
	v_mfma_f32_16x16x32_bf16 v[154:157], v[78:81], v[190:193], v[154:157]
	v_mfma_f32_16x16x32_bf16 v[142:145], v[62:65], v[204:207], v[142:145]
	v_mfma_f32_16x16x32_bf16 v[138:141], v[78:81], v[204:207], v[138:141]
	v_mfma_f32_16x16x32_bf16 v[126:129], v[62:65], v[212:215], v[126:129]
	v_mfma_f32_16x16x32_bf16 v[122:125], v[78:81], v[212:215], v[122:125]
	v_mfma_f32_16x16x32_bf16 v[110:113], v[62:65], v[220:223], v[110:113]
	v_mfma_f32_16x16x32_bf16 v[106:109], v[78:81], v[220:223], v[106:109]
	s_setprio 0
	s_setprio 1
	v_mfma_f32_16x16x32_bf16 v[150:153], v[82:85], v[186:189], v[150:153]
	v_mfma_f32_16x16x32_bf16 v[146:149], v[90:93], v[186:189], v[146:149]
	v_mfma_f32_16x16x32_bf16 v[134:137], v[82:85], v[200:203], v[134:137]
	v_mfma_f32_16x16x32_bf16 v[130:133], v[90:93], v[200:203], v[130:133]
	v_mfma_f32_16x16x32_bf16 v[118:121], v[82:85], v[208:211], v[118:121]
	v_mfma_f32_16x16x32_bf16 v[114:117], v[90:93], v[208:211], v[114:117]
	v_mfma_f32_16x16x32_bf16 v[102:105], v[82:85], v[216:219], v[102:105]
	v_mfma_f32_16x16x32_bf16 v[98:101], v[90:93], v[216:219], v[98:101]
	v_mfma_f32_16x16x32_bf16 v[150:153], v[86:89], v[190:193], v[150:153]
	v_mfma_f32_16x16x32_bf16 v[146:149], v[94:97], v[190:193], v[146:149]
	v_mfma_f32_16x16x32_bf16 v[134:137], v[86:89], v[204:207], v[134:137]
	v_mfma_f32_16x16x32_bf16 v[130:133], v[94:97], v[204:207], v[130:133]
	v_mfma_f32_16x16x32_bf16 v[118:121], v[86:89], v[212:215], v[118:121]
	v_mfma_f32_16x16x32_bf16 v[114:117], v[94:97], v[212:215], v[114:117]
	v_mfma_f32_16x16x32_bf16 v[102:105], v[86:89], v[220:223], v[102:105]
	v_mfma_f32_16x16x32_bf16 v[98:101], v[94:97], v[220:223], v[98:101]
	s_barrier
	s_setprio 0
	s_add_i32 s10, s10, s94
	v_lshl_add_u64 v[194:195], s[44:45], 0, v[0:1]
	s_mov_b32 m0, s10
	ds_read_b128 v[186:189], v199 offset:16384
	ds_read_b128 v[190:193], v199 offset:17408
	ds_read_b128 v[200:203], v199 offset:18432
	ds_read_b128 v[204:207], v199 offset:19456
	ds_read_b128 v[208:211], v199 offset:20480
	ds_read_b128 v[212:215], v199 offset:21504
	ds_read_b128 v[216:219], v199 offset:22528
	ds_read_b128 v[220:223], v199 offset:23552
	global_load_lds_dwordx4 v[194:195], off
	s_add_i32 m0, s10, 0x2000
	s_add_u32 s10, s44, 0xb0000
	v_lshl_add_u64 v[224:225], s[44:45], 0, v[180:181]
	s_addc_u32 s11, s45, 0
	s_add_i32 s24, vcc_lo, s94
	global_load_lds_dwordx4 v[224:225], off
	v_lshl_add_u64 v[226:227], s[10:11], 0, v[0:1]
	s_mov_b32 m0, s24
	v_lshl_add_u64 v[238:239], s[68:69], 0, v[178:179]
	global_load_lds_dwordx4 v[226:227], off
	v_lshl_add_u64 v[226:227], s[10:11], 0, v[180:181]
	s_add_i32 m0, s24, 0x2000
	s_nop 0
	global_load_lds_dwordx4 v[226:227], off
	v_lshl_add_u64 v[226:227], s[68:69], 0, v[176:177]
	s_mov_b32 m0, s95
	s_nop 0
	global_load_lds_dwordx4 v[226:227], off
	s_mov_b32 m0, s2
	s_nop 0
	global_load_lds_dwordx4 v[238:239], off
	s_waitcnt vmcnt(8)
	s_waitcnt lgkmcnt(0)
	s_setprio 1
	s_barrier
; #define PG8_STAGE(bufoff, gbase, voff) do { _Pragma("unroll") for (int _i = 0; _i < 2; ++_i) \
;         __builtin_amdgcn_global_load_lds((const unsigned*)((const char*)(gbase) + (voff)[_i]), (PG8_LAS unsigned*)(lds + (bufoff) + ldsw + _i * 8192), 16, 0, 0); } while (0)
; #define PG8_LDA(dst, b, h) do { _Pragma("unroll") for (int m = 0; m < 4; ++m) _Pragma("unroll") for (int k = 0; k < 2; ++k) dst[m][k] = *(const PG8_LAS bf16x8*)(lds + PG8_SA(b, h) + aoff + m * 2048 + k * 1024); } while (0)
; #define PG8_LDB(dst, b, h) do { _Pragma("unroll") for (int n = 0; n < 2; ++n) _Pragma("unroll") for (int k = 0; k < 2; ++k) dst[n][k] = *(const PG8_LAS bf16x8*)(lds + PG8_SB(b, h) + boff + n * 2048 + k * 1024); } while (0)
; #define PG8_MMA(ai, bj, At, Bt) do { __builtin_amdgcn_s_setprio(1); _Pragma("unroll") for (int m = 0; m < 4; ++m) _Pragma("unroll") for (int n = 0; n < 2; ++n) _Pragma("unroll") for (int k = 0; k < 2; ++k) \
;         acc[ai][bj][m][n] = __builtin_amdgcn_mfma_f32_16x16x32_bf16(Bt[n][k], At[m][k], acc[ai][bj][m][n], 0, 0, 0); __builtin_amdgcn_s_setprio(0); } while (0)
; #define PG8_WAIT_V(n) asm volatile("s_waitcnt vmcnt(" #n ")" ::: "memory")
; #define PG8_WAIT_L(n) asm volatile("s_waitcnt lgkmcnt(" #n ")" ::: "memory")
; #define PG8_BAR __builtin_amdgcn_s_barrier()
; #define PG8_SCHED __builtin_amdgcn_sched_barrier(0)
; template <class Epi, class Sched, bool ALIGN_EPI = false, bool SP2 = false>
; __device__ __forceinline__ void gemm_phase(PG8_LAS unsigned char* lds, const Gemm g, const Sched& S, const Epi& E) {
;     ...
;             PG8_WAIT_V(8); PG8_WAIT_L(0); PG8_BAR; PG8_MMA(1, 0, At, B0); PG8_MMA(1, 1, At, B1); PG8_BAR; PG8_SCHED;
;             PG8_LDB(B0, 1, 0); PG8_LDB(B1, 1, 1); PG8_SCHED; PG8_LDA(At, 1, 0); PG8_STAGE(PG8_SA(0, 1), a2 + hstep, voffA);
;             PG8_WAIT_V(8); PG8_WAIT_L(0); PG8_BAR; PG8_MMA(0, 0, At, B0); PG8_MMA(0, 1, At, B1); PG8_BAR; PG8_SCHED;
	v_mfma_f32_16x16x32_bf16 v[70:73], v[58:61], v[186:189], v[70:73]
	v_mfma_f32_16x16x32_bf16 v[66:69], v[74:77], v[186:189], v[66:69]
	v_mfma_f32_16x16x32_bf16 v[46:49], v[58:61], v[200:203], v[46:49]
	v_mfma_f32_16x16x32_bf16 v[42:45], v[74:77], v[200:203], v[42:45]
	v_mfma_f32_16x16x32_bf16 v[30:33], v[58:61], v[208:211], v[30:33]
	v_mfma_f32_16x16x32_bf16 v[26:29], v[74:77], v[208:211], v[26:29]
	v_mfma_f32_16x16x32_bf16 v[14:17], v[58:61], v[216:219], v[14:17]
	v_mfma_f32_16x16x32_bf16 v[10:13], v[74:77], v[216:219], v[10:13]
	v_mfma_f32_16x16x32_bf16 v[70:73], v[62:65], v[190:193], v[70:73]
	v_mfma_f32_16x16x32_bf16 v[66:69], v[78:81], v[190:193], v[66:69]
	v_mfma_f32_16x16x32_bf16 v[46:49], v[62:65], v[204:207], v[46:49]
	v_mfma_f32_16x16x32_bf16 v[42:45], v[78:81], v[204:207], v[42:45]
	v_mfma_f32_16x16x32_bf16 v[30:33], v[62:65], v[212:215], v[30:33]
	v_mfma_f32_16x16x32_bf16 v[26:29], v[78:81], v[212:215], v[26:29]
	v_mfma_f32_16x16x32_bf16 v[14:17], v[62:65], v[220:223], v[14:17]
	v_mfma_f32_16x16x32_bf16 v[10:13], v[78:81], v[220:223], v[10:13]
	s_setprio 0
	s_setprio 1
	v_mfma_f32_16x16x32_bf16 v[54:57], v[82:85], v[186:189], v[54:57]
	v_mfma_f32_16x16x32_bf16 v[50:53], v[90:93], v[186:189], v[50:53]
	v_mfma_f32_16x16x32_bf16 v[38:41], v[82:85], v[200:203], v[38:41]
	v_mfma_f32_16x16x32_bf16 v[34:37], v[90:93], v[200:203], v[34:37]
	v_mfma_f32_16x16x32_bf16 v[22:25], v[82:85], v[208:211], v[22:25]
	v_mfma_f32_16x16x32_bf16 v[18:21], v[90:93], v[208:211], v[18:21]
	v_mfma_f32_16x16x32_bf16 v[6:9], v[82:85], v[216:219], v[6:9]
	v_mfma_f32_16x16x32_bf16 v[2:5], v[90:93], v[216:219], v[2:5]
	v_mfma_f32_16x16x32_bf16 v[54:57], v[86:89], v[190:193], v[54:57]
	v_mfma_f32_16x16x32_bf16 v[50:53], v[94:97], v[190:193], v[50:53]
	v_mfma_f32_16x16x32_bf16 v[38:41], v[86:89], v[204:207], v[38:41]
	v_mfma_f32_16x16x32_bf16 v[34:37], v[94:97], v[204:207], v[34:37]
	v_mfma_f32_16x16x32_bf16 v[22:25], v[86:89], v[212:215], v[22:25]
	v_mfma_f32_16x16x32_bf16 v[18:21], v[94:97], v[212:215], v[18:21]
	v_mfma_f32_16x16x32_bf16 v[6:9], v[86:89], v[220:223], v[6:9]
	v_mfma_f32_16x16x32_bf16 v[2:5], v[94:97], v[220:223], v[2:5]
	s_barrier
	s_setprio 0
	s_add_i32 s24, 16, 0x18000
	s_add_i32 s25, 16, 0x1c000
	v_add_u32_e32 v78, s24, v197
	v_add_u32_e32 v94, s25, v197
	ds_read_b128 v[58:61], v78
	ds_read_b128 v[62:65], v78 offset:1024
	ds_read_b128 v[74:77], v78 offset:2048
	ds_read_b128 v[78:81], v78 offset:3072
	ds_read_b128 v[82:85], v94
	ds_read_b128 v[86:89], v94 offset:1024
	ds_read_b128 v[90:93], v94 offset:2048
	ds_read_b128 v[94:97], v94 offset:3072
	s_add_u32 s10, s68, 0xb0000
	s_addc_u32 s11, s69, 0
	s_mov_b32 m0, s3
	v_lshl_add_u64 v[240:241], s[10:11], 0, v[176:177]
	ds_read_b128 v[186:189], v199 offset:32768
	ds_read_b128 v[190:193], v199 offset:33792
	ds_read_b128 v[200:203], v199 offset:34816
	ds_read_b128 v[204:207], v199 offset:35840
	ds_read_b128 v[208:211], v199 offset:36864
	ds_read_b128 v[212:215], v199 offset:37888
	ds_read_b128 v[216:219], v199 offset:38912
	ds_read_b128 v[220:223], v199 offset:39936
	global_load_lds_dwordx4 v[240:241], off
	v_lshl_add_u64 v[240:241], s[10:11], 0, v[178:179]
	s_mov_b32 m0, s96
	s_nop 0
	global_load_lds_dwordx4 v[240:241], off
	s_waitcnt vmcnt(8)
	s_waitcnt lgkmcnt(0)
	s_setprio 1
	s_barrier
	v_mfma_f32_16x16x32_bf16 v[158:161], v[58:61], v[186:189], v[158:161]
	v_mfma_f32_16x16x32_bf16 v[154:157], v[74:77], v[186:189], v[154:157]
	v_mfma_f32_16x16x32_bf16 v[142:145], v[58:61], v[200:203], v[142:145]
	v_mfma_f32_16x16x32_bf16 v[138:141], v[74:77], v[200:203], v[138:141]
	v_mfma_f32_16x16x32_bf16 v[126:129], v[58:61], v[208:211], v[126:129]
	v_mfma_f32_16x16x32_bf16 v[122:125], v[74:77], v[208:211], v[122:125]
	v_mfma_f32_16x16x32_bf16 v[110:113], v[58:61], v[216:219], v[110:113]
	v_mfma_f32_16x16x32_bf16 v[106:109], v[74:77], v[216:219], v[106:109]
	v_mfma_f32_16x16x32_bf16 v[158:161], v[62:65], v[190:193], v[158:161]
	v_mfma_f32_16x16x32_bf16 v[154:157], v[78:81], v[190:193], v[154:157]
	v_mfma_f32_16x16x32_bf16 v[142:145], v[62:65], v[204:207], v[142:145]
	v_mfma_f32_16x16x32_bf16 v[138:141], v[78:81], v[204:207], v[138:141]
	v_mfma_f32_16x16x32_bf16 v[126:129], v[62:65], v[212:215], v[126:129]
	v_mfma_f32_16x16x32_bf16 v[122:125], v[78:81], v[212:215], v[122:125]
	v_mfma_f32_16x16x32_bf16 v[110:113], v[62:65], v[220:223], v[110:113]
	v_mfma_f32_16x16x32_bf16 v[106:109], v[78:81], v[220:223], v[106:109]
	s_setprio 0
	s_setprio 1
	v_mfma_f32_16x16x32_bf16 v[150:153], v[82:85], v[186:189], v[150:153]
	v_mfma_f32_16x16x32_bf16 v[146:149], v[90:93], v[186:189], v[146:149]
	v_mfma_f32_16x16x32_bf16 v[134:137], v[82:85], v[200:203], v[134:137]
	v_mfma_f32_16x16x32_bf16 v[130:133], v[90:93], v[200:203], v[130:133]
	v_mfma_f32_16x16x32_bf16 v[118:121], v[82:85], v[208:211], v[118:121]
	v_mfma_f32_16x16x32_bf16 v[114:117], v[90:93], v[208:211], v[114:117]
	v_mfma_f32_16x16x32_bf16 v[102:105], v[82:85], v[216:219], v[102:105]
	v_mfma_f32_16x16x32_bf16 v[98:101], v[90:93], v[216:219], v[98:101]
	v_mfma_f32_16x16x32_bf16 v[150:153], v[86:89], v[190:193], v[150:153]
	v_mfma_f32_16x16x32_bf16 v[146:149], v[94:97], v[190:193], v[146:149]
	v_mfma_f32_16x16x32_bf16 v[134:137], v[86:89], v[204:207], v[134:137]
	v_mfma_f32_16x16x32_bf16 v[130:133], v[94:97], v[204:207], v[130:133]
	v_mfma_f32_16x16x32_bf16 v[118:121], v[86:89], v[212:215], v[118:121]
	v_mfma_f32_16x16x32_bf16 v[114:117], v[94:97], v[212:215], v[114:117]
	v_mfma_f32_16x16x32_bf16 v[102:105], v[86:89], v[220:223], v[102:105]
	v_mfma_f32_16x16x32_bf16 v[98:101], v[94:97], v[220:223], v[98:101]
	s_barrier
; #define PG8_STAGE(bufoff, gbase, voff) do { _Pragma("unroll") for (int _i = 0; _i < 2; ++_i) \
;         __builtin_amdgcn_global_load_lds((const unsigned*)((const char*)(gbase) + (voff)[_i]), (PG8_LAS unsigned*)(lds + (bufoff) + ldsw + _i * 8192), 16, 0, 0); } while (0)
; #define PG8_LDA(dst, b, h) do { _Pragma("unroll") for (int m = 0; m < 4; ++m) _Pragma("unroll") for (int k = 0; k < 2; ++k) dst[m][k] = *(const PG8_LAS bf16x8*)(lds + PG8_SA(b, h) + aoff + m * 2048 + k * 1024); } while (0)
; #define PG8_MMA(ai, bj, At, Bt) do { __builtin_amdgcn_s_setprio(1); _Pragma("unroll") for (int m = 0; m < 4; ++m) _Pragma("unroll") for (int n = 0; n < 2; ++n) _Pragma("unroll") for (int k = 0; k < 2; ++k) \
;         acc[ai][bj][m][n] = __builtin_amdgcn_mfma_f32_16x16x32_bf16(Bt[n][k], At[m][k], acc[ai][bj][m][n], 0, 0, 0); __builtin_amdgcn_s_setprio(0); } while (0)
; #define PG8_WAIT_V(n) asm volatile("s_waitcnt vmcnt(" #n ")" ::: "memory")
; #define PG8_WAIT_L(n) asm volatile("s_waitcnt lgkmcnt(" #n ")" ::: "memory")
; #define PG8_BAR __builtin_amdgcn_s_barrier()
; #define PG8_SCHED __builtin_amdgcn_sched_barrier(0)
; template <class Epi, class Sched, bool ALIGN_EPI = false, bool SP2 = false>
; __device__ __forceinline__ void gemm_phase(PG8_LAS unsigned char* lds, const Gemm g, const Sched& S, const Epi& E) {
;     ...
;             PG8_LDA(At, 1, 1); PG8_STAGE(PG8_SB(1, 0), b3, voffB); PG8_STAGE(PG8_SB(1, 1), b3 + hstep, voffB); PG8_STAGE(PG8_SA(1, 0), a3, voffA);
;             PG8_WAIT_V(8); PG8_WAIT_L(0); PG8_BAR; PG8_MMA(1, 0, At, B0); PG8_MMA(1, 1, At, B1); PG8_BAR; PG8_SCHED;
;     ...
;         if constexpr (ALIGN_EPI) { if (wr == 0) PG8_BAR; }
	s_setprio 0
	s_add_i32 s10, s24, s94
	v_lshl_add_u64 v[194:195], v[194:195], 0, s[28:29]
	s_mov_b32 m0, s10
	ds_read_b128 v[186:189], v199 offset:49152
	ds_read_b128 v[190:193], v199 offset:50176
	ds_read_b128 v[200:203], v199 offset:51200
	ds_read_b128 v[204:207], v199 offset:52224
	ds_read_b128 v[208:211], v199 offset:53248
	ds_read_b128 v[212:215], v199 offset:54272
	ds_read_b128 v[216:219], v199 offset:55296
	ds_read_b128 v[220:223], v199 offset:56320
	global_load_lds_dwordx4 v[194:195], off
	s_add_i32 m0, s10, 0x2000
	s_add_u32 s10, s44, 0xb0080
	v_lshl_add_u64 v[194:195], v[224:225], 0, s[28:29]
	s_addc_u32 s11, s45, 0
	s_add_i32 s24, s25, s94
	global_load_lds_dwordx4 v[194:195], off
	v_lshl_add_u64 v[194:195], s[10:11], 0, v[0:1]
	s_mov_b32 m0, s24
	s_nop 0
	global_load_lds_dwordx4 v[194:195], off
	v_lshl_add_u64 v[194:195], s[10:11], 0, v[180:181]
	s_add_i32 m0, s24, 0x2000
	s_nop 0
	global_load_lds_dwordx4 v[194:195], off
	v_lshl_add_u64 v[194:195], v[226:227], 0, s[28:29]
	s_mov_b32 m0, s57
	s_nop 0
	global_load_lds_dwordx4 v[194:195], off
	v_lshl_add_u64 v[194:195], v[238:239], 0, s[28:29]
	s_mov_b32 m0, s78
	s_nop 0
	global_load_lds_dwordx4 v[194:195], off
	s_waitcnt vmcnt(8)
	s_waitcnt lgkmcnt(0)
	s_setprio 1
	s_barrier
	v_mfma_f32_16x16x32_bf16 v[70:73], v[58:61], v[186:189], v[70:73]
	v_mfma_f32_16x16x32_bf16 v[66:69], v[74:77], v[186:189], v[66:69]
	v_mfma_f32_16x16x32_bf16 v[46:49], v[58:61], v[200:203], v[46:49]
	v_mfma_f32_16x16x32_bf16 v[42:45], v[74:77], v[200:203], v[42:45]
	v_mfma_f32_16x16x32_bf16 v[30:33], v[58:61], v[208:211], v[30:33]
	v_mfma_f32_16x16x32_bf16 v[26:29], v[74:77], v[208:211], v[26:29]
	v_mfma_f32_16x16x32_bf16 v[14:17], v[58:61], v[216:219], v[14:17]
	v_mfma_f32_16x16x32_bf16 v[10:13], v[74:77], v[216:219], v[10:13]
	v_mfma_f32_16x16x32_bf16 v[70:73], v[62:65], v[190:193], v[70:73]
	v_mfma_f32_16x16x32_bf16 v[66:69], v[78:81], v[190:193], v[66:69]
	v_mfma_f32_16x16x32_bf16 v[46:49], v[62:65], v[204:207], v[46:49]
	v_mfma_f32_16x16x32_bf16 v[42:45], v[78:81], v[204:207], v[42:45]
	v_mfma_f32_16x16x32_bf16 v[30:33], v[62:65], v[212:215], v[30:33]
	v_mfma_f32_16x16x32_bf16 v[26:29], v[78:81], v[212:215], v[26:29]
	v_mfma_f32_16x16x32_bf16 v[14:17], v[62:65], v[220:223], v[14:17]
	v_mfma_f32_16x16x32_bf16 v[10:13], v[78:81], v[220:223], v[10:13]
	s_setprio 0
	s_setprio 1
	v_mfma_f32_16x16x32_bf16 v[54:57], v[82:85], v[186:189], v[54:57]
	v_mfma_f32_16x16x32_bf16 v[50:53], v[90:93], v[186:189], v[50:53]
	v_mfma_f32_16x16x32_bf16 v[38:41], v[82:85], v[200:203], v[38:41]
	v_mfma_f32_16x16x32_bf16 v[34:37], v[90:93], v[200:203], v[34:37]
	v_mfma_f32_16x16x32_bf16 v[22:25], v[82:85], v[208:211], v[22:25]
	v_mfma_f32_16x16x32_bf16 v[18:21], v[90:93], v[208:211], v[18:21]
	v_mfma_f32_16x16x32_bf16 v[6:9], v[82:85], v[216:219], v[6:9]
	v_mfma_f32_16x16x32_bf16 v[2:5], v[90:93], v[216:219], v[2:5]
	v_mfma_f32_16x16x32_bf16 v[54:57], v[86:89], v[190:193], v[54:57]
	v_mfma_f32_16x16x32_bf16 v[50:53], v[94:97], v[190:193], v[50:53]
	v_mfma_f32_16x16x32_bf16 v[38:41], v[86:89], v[204:207], v[38:41]
	v_mfma_f32_16x16x32_bf16 v[34:37], v[94:97], v[204:207], v[34:37]
	v_mfma_f32_16x16x32_bf16 v[22:25], v[86:89], v[212:215], v[22:25]
	v_mfma_f32_16x16x32_bf16 v[18:21], v[94:97], v[212:215], v[18:21]
	v_mfma_f32_16x16x32_bf16 v[6:9], v[86:89], v[220:223], v[6:9]
	v_mfma_f32_16x16x32_bf16 v[2:5], v[94:97], v[220:223], v[2:5]
	s_barrier
	s_setprio 0
	s_add_i32 s73, s73, 2
	s_add_u32 s35, s35, 0x100
	s_addc_u32 s72, s72, 0
	s_cmp_gt_u32 s73, 41
	s_mov_b64 s[24:25], s[42:43]
	s_cbranch_scc0 .LBB0_1208
	s_and_b64 vcc, exec, s[20:21]
	s_cbranch_vccz .LBB0_1211
	s_barrier

; #define PG8_STAGE(bufoff, gbase, voff) do { _Pragma("unroll") for (int _i = 0; _i < 2; ++_i) \
;         __builtin_amdgcn_global_load_lds((const unsigned*)((const char*)(gbase) + (voff)[_i]), (PG8_LAS unsigned*)(lds + (bufoff) + ldsw + _i * 8192), 16, 0, 0); } while (0)
; #define PG8_LDA(dst, b, h) do { _Pragma("unroll") for (int m = 0; m < 4; ++m) _Pragma("unroll") for (int k = 0; k < 2; ++k) dst[m][k] = *(const PG8_LAS bf16x8*)(lds + PG8_SA(b, h) + aoff + m * 2048 + k * 1024); } while (0)
; #define PG8_LDB(dst, b, h) do { _Pragma("unroll") for (int n = 0; n < 2; ++n) _Pragma("unroll") for (int k = 0; k < 2; ++k) dst[n][k] = *(const PG8_LAS bf16x8*)(lds + PG8_SB(b, h) + boff + n * 2048 + k * 1024); } while (0)
; #define PG8_MMA(ai, bj, At, Bt) do { __builtin_amdgcn_s_setprio(1); _Pragma("unroll") for (int m = 0; m < 4; ++m) _Pragma("unroll") for (int n = 0; n < 2; ++n) _Pragma("unroll") for (int k = 0; k < 2; ++k) \
;         acc[ai][bj][m][n] = __builtin_amdgcn_mfma_f32_16x16x32_bf16(Bt[n][k], At[m][k], acc[ai][bj][m][n], 0, 0, 0); __builtin_amdgcn_s_setprio(0); } while (0)
; #define PG8_WAIT_V(n) asm volatile("s_waitcnt vmcnt(" #n ")" ::: "memory")
; #define PG8_WAIT_L(n) asm volatile("s_waitcnt lgkmcnt(" #n ")" ::: "memory")
; #define PG8_BAR __builtin_amdgcn_s_barrier()
; #define PG8_SCHED __builtin_amdgcn_sched_barrier(0)
; template <class Epi, class Sched, bool ALIGN_EPI = false, bool SP2 = false>
; __device__ __forceinline__ void gemm_phase(PG8_LAS unsigned char* lds, const Gemm g, const Sched& S, const Epi& E) {
;     ...
;             PG8_LDB(B0, 0, 0); PG8_LDB(B1, 0, 1); PG8_SCHED; PG8_LDA(At, 0, 0); PG8_STAGE(PG8_SA(1, 1), a1 + hstep, voffA);
;             PG8_WAIT_V(8); PG8_WAIT_L(0); PG8_BAR; PG8_MMA(0, 0, At, B0); PG8_MMA(0, 1, At, B1); PG8_BAR; PG8_SCHED;
;             PG8_LDA(At, 0, 1); PG8_STAGE(PG8_SB(0, 0), b2, voffB); PG8_STAGE(PG8_SB(0, 1), b2 + hstep, voffB); PG8_STAGE(PG8_SA(0, 0), a2, voffA);
;             PG8_WAIT_V(8); PG8_WAIT_L(0); PG8_BAR; PG8_MMA(1, 0, At, B0); PG8_MMA(1, 1, At, B1); PG8_BAR; PG8_SCHED;
.LBB0_1275:
	s_add_u32 s10, s40, 0xfffc0080
	s_addc_u32 s11, s41, -1
	s_add_i32 s64, 16, 0x10000
	s_cmp_eq_u32 s63, 12
	s_cselect_b32 s51, s34, s11
	s_cselect_b32 s50, s35, s10
	s_cselect_b32 s49, s27, s62
	s_cselect_b32 s48, s43, s59
	s_add_i32 s65, 16, 0x14000
	v_add_u32_e32 v142, s64, v179
	v_add_u32_e32 v176, s65, v179
	ds_read_b128 v[130:133], v142
	ds_read_b128 v[134:137], v142 offset:1024
	ds_read_b128 v[138:141], v142 offset:2048
	ds_read_b128 v[142:145], v142 offset:3072
	ds_read_b128 v[158:161], v176
	ds_read_b128 v[182:185], v176 offset:1024
	ds_read_b128 v[186:189], v176 offset:2048
	ds_read_b128 v[190:193], v176 offset:3072
	v_lshl_add_u64 v[176:177], s[40:41], 0, v[156:157]
	s_add_i32 m0, s4, 0xc000
	ds_read_b128 v[194:197], v181
	ds_read_b128 v[198:201], v181 offset:1024
	ds_read_b128 v[202:205], v181 offset:2048
	ds_read_b128 v[206:209], v181 offset:3072
	ds_read_b128 v[210:213], v181 offset:4096
	ds_read_b128 v[214:217], v181 offset:5120
	ds_read_b128 v[218:221], v181 offset:6144
	ds_read_b128 v[222:225], v181 offset:7168
	global_load_lds_dwordx4 v[176:177], off
	v_lshl_add_u64 v[176:177], s[40:41], 0, v[154:155]
	s_add_i32 m0, s4, 0xe000
	s_nop 0
	global_load_lds_dwordx4 v[176:177], off
	s_waitcnt vmcnt(8)
	s_waitcnt lgkmcnt(0)
	s_setprio 1
	s_barrier
	v_mfma_f32_16x16x32_bf16 v[126:129], v[130:133], v[194:197], v[126:129]
	v_mfma_f32_16x16x32_bf16 v[122:125], v[138:141], v[194:197], v[122:125]
	v_mfma_f32_16x16x32_bf16 v[110:113], v[130:133], v[202:205], v[110:113]
	v_mfma_f32_16x16x32_bf16 v[106:109], v[138:141], v[202:205], v[106:109]
	v_mfma_f32_16x16x32_bf16 v[94:97], v[130:133], v[210:213], v[94:97]
	v_mfma_f32_16x16x32_bf16 v[90:93], v[138:141], v[210:213], v[90:93]
	v_mfma_f32_16x16x32_bf16 v[78:81], v[130:133], v[218:221], v[78:81]
	v_mfma_f32_16x16x32_bf16 v[74:77], v[138:141], v[218:221], v[74:77]
	v_mfma_f32_16x16x32_bf16 v[126:129], v[134:137], v[198:201], v[126:129]
	v_mfma_f32_16x16x32_bf16 v[122:125], v[142:145], v[198:201], v[122:125]
	v_mfma_f32_16x16x32_bf16 v[110:113], v[134:137], v[206:209], v[110:113]
	v_mfma_f32_16x16x32_bf16 v[106:109], v[142:145], v[206:209], v[106:109]
	v_mfma_f32_16x16x32_bf16 v[94:97], v[134:137], v[214:217], v[94:97]
	v_mfma_f32_16x16x32_bf16 v[90:93], v[142:145], v[214:217], v[90:93]
	v_mfma_f32_16x16x32_bf16 v[78:81], v[134:137], v[222:225], v[78:81]
	v_mfma_f32_16x16x32_bf16 v[74:77], v[142:145], v[222:225], v[74:77]
	s_setprio 0
	s_setprio 1
	v_mfma_f32_16x16x32_bf16 v[118:121], v[158:161], v[194:197], v[118:121]
	v_mfma_f32_16x16x32_bf16 v[114:117], v[186:189], v[194:197], v[114:117]
	v_mfma_f32_16x16x32_bf16 v[102:105], v[158:161], v[202:205], v[102:105]
	v_mfma_f32_16x16x32_bf16 v[98:101], v[186:189], v[202:205], v[98:101]
	v_mfma_f32_16x16x32_bf16 v[86:89], v[158:161], v[210:213], v[86:89]
	v_mfma_f32_16x16x32_bf16 v[82:85], v[186:189], v[210:213], v[82:85]
	v_mfma_f32_16x16x32_bf16 v[70:73], v[158:161], v[218:221], v[70:73]
	v_mfma_f32_16x16x32_bf16 v[66:69], v[186:189], v[218:221], v[66:69]
	v_mfma_f32_16x16x32_bf16 v[118:121], v[182:185], v[198:201], v[118:121]
	v_mfma_f32_16x16x32_bf16 v[114:117], v[190:193], v[198:201], v[114:117]
	v_mfma_f32_16x16x32_bf16 v[102:105], v[182:185], v[206:209], v[102:105]
	v_mfma_f32_16x16x32_bf16 v[98:101], v[190:193], v[206:209], v[98:101]
	v_mfma_f32_16x16x32_bf16 v[86:89], v[182:185], v[214:217], v[86:89]
	v_mfma_f32_16x16x32_bf16 v[82:85], v[190:193], v[214:217], v[82:85]
	v_mfma_f32_16x16x32_bf16 v[70:73], v[182:185], v[222:225], v[70:73]
	v_mfma_f32_16x16x32_bf16 v[66:69], v[190:193], v[222:225], v[66:69]
	s_barrier
	s_setprio 0
	s_add_i32 s10, s64, s3
	v_lshl_add_u64 v[176:177], s[48:49], 0, v[0:1]
	s_mov_b32 m0, s10
	ds_read_b128 v[194:197], v181 offset:16384
	ds_read_b128 v[198:201], v181 offset:17408
	ds_read_b128 v[202:205], v181 offset:18432
	ds_read_b128 v[206:209], v181 offset:19456
	ds_read_b128 v[210:213], v181 offset:20480
	ds_read_b128 v[214:217], v181 offset:21504
	ds_read_b128 v[218:221], v181 offset:22528
	ds_read_b128 v[222:225], v181 offset:23552
	global_load_lds_dwordx4 v[176:177], off
	s_add_i32 m0, s10, 0x2000
	s_add_u32 s10, s48, 0x40000
	v_lshl_add_u64 v[226:227], s[48:49], 0, v[146:147]
	s_addc_u32 s11, s49, 0
	s_add_i32 s64, s65, s3
	global_load_lds_dwordx4 v[226:227], off
	v_lshl_add_u64 v[238:239], s[10:11], 0, v[0:1]
	s_mov_b32 m0, s64
	v_lshl_add_u64 v[240:241], s[50:51], 0, v[148:149]
	global_load_lds_dwordx4 v[238:239], off
	v_lshl_add_u64 v[238:239], s[10:11], 0, v[146:147]
	s_add_i32 m0, s64, 0x2000
	s_nop 0
	global_load_lds_dwordx4 v[238:239], off
	v_lshl_add_u64 v[238:239], s[50:51], 0, v[150:151]
	s_mov_b32 m0, s4
	s_nop 0
	global_load_lds_dwordx4 v[238:239], off
	s_mov_b32 m0, s5
	s_nop 0
	global_load_lds_dwordx4 v[240:241], off
	s_waitcnt vmcnt(8)
	s_waitcnt lgkmcnt(0)
	s_setprio 1
	s_barrier
; #define PG8_STAGE(bufoff, gbase, voff) do { _Pragma("unroll") for (int _i = 0; _i < 2; ++_i) \
;         __builtin_amdgcn_global_load_lds((const unsigned*)((const char*)(gbase) + (voff)[_i]), (PG8_LAS unsigned*)(lds + (bufoff) + ldsw + _i * 8192), 16, 0, 0); } while (0)
; #define PG8_LDA(dst, b, h) do { _Pragma("unroll") for (int m = 0; m < 4; ++m) _Pragma("unroll") for (int k = 0; k < 2; ++k) dst[m][k] = *(const PG8_LAS bf16x8*)(lds + PG8_SA(b, h) + aoff + m * 2048 + k * 1024); } while (0)
; #define PG8_LDB(dst, b, h) do { _Pragma("unroll") for (int n = 0; n < 2; ++n) _Pragma("unroll") for (int k = 0; k < 2; ++k) dst[n][k] = *(const PG8_LAS bf16x8*)(lds + PG8_SB(b, h) + boff + n * 2048 + k * 1024); } while (0)
; #define PG8_MMA(ai, bj, At, Bt) do { __builtin_amdgcn_s_setprio(1); _Pragma("unroll") for (int m = 0; m < 4; ++m) _Pragma("unroll") for (int n = 0; n < 2; ++n) _Pragma("unroll") for (int k = 0; k < 2; ++k) \
;         acc[ai][bj][m][n] = __builtin_amdgcn_mfma_f32_16x16x32_bf16(Bt[n][k], At[m][k], acc[ai][bj][m][n], 0, 0, 0); __builtin_amdgcn_s_setprio(0); } while (0)
; #define PG8_WAIT_V(n) asm volatile("s_waitcnt vmcnt(" #n ")" ::: "memory")
; #define PG8_WAIT_L(n) asm volatile("s_waitcnt lgkmcnt(" #n ")" ::: "memory")
; #define PG8_BAR __builtin_amdgcn_s_barrier()
; #define PG8_SCHED __builtin_amdgcn_sched_barrier(0)
; template <class Epi, class Sched, bool ALIGN_EPI = false, bool SP2 = false>
; __device__ __forceinline__ void gemm_phase(PG8_LAS unsigned char* lds, const Gemm g, const Sched& S, const Epi& E) {
;     ...
;             PG8_WAIT_V(8); PG8_WAIT_L(0); PG8_BAR; PG8_MMA(1, 0, At, B0); PG8_MMA(1, 1, At, B1); PG8_BAR; PG8_SCHED;
;             PG8_LDB(B0, 1, 0); PG8_LDB(B1, 1, 1); PG8_SCHED; PG8_LDA(At, 1, 0); PG8_STAGE(PG8_SA(0, 1), a2 + hstep, voffA);
;             PG8_WAIT_V(8); PG8_WAIT_L(0); PG8_BAR; PG8_MMA(0, 0, At, B0); PG8_MMA(0, 1, At, B1); PG8_BAR; PG8_SCHED;
	v_mfma_f32_16x16x32_bf16 v[62:65], v[130:133], v[194:197], v[62:65]
	v_mfma_f32_16x16x32_bf16 v[58:61], v[138:141], v[194:197], v[58:61]
	v_mfma_f32_16x16x32_bf16 v[46:49], v[130:133], v[202:205], v[46:49]
	v_mfma_f32_16x16x32_bf16 v[42:45], v[138:141], v[202:205], v[42:45]
	v_mfma_f32_16x16x32_bf16 v[30:33], v[130:133], v[210:213], v[30:33]
	v_mfma_f32_16x16x32_bf16 v[26:29], v[138:141], v[210:213], v[26:29]
	v_mfma_f32_16x16x32_bf16 v[14:17], v[130:133], v[218:221], v[14:17]
	v_mfma_f32_16x16x32_bf16 v[10:13], v[138:141], v[218:221], v[10:13]
	v_mfma_f32_16x16x32_bf16 v[62:65], v[134:137], v[198:201], v[62:65]
	v_mfma_f32_16x16x32_bf16 v[58:61], v[142:145], v[198:201], v[58:61]
	v_mfma_f32_16x16x32_bf16 v[46:49], v[134:137], v[206:209], v[46:49]
	v_mfma_f32_16x16x32_bf16 v[42:45], v[142:145], v[206:209], v[42:45]
	v_mfma_f32_16x16x32_bf16 v[30:33], v[134:137], v[214:217], v[30:33]
	v_mfma_f32_16x16x32_bf16 v[26:29], v[142:145], v[214:217], v[26:29]
	v_mfma_f32_16x16x32_bf16 v[14:17], v[134:137], v[222:225], v[14:17]
	v_mfma_f32_16x16x32_bf16 v[10:13], v[142:145], v[222:225], v[10:13]
	s_setprio 0
	s_setprio 1
	v_mfma_f32_16x16x32_bf16 v[54:57], v[158:161], v[194:197], v[54:57]
	v_mfma_f32_16x16x32_bf16 v[50:53], v[186:189], v[194:197], v[50:53]
	v_mfma_f32_16x16x32_bf16 v[38:41], v[158:161], v[202:205], v[38:41]
	v_mfma_f32_16x16x32_bf16 v[34:37], v[186:189], v[202:205], v[34:37]
	v_mfma_f32_16x16x32_bf16 v[22:25], v[158:161], v[210:213], v[22:25]
	v_mfma_f32_16x16x32_bf16 v[18:21], v[186:189], v[210:213], v[18:21]
	v_mfma_f32_16x16x32_bf16 v[6:9], v[158:161], v[218:221], v[6:9]
	v_mfma_f32_16x16x32_bf16 v[2:5], v[186:189], v[218:221], v[2:5]
	v_mfma_f32_16x16x32_bf16 v[54:57], v[182:185], v[198:201], v[54:57]
	v_mfma_f32_16x16x32_bf16 v[50:53], v[190:193], v[198:201], v[50:53]
	v_mfma_f32_16x16x32_bf16 v[38:41], v[182:185], v[206:209], v[38:41]
	v_mfma_f32_16x16x32_bf16 v[34:37], v[190:193], v[206:209], v[34:37]
	v_mfma_f32_16x16x32_bf16 v[22:25], v[182:185], v[214:217], v[22:25]
	v_mfma_f32_16x16x32_bf16 v[18:21], v[190:193], v[214:217], v[18:21]
	v_mfma_f32_16x16x32_bf16 v[6:9], v[182:185], v[222:225], v[6:9]
	v_mfma_f32_16x16x32_bf16 v[2:5], v[190:193], v[222:225], v[2:5]
	s_barrier
	s_setprio 0
	s_add_i32 s64, 16, 0x18000
	s_add_i32 s65, 16, 0x1c000
	v_add_u32_e32 v142, s64, v179
	v_add_u32_e32 v190, s65, v179
	ds_read_b128 v[130:133], v142
	ds_read_b128 v[134:137], v142 offset:1024
	ds_read_b128 v[138:141], v142 offset:2048
	ds_read_b128 v[142:145], v142 offset:3072
	ds_read_b128 v[158:161], v190
	ds_read_b128 v[182:185], v190 offset:1024
	ds_read_b128 v[186:189], v190 offset:2048
	ds_read_b128 v[190:193], v190 offset:3072
	s_add_u32 s10, s50, 0x40000
	s_addc_u32 s11, s51, 0
	s_mov_b32 m0, s6
	v_lshl_add_u64 v[242:243], s[10:11], 0, v[150:151]
	ds_read_b128 v[194:197], v181 offset:32768
	ds_read_b128 v[198:201], v181 offset:33792
	ds_read_b128 v[202:205], v181 offset:34816
	ds_read_b128 v[206:209], v181 offset:35840
	ds_read_b128 v[210:213], v181 offset:36864
	ds_read_b128 v[214:217], v181 offset:37888
	ds_read_b128 v[218:221], v181 offset:38912
	ds_read_b128 v[222:225], v181 offset:39936
	global_load_lds_dwordx4 v[242:243], off
	v_lshl_add_u64 v[242:243], s[10:11], 0, v[148:149]
	s_mov_b32 m0, s7
	s_nop 0
	global_load_lds_dwordx4 v[242:243], off
	s_waitcnt vmcnt(8)
	s_waitcnt lgkmcnt(0)
	s_setprio 1
	s_barrier
	v_mfma_f32_16x16x32_bf16 v[126:129], v[130:133], v[194:197], v[126:129]
	v_mfma_f32_16x16x32_bf16 v[122:125], v[138:141], v[194:197], v[122:125]
	v_mfma_f32_16x16x32_bf16 v[110:113], v[130:133], v[202:205], v[110:113]
	v_mfma_f32_16x16x32_bf16 v[106:109], v[138:141], v[202:205], v[106:109]
	v_mfma_f32_16x16x32_bf16 v[94:97], v[130:133], v[210:213], v[94:97]
	v_mfma_f32_16x16x32_bf16 v[90:93], v[138:141], v[210:213], v[90:93]
	v_mfma_f32_16x16x32_bf16 v[78:81], v[130:133], v[218:221], v[78:81]
	v_mfma_f32_16x16x32_bf16 v[74:77], v[138:141], v[218:221], v[74:77]
	v_mfma_f32_16x16x32_bf16 v[126:129], v[134:137], v[198:201], v[126:129]
	v_mfma_f32_16x16x32_bf16 v[122:125], v[142:145], v[198:201], v[122:125]
	v_mfma_f32_16x16x32_bf16 v[110:113], v[134:137], v[206:209], v[110:113]
	v_mfma_f32_16x16x32_bf16 v[106:109], v[142:145], v[206:209], v[106:109]
	v_mfma_f32_16x16x32_bf16 v[94:97], v[134:137], v[214:217], v[94:97]
	v_mfma_f32_16x16x32_bf16 v[90:93], v[142:145], v[214:217], v[90:93]
	v_mfma_f32_16x16x32_bf16 v[78:81], v[134:137], v[222:225], v[78:81]
	v_mfma_f32_16x16x32_bf16 v[74:77], v[142:145], v[222:225], v[74:77]
	s_setprio 0
	s_setprio 1
	v_mfma_f32_16x16x32_bf16 v[118:121], v[158:161], v[194:197], v[118:121]
	v_mfma_f32_16x16x32_bf16 v[114:117], v[186:189], v[194:197], v[114:117]
	v_mfma_f32_16x16x32_bf16 v[102:105], v[158:161], v[202:205], v[102:105]
	v_mfma_f32_16x16x32_bf16 v[98:101], v[186:189], v[202:205], v[98:101]
	v_mfma_f32_16x16x32_bf16 v[86:89], v[158:161], v[210:213], v[86:89]
	v_mfma_f32_16x16x32_bf16 v[82:85], v[186:189], v[210:213], v[82:85]
	v_mfma_f32_16x16x32_bf16 v[70:73], v[158:161], v[218:221], v[70:73]
	v_mfma_f32_16x16x32_bf16 v[66:69], v[186:189], v[218:221], v[66:69]
	v_mfma_f32_16x16x32_bf16 v[118:121], v[182:185], v[198:201], v[118:121]
	v_mfma_f32_16x16x32_bf16 v[114:117], v[190:193], v[198:201], v[114:117]
	v_mfma_f32_16x16x32_bf16 v[102:105], v[182:185], v[206:209], v[102:105]
	v_mfma_f32_16x16x32_bf16 v[98:101], v[190:193], v[206:209], v[98:101]
	v_mfma_f32_16x16x32_bf16 v[86:89], v[182:185], v[214:217], v[86:89]
	v_mfma_f32_16x16x32_bf16 v[82:85], v[190:193], v[214:217], v[82:85]
	v_mfma_f32_16x16x32_bf16 v[70:73], v[182:185], v[222:225], v[70:73]
	v_mfma_f32_16x16x32_bf16 v[66:69], v[190:193], v[222:225], v[66:69]
	s_barrier
; #define PG8_STAGE(bufoff, gbase, voff) do { _Pragma("unroll") for (int _i = 0; _i < 2; ++_i) \
;         __builtin_amdgcn_global_load_lds((const unsigned*)((const char*)(gbase) + (voff)[_i]), (PG8_LAS unsigned*)(lds + (bufoff) + ldsw + _i * 8192), 16, 0, 0); } while (0)
; #define PG8_LDA(dst, b, h) do { _Pragma("unroll") for (int m = 0; m < 4; ++m) _Pragma("unroll") for (int k = 0; k < 2; ++k) dst[m][k] = *(const PG8_LAS bf16x8*)(lds + PG8_SA(b, h) + aoff + m * 2048 + k * 1024); } while (0)
; #define PG8_MMA(ai, bj, At, Bt) do { __builtin_amdgcn_s_setprio(1); _Pragma("unroll") for (int m = 0; m < 4; ++m) _Pragma("unroll") for (int n = 0; n < 2; ++n) _Pragma("unroll") for (int k = 0; k < 2; ++k) \
;         acc[ai][bj][m][n] = __builtin_amdgcn_mfma_f32_16x16x32_bf16(Bt[n][k], At[m][k], acc[ai][bj][m][n], 0, 0, 0); __builtin_amdgcn_s_setprio(0); } while (0)
; #define PG8_WAIT_V(n) asm volatile("s_waitcnt vmcnt(" #n ")" ::: "memory")
; #define PG8_WAIT_L(n) asm volatile("s_waitcnt lgkmcnt(" #n ")" ::: "memory")
; #define PG8_BAR __builtin_amdgcn_s_barrier()
; #define PG8_SCHED __builtin_amdgcn_sched_barrier(0)
; template <class Epi, class Sched, bool ALIGN_EPI = false, bool SP2 = false>
; __device__ __forceinline__ void gemm_phase(PG8_LAS unsigned char* lds, const Gemm g, const Sched& S, const Epi& E) {
;     ...
;             PG8_LDA(At, 1, 1); PG8_STAGE(PG8_SB(1, 0), b3, voffB); PG8_STAGE(PG8_SB(1, 1), b3 + hstep, voffB); PG8_STAGE(PG8_SA(1, 0), a3, voffA);
;             PG8_WAIT_V(8); PG8_WAIT_L(0); PG8_BAR; PG8_MMA(1, 0, At, B0); PG8_MMA(1, 1, At, B1); PG8_BAR; PG8_SCHED;
;     ...
;         if constexpr (ALIGN_EPI) { if (wr == 0) PG8_BAR; }
	s_setprio 0
	s_add_i32 s10, s64, s3
	v_lshl_add_u64 v[176:177], v[176:177], 0, s[28:29]
	s_mov_b32 m0, s10
	ds_read_b128 v[194:197], v181 offset:49152
	ds_read_b128 v[198:201], v181 offset:50176
	ds_read_b128 v[202:205], v181 offset:51200
	ds_read_b128 v[206:209], v181 offset:52224
	ds_read_b128 v[210:213], v181 offset:53248
	ds_read_b128 v[214:217], v181 offset:54272
	ds_read_b128 v[218:221], v181 offset:55296
	ds_read_b128 v[222:225], v181 offset:56320
	global_load_lds_dwordx4 v[176:177], off
	s_add_i32 m0, s10, 0x2000
	s_add_u32 s10, s48, 0x40080
	v_lshl_add_u64 v[176:177], v[226:227], 0, s[28:29]
	s_addc_u32 s11, s49, 0
	s_add_i32 s48, s65, s3
	global_load_lds_dwordx4 v[176:177], off
	v_lshl_add_u64 v[176:177], s[10:11], 0, v[0:1]
	s_mov_b32 m0, s48
	s_nop 0
	global_load_lds_dwordx4 v[176:177], off
	v_lshl_add_u64 v[176:177], s[10:11], 0, v[146:147]
	s_add_i32 m0, s48, 0x2000
	s_nop 0
	global_load_lds_dwordx4 v[176:177], off
	v_lshl_add_u64 v[176:177], v[238:239], 0, s[28:29]
	s_mov_b32 m0, s54
	s_nop 0
	global_load_lds_dwordx4 v[176:177], off
	v_lshl_add_u64 v[176:177], v[240:241], 0, s[28:29]
	s_mov_b32 m0, s55
	s_nop 0
	global_load_lds_dwordx4 v[176:177], off
	s_waitcnt vmcnt(8)
	s_waitcnt lgkmcnt(0)
	s_setprio 1
	s_barrier
	v_mfma_f32_16x16x32_bf16 v[62:65], v[130:133], v[194:197], v[62:65]
	v_mfma_f32_16x16x32_bf16 v[58:61], v[138:141], v[194:197], v[58:61]
	v_mfma_f32_16x16x32_bf16 v[46:49], v[130:133], v[202:205], v[46:49]
	v_mfma_f32_16x16x32_bf16 v[42:45], v[138:141], v[202:205], v[42:45]
	v_mfma_f32_16x16x32_bf16 v[30:33], v[130:133], v[210:213], v[30:33]
	v_mfma_f32_16x16x32_bf16 v[26:29], v[138:141], v[210:213], v[26:29]
	v_mfma_f32_16x16x32_bf16 v[14:17], v[130:133], v[218:221], v[14:17]
	v_mfma_f32_16x16x32_bf16 v[10:13], v[138:141], v[218:221], v[10:13]
	v_mfma_f32_16x16x32_bf16 v[62:65], v[134:137], v[198:201], v[62:65]
	v_mfma_f32_16x16x32_bf16 v[58:61], v[142:145], v[198:201], v[58:61]
	v_mfma_f32_16x16x32_bf16 v[46:49], v[134:137], v[206:209], v[46:49]
	v_mfma_f32_16x16x32_bf16 v[42:45], v[142:145], v[206:209], v[42:45]
	v_mfma_f32_16x16x32_bf16 v[30:33], v[134:137], v[214:217], v[30:33]
	v_mfma_f32_16x16x32_bf16 v[26:29], v[142:145], v[214:217], v[26:29]
	v_mfma_f32_16x16x32_bf16 v[14:17], v[134:137], v[222:225], v[14:17]
	v_mfma_f32_16x16x32_bf16 v[10:13], v[142:145], v[222:225], v[10:13]
	s_setprio 0
	s_setprio 1
	v_mfma_f32_16x16x32_bf16 v[54:57], v[158:161], v[194:197], v[54:57]
	v_mfma_f32_16x16x32_bf16 v[50:53], v[186:189], v[194:197], v[50:53]
	v_mfma_f32_16x16x32_bf16 v[38:41], v[158:161], v[202:205], v[38:41]
	v_mfma_f32_16x16x32_bf16 v[34:37], v[186:189], v[202:205], v[34:37]
	v_mfma_f32_16x16x32_bf16 v[22:25], v[158:161], v[210:213], v[22:25]
	v_mfma_f32_16x16x32_bf16 v[18:21], v[186:189], v[210:213], v[18:21]
	v_mfma_f32_16x16x32_bf16 v[6:9], v[158:161], v[218:221], v[6:9]
	v_mfma_f32_16x16x32_bf16 v[2:5], v[186:189], v[218:221], v[2:5]
	v_mfma_f32_16x16x32_bf16 v[54:57], v[182:185], v[198:201], v[54:57]
	v_mfma_f32_16x16x32_bf16 v[50:53], v[190:193], v[198:201], v[50:53]
	v_mfma_f32_16x16x32_bf16 v[38:41], v[182:185], v[206:209], v[38:41]
	v_mfma_f32_16x16x32_bf16 v[34:37], v[190:193], v[206:209], v[34:37]
	v_mfma_f32_16x16x32_bf16 v[22:25], v[182:185], v[214:217], v[22:25]
	v_mfma_f32_16x16x32_bf16 v[18:21], v[190:193], v[214:217], v[18:21]
	v_mfma_f32_16x16x32_bf16 v[6:9], v[182:185], v[222:225], v[6:9]
	v_mfma_f32_16x16x32_bf16 v[2:5], v[190:193], v[222:225], v[2:5]
	s_barrier
	s_setprio 0
	s_add_i32 s63, s63, 2
	s_add_u32 s59, s59, 0x100
	s_addc_u32 s62, s62, 0
	s_add_u32 s40, s40, 0x100
	s_addc_u32 s41, s41, 0
	s_cmp_gt_u32 s63, 13
	s_cbranch_scc0 .LBB0_1275
	s_and_b64 vcc, exec, s[24:25]
	s_cbranch_vccz .LBB0_1278
	s_barrier

; #define PG8_STAGE(bufoff, gbase, voff) do { _Pragma("unroll") for (int _i = 0; _i < 2; ++_i) \
;         __builtin_amdgcn_global_load_lds((const unsigned*)((const char*)(gbase) + (voff)[_i]), (PG8_LAS unsigned*)(lds + (bufoff) + ldsw + _i * 8192), 16, 0, 0); } while (0)
; #define PG8_LDA(dst, b, h) do { _Pragma("unroll") for (int m = 0; m < 4; ++m) _Pragma("unroll") for (int k = 0; k < 2; ++k) dst[m][k] = *(const PG8_LAS bf16x8*)(lds + PG8_SA(b, h) + aoff + m * 2048 + k * 1024); } while (0)
; #define PG8_LDB(dst, b, h) do { _Pragma("unroll") for (int n = 0; n < 2; ++n) _Pragma("unroll") for (int k = 0; k < 2; ++k) dst[n][k] = *(const PG8_LAS bf16x8*)(lds + PG8_SB(b, h) + boff + n * 2048 + k * 1024); } while (0)
; #define PG8_MMA(ai, bj, At, Bt) do { __builtin_amdgcn_s_setprio(1); _Pragma("unroll") for (int m = 0; m < 4; ++m) _Pragma("unroll") for (int n = 0; n < 2; ++n) _Pragma("unroll") for (int k = 0; k < 2; ++k) \
;         acc[ai][bj][m][n] = __builtin_amdgcn_mfma_f32_16x16x32_bf16(Bt[n][k], At[m][k], acc[ai][bj][m][n], 0, 0, 0); __builtin_amdgcn_s_setprio(0); } while (0)
; #define PG8_WAIT_V(n) asm volatile("s_waitcnt vmcnt(" #n ")" ::: "memory")
; #define PG8_WAIT_L(n) asm volatile("s_waitcnt lgkmcnt(" #n ")" ::: "memory")
; #define PG8_BAR __builtin_amdgcn_s_barrier()
; #define PG8_SCHED __builtin_amdgcn_sched_barrier(0)
; template <class Epi, class Sched, bool ALIGN_EPI = false, bool SP2 = false>
; __device__ __forceinline__ void gemm_phase(PG8_LAS unsigned char* lds, const Gemm g, const Sched& S, const Epi& E) {
;     ...
;             PG8_LDB(B0, 0, 0); PG8_LDB(B1, 0, 1); PG8_SCHED; PG8_LDA(At, 0, 0); PG8_STAGE(PG8_SA(1, 1), a1 + hstep, voffA);
;             PG8_WAIT_V(8); PG8_WAIT_L(0); PG8_BAR; PG8_MMA(0, 0, At, B0); PG8_MMA(0, 1, At, B1); PG8_BAR; PG8_SCHED;
;             PG8_LDA(At, 0, 1); PG8_STAGE(PG8_SB(0, 0), b2, voffB); PG8_STAGE(PG8_SB(0, 1), b2 + hstep, voffB); PG8_STAGE(PG8_SA(0, 0), a2, voffA);
;             PG8_WAIT_V(8); PG8_WAIT_L(0); PG8_BAR; PG8_MMA(1, 0, At, B0); PG8_MMA(1, 1, At, B1); PG8_BAR; PG8_SCHED;
.LBB0_1295:
	s_add_u32 s40, s42, 0x100
	s_addc_u32 s41, s43, 0
	s_add_i32 s10, 16, 0x10000
	s_cmp_eq_u32 s68, 40
	s_cselect_b32 s49, s25, s41
	s_cselect_b32 s48, s24, s40
	v_add_u32_e32 v140, s10, v143
	s_cselect_b32 s47, s27, s67
	s_cselect_b32 s46, s26, s66
	s_add_i32 s69, 16, 0x14000
	ds_read_b128 v[146:149], v140
	ds_read_b128 v[150:153], v140 offset:1024
	ds_read_b128 v[154:157], v140 offset:2048
	ds_read_b128 v[158:161], v140 offset:3072
	v_add_u32_e32 v140, s69, v143
	ds_read_b128 v[176:179], v140
	ds_read_b128 v[180:183], v140 offset:1024
	ds_read_b128 v[184:187], v140 offset:2048
	ds_read_b128 v[188:191], v140 offset:3072
	v_lshl_add_u64 v[140:141], s[42:43], 0, v[138:139]
	s_add_i32 m0, s9, 0xc000
	ds_read_b128 v[192:195], v145
	ds_read_b128 v[196:199], v145 offset:1024
	ds_read_b128 v[200:203], v145 offset:2048
	ds_read_b128 v[204:207], v145 offset:3072
	ds_read_b128 v[208:211], v145 offset:4096
	ds_read_b128 v[212:215], v145 offset:5120
	ds_read_b128 v[216:219], v145 offset:6144
	ds_read_b128 v[220:223], v145 offset:7168
	global_load_lds_dwordx4 v[140:141], off
	v_lshl_add_u64 v[140:141], s[42:43], 0, v[136:137]
	s_add_i32 m0, s9, 0xe000
	s_nop 0
	global_load_lds_dwordx4 v[140:141], off
	s_waitcnt vmcnt(8)
	s_waitcnt lgkmcnt(0)
	s_setprio 1
	s_barrier
	v_mfma_f32_16x16x32_bf16 v[126:129], v[146:149], v[192:195], v[126:129]
	v_mfma_f32_16x16x32_bf16 v[122:125], v[154:157], v[192:195], v[122:125]
	v_mfma_f32_16x16x32_bf16 v[114:117], v[146:149], v[200:203], v[114:117]
	v_mfma_f32_16x16x32_bf16 v[110:113], v[154:157], v[200:203], v[110:113]
	v_mfma_f32_16x16x32_bf16 v[98:101], v[146:149], v[208:211], v[98:101]
	v_mfma_f32_16x16x32_bf16 v[94:97], v[154:157], v[208:211], v[94:97]
	v_mfma_f32_16x16x32_bf16 v[82:85], v[146:149], v[216:219], v[82:85]
	v_mfma_f32_16x16x32_bf16 v[78:81], v[154:157], v[216:219], v[78:81]
	v_mfma_f32_16x16x32_bf16 v[126:129], v[150:153], v[196:199], v[126:129]
	v_mfma_f32_16x16x32_bf16 v[122:125], v[158:161], v[196:199], v[122:125]
	v_mfma_f32_16x16x32_bf16 v[114:117], v[150:153], v[204:207], v[114:117]
	v_mfma_f32_16x16x32_bf16 v[110:113], v[158:161], v[204:207], v[110:113]
	v_mfma_f32_16x16x32_bf16 v[98:101], v[150:153], v[212:215], v[98:101]
	v_mfma_f32_16x16x32_bf16 v[94:97], v[158:161], v[212:215], v[94:97]
	v_mfma_f32_16x16x32_bf16 v[82:85], v[150:153], v[220:223], v[82:85]
	v_mfma_f32_16x16x32_bf16 v[78:81], v[158:161], v[220:223], v[78:81]
	s_setprio 0
	s_setprio 1
	v_mfma_f32_16x16x32_bf16 v[118:121], v[176:179], v[192:195], v[118:121]
	v_mfma_f32_16x16x32_bf16 v[106:109], v[184:187], v[192:195], v[106:109]
	v_mfma_f32_16x16x32_bf16 v[102:105], v[176:179], v[200:203], v[102:105]
	v_mfma_f32_16x16x32_bf16 v[90:93], v[184:187], v[200:203], v[90:93]
	v_mfma_f32_16x16x32_bf16 v[86:89], v[176:179], v[208:211], v[86:89]
	v_mfma_f32_16x16x32_bf16 v[74:77], v[184:187], v[208:211], v[74:77]
	v_mfma_f32_16x16x32_bf16 v[70:73], v[176:179], v[216:219], v[70:73]
	v_mfma_f32_16x16x32_bf16 v[66:69], v[184:187], v[216:219], v[66:69]
	v_mfma_f32_16x16x32_bf16 v[118:121], v[180:183], v[196:199], v[118:121]
	v_mfma_f32_16x16x32_bf16 v[106:109], v[188:191], v[196:199], v[106:109]
	v_mfma_f32_16x16x32_bf16 v[102:105], v[180:183], v[204:207], v[102:105]
	v_mfma_f32_16x16x32_bf16 v[90:93], v[188:191], v[204:207], v[90:93]
	v_mfma_f32_16x16x32_bf16 v[86:89], v[180:183], v[212:215], v[86:89]
	v_mfma_f32_16x16x32_bf16 v[74:77], v[188:191], v[212:215], v[74:77]
	v_mfma_f32_16x16x32_bf16 v[70:73], v[180:183], v[220:223], v[70:73]
	v_mfma_f32_16x16x32_bf16 v[66:69], v[188:191], v[220:223], v[66:69]
	s_barrier
	s_setprio 0
	s_add_i32 s10, s10, s6
	v_lshl_add_u64 v[140:141], s[46:47], 0, v[0:1]
	s_mov_b32 m0, s10
	ds_read_b128 v[192:195], v145 offset:16384
	ds_read_b128 v[196:199], v145 offset:17408
	ds_read_b128 v[200:203], v145 offset:18432
	ds_read_b128 v[204:207], v145 offset:19456
	ds_read_b128 v[208:211], v145 offset:20480
	ds_read_b128 v[212:215], v145 offset:21504
	ds_read_b128 v[216:219], v145 offset:22528
	ds_read_b128 v[220:223], v145 offset:23552
	global_load_lds_dwordx4 v[140:141], off
	s_add_i32 m0, s10, 0x2000
	s_add_u32 s10, s46, 0xb0000
	v_lshl_add_u64 v[224:225], s[46:47], 0, v[130:131]
	s_addc_u32 s11, s47, 0
	s_add_i32 s42, s69, s6
	global_load_lds_dwordx4 v[224:225], off
	v_lshl_add_u64 v[226:227], s[10:11], 0, v[0:1]
	s_mov_b32 m0, s42
	v_lshl_add_u64 v[238:239], s[48:49], 0, v[132:133]
	global_load_lds_dwordx4 v[226:227], off
	v_lshl_add_u64 v[226:227], s[10:11], 0, v[130:131]
	s_add_i32 m0, s42, 0x2000
	s_nop 0
	global_load_lds_dwordx4 v[226:227], off
	v_lshl_add_u64 v[226:227], s[48:49], 0, v[134:135]
	s_mov_b32 m0, s9
	s_nop 0
	global_load_lds_dwordx4 v[226:227], off
	s_mov_b32 m0, s50
	s_nop 0
	global_load_lds_dwordx4 v[238:239], off
	s_waitcnt vmcnt(8)
	s_waitcnt lgkmcnt(0)
	s_setprio 1
	s_barrier
; #define PG8_STAGE(bufoff, gbase, voff) do { _Pragma("unroll") for (int _i = 0; _i < 2; ++_i) \
;         __builtin_amdgcn_global_load_lds((const unsigned*)((const char*)(gbase) + (voff)[_i]), (PG8_LAS unsigned*)(lds + (bufoff) + ldsw + _i * 8192), 16, 0, 0); } while (0)
; #define PG8_LDA(dst, b, h) do { _Pragma("unroll") for (int m = 0; m < 4; ++m) _Pragma("unroll") for (int k = 0; k < 2; ++k) dst[m][k] = *(const PG8_LAS bf16x8*)(lds + PG8_SA(b, h) + aoff + m * 2048 + k * 1024); } while (0)
; #define PG8_LDB(dst, b, h) do { _Pragma("unroll") for (int n = 0; n < 2; ++n) _Pragma("unroll") for (int k = 0; k < 2; ++k) dst[n][k] = *(const PG8_LAS bf16x8*)(lds + PG8_SB(b, h) + boff + n * 2048 + k * 1024); } while (0)
; #define PG8_MMA(ai, bj, At, Bt) do { __builtin_amdgcn_s_setprio(1); _Pragma("unroll") for (int m = 0; m < 4; ++m) _Pragma("unroll") for (int n = 0; n < 2; ++n) _Pragma("unroll") for (int k = 0; k < 2; ++k) \
;         acc[ai][bj][m][n] = __builtin_amdgcn_mfma_f32_16x16x32_bf16(Bt[n][k], At[m][k], acc[ai][bj][m][n], 0, 0, 0); __builtin_amdgcn_s_setprio(0); } while (0)
; #define PG8_WAIT_V(n) asm volatile("s_waitcnt vmcnt(" #n ")" ::: "memory")
; #define PG8_WAIT_L(n) asm volatile("s_waitcnt lgkmcnt(" #n ")" ::: "memory")
; #define PG8_BAR __builtin_amdgcn_s_barrier()
; #define PG8_SCHED __builtin_amdgcn_sched_barrier(0)
; template <class Epi, class Sched, bool ALIGN_EPI = false, bool SP2 = false>
; __device__ __forceinline__ void gemm_phase(PG8_LAS unsigned char* lds, const Gemm g, const Sched& S, const Epi& E) {
;     ...
;             PG8_WAIT_V(8); PG8_WAIT_L(0); PG8_BAR; PG8_MMA(1, 0, At, B0); PG8_MMA(1, 1, At, B1); PG8_BAR; PG8_SCHED;
;             PG8_LDB(B0, 1, 0); PG8_LDB(B1, 1, 1); PG8_SCHED; PG8_LDA(At, 1, 0); PG8_STAGE(PG8_SA(0, 1), a2 + hstep, voffA);
;             PG8_WAIT_V(8); PG8_WAIT_L(0); PG8_BAR; PG8_MMA(0, 0, At, B0); PG8_MMA(0, 1, At, B1); PG8_BAR; PG8_SCHED;
	v_mfma_f32_16x16x32_bf16 v[62:65], v[146:149], v[192:195], v[62:65]
	v_mfma_f32_16x16x32_bf16 v[58:61], v[154:157], v[192:195], v[58:61]
	v_mfma_f32_16x16x32_bf16 v[50:53], v[146:149], v[200:203], v[50:53]
	v_mfma_f32_16x16x32_bf16 v[46:49], v[154:157], v[200:203], v[46:49]
	v_mfma_f32_16x16x32_bf16 v[34:37], v[146:149], v[208:211], v[34:37]
	v_mfma_f32_16x16x32_bf16 v[30:33], v[154:157], v[208:211], v[30:33]
	v_mfma_f32_16x16x32_bf16 v[18:21], v[146:149], v[216:219], v[18:21]
	v_mfma_f32_16x16x32_bf16 v[14:17], v[154:157], v[216:219], v[14:17]
	v_mfma_f32_16x16x32_bf16 v[62:65], v[150:153], v[196:199], v[62:65]
	v_mfma_f32_16x16x32_bf16 v[58:61], v[158:161], v[196:199], v[58:61]
	v_mfma_f32_16x16x32_bf16 v[50:53], v[150:153], v[204:207], v[50:53]
	v_mfma_f32_16x16x32_bf16 v[46:49], v[158:161], v[204:207], v[46:49]
	v_mfma_f32_16x16x32_bf16 v[34:37], v[150:153], v[212:215], v[34:37]
	v_mfma_f32_16x16x32_bf16 v[30:33], v[158:161], v[212:215], v[30:33]
	v_mfma_f32_16x16x32_bf16 v[18:21], v[150:153], v[220:223], v[18:21]
	v_mfma_f32_16x16x32_bf16 v[14:17], v[158:161], v[220:223], v[14:17]
	s_setprio 0
	s_setprio 1
	v_mfma_f32_16x16x32_bf16 v[54:57], v[176:179], v[192:195], v[54:57]
	v_mfma_f32_16x16x32_bf16 v[42:45], v[184:187], v[192:195], v[42:45]
	v_mfma_f32_16x16x32_bf16 v[38:41], v[176:179], v[200:203], v[38:41]
	v_mfma_f32_16x16x32_bf16 v[26:29], v[184:187], v[200:203], v[26:29]
	v_mfma_f32_16x16x32_bf16 v[22:25], v[176:179], v[208:211], v[22:25]
	v_mfma_f32_16x16x32_bf16 v[10:13], v[184:187], v[208:211], v[10:13]
	v_mfma_f32_16x16x32_bf16 v[6:9], v[176:179], v[216:219], v[6:9]
	v_mfma_f32_16x16x32_bf16 v[2:5], v[184:187], v[216:219], v[2:5]
	v_mfma_f32_16x16x32_bf16 v[54:57], v[180:183], v[196:199], v[54:57]
	v_mfma_f32_16x16x32_bf16 v[42:45], v[188:191], v[196:199], v[42:45]
	v_mfma_f32_16x16x32_bf16 v[38:41], v[180:183], v[204:207], v[38:41]
	v_mfma_f32_16x16x32_bf16 v[26:29], v[188:191], v[204:207], v[26:29]
	v_mfma_f32_16x16x32_bf16 v[22:25], v[180:183], v[212:215], v[22:25]
	v_mfma_f32_16x16x32_bf16 v[10:13], v[188:191], v[212:215], v[10:13]
	v_mfma_f32_16x16x32_bf16 v[6:9], v[180:183], v[220:223], v[6:9]
	v_mfma_f32_16x16x32_bf16 v[2:5], v[188:191], v[220:223], v[2:5]
	s_barrier
	s_setprio 0
	s_add_i32 s42, 16, 0x18000
	s_add_i32 s43, 16, 0x1c000
	v_add_u32_e32 v158, s42, v143
	v_add_u32_e32 v188, s43, v143
	ds_read_b128 v[146:149], v158
	ds_read_b128 v[150:153], v158 offset:1024
	ds_read_b128 v[154:157], v158 offset:2048
	ds_read_b128 v[158:161], v158 offset:3072
	ds_read_b128 v[176:179], v188
	ds_read_b128 v[180:183], v188 offset:1024
	ds_read_b128 v[184:187], v188 offset:2048
	ds_read_b128 v[188:191], v188 offset:3072
	s_add_u32 s10, s48, 0xb0000
	s_addc_u32 s11, s49, 0
	s_mov_b32 m0, s51
	v_lshl_add_u64 v[240:241], s[10:11], 0, v[134:135]
	ds_read_b128 v[192:195], v145 offset:32768
	ds_read_b128 v[196:199], v145 offset:33792
	ds_read_b128 v[200:203], v145 offset:34816
	ds_read_b128 v[204:207], v145 offset:35840
	ds_read_b128 v[208:211], v145 offset:36864
	ds_read_b128 v[212:215], v145 offset:37888
	ds_read_b128 v[216:219], v145 offset:38912
	ds_read_b128 v[220:223], v145 offset:39936
	global_load_lds_dwordx4 v[240:241], off
	v_lshl_add_u64 v[240:241], s[10:11], 0, v[132:133]
	s_mov_b32 m0, s54
	s_nop 0
	global_load_lds_dwordx4 v[240:241], off
	s_waitcnt vmcnt(8)
	s_waitcnt lgkmcnt(0)
	s_setprio 1
	s_barrier
	v_mfma_f32_16x16x32_bf16 v[126:129], v[146:149], v[192:195], v[126:129]
	v_mfma_f32_16x16x32_bf16 v[122:125], v[154:157], v[192:195], v[122:125]
	v_mfma_f32_16x16x32_bf16 v[114:117], v[146:149], v[200:203], v[114:117]
	v_mfma_f32_16x16x32_bf16 v[110:113], v[154:157], v[200:203], v[110:113]
	v_mfma_f32_16x16x32_bf16 v[98:101], v[146:149], v[208:211], v[98:101]
	v_mfma_f32_16x16x32_bf16 v[94:97], v[154:157], v[208:211], v[94:97]
	v_mfma_f32_16x16x32_bf16 v[82:85], v[146:149], v[216:219], v[82:85]
	v_mfma_f32_16x16x32_bf16 v[78:81], v[154:157], v[216:219], v[78:81]
	v_mfma_f32_16x16x32_bf16 v[126:129], v[150:153], v[196:199], v[126:129]
	v_mfma_f32_16x16x32_bf16 v[122:125], v[158:161], v[196:199], v[122:125]
	v_mfma_f32_16x16x32_bf16 v[114:117], v[150:153], v[204:207], v[114:117]
	v_mfma_f32_16x16x32_bf16 v[110:113], v[158:161], v[204:207], v[110:113]
	v_mfma_f32_16x16x32_bf16 v[98:101], v[150:153], v[212:215], v[98:101]
	v_mfma_f32_16x16x32_bf16 v[94:97], v[158:161], v[212:215], v[94:97]
	v_mfma_f32_16x16x32_bf16 v[82:85], v[150:153], v[220:223], v[82:85]
	v_mfma_f32_16x16x32_bf16 v[78:81], v[158:161], v[220:223], v[78:81]
	s_setprio 0
	s_setprio 1
	v_mfma_f32_16x16x32_bf16 v[118:121], v[176:179], v[192:195], v[118:121]
	v_mfma_f32_16x16x32_bf16 v[106:109], v[184:187], v[192:195], v[106:109]
	v_mfma_f32_16x16x32_bf16 v[102:105], v[176:179], v[200:203], v[102:105]
	v_mfma_f32_16x16x32_bf16 v[90:93], v[184:187], v[200:203], v[90:93]
	v_mfma_f32_16x16x32_bf16 v[86:89], v[176:179], v[208:211], v[86:89]
	v_mfma_f32_16x16x32_bf16 v[74:77], v[184:187], v[208:211], v[74:77]
	v_mfma_f32_16x16x32_bf16 v[70:73], v[176:179], v[216:219], v[70:73]
	v_mfma_f32_16x16x32_bf16 v[66:69], v[184:187], v[216:219], v[66:69]
	v_mfma_f32_16x16x32_bf16 v[118:121], v[180:183], v[196:199], v[118:121]
	v_mfma_f32_16x16x32_bf16 v[106:109], v[188:191], v[196:199], v[106:109]
	v_mfma_f32_16x16x32_bf16 v[102:105], v[180:183], v[204:207], v[102:105]
	v_mfma_f32_16x16x32_bf16 v[90:93], v[188:191], v[204:207], v[90:93]
	v_mfma_f32_16x16x32_bf16 v[86:89], v[180:183], v[212:215], v[86:89]
	v_mfma_f32_16x16x32_bf16 v[74:77], v[188:191], v[212:215], v[74:77]
	v_mfma_f32_16x16x32_bf16 v[70:73], v[180:183], v[220:223], v[70:73]
	v_mfma_f32_16x16x32_bf16 v[66:69], v[188:191], v[220:223], v[66:69]
	s_barrier
; #define PG8_STAGE(bufoff, gbase, voff) do { _Pragma("unroll") for (int _i = 0; _i < 2; ++_i) \
;         __builtin_amdgcn_global_load_lds((const unsigned*)((const char*)(gbase) + (voff)[_i]), (PG8_LAS unsigned*)(lds + (bufoff) + ldsw + _i * 8192), 16, 0, 0); } while (0)
; #define PG8_LDA(dst, b, h) do { _Pragma("unroll") for (int m = 0; m < 4; ++m) _Pragma("unroll") for (int k = 0; k < 2; ++k) dst[m][k] = *(const PG8_LAS bf16x8*)(lds + PG8_SA(b, h) + aoff + m * 2048 + k * 1024); } while (0)
; #define PG8_MMA(ai, bj, At, Bt) do { __builtin_amdgcn_s_setprio(1); _Pragma("unroll") for (int m = 0; m < 4; ++m) _Pragma("unroll") for (int n = 0; n < 2; ++n) _Pragma("unroll") for (int k = 0; k < 2; ++k) \
;         acc[ai][bj][m][n] = __builtin_amdgcn_mfma_f32_16x16x32_bf16(Bt[n][k], At[m][k], acc[ai][bj][m][n], 0, 0, 0); __builtin_amdgcn_s_setprio(0); } while (0)
; #define PG8_WAIT_V(n) asm volatile("s_waitcnt vmcnt(" #n ")" ::: "memory")
; #define PG8_WAIT_L(n) asm volatile("s_waitcnt lgkmcnt(" #n ")" ::: "memory")
; #define PG8_BAR __builtin_amdgcn_s_barrier()
; #define PG8_SCHED __builtin_amdgcn_sched_barrier(0)
; template <class Epi, class Sched, bool ALIGN_EPI = false, bool SP2 = false>
; __device__ __forceinline__ void gemm_phase(PG8_LAS unsigned char* lds, const Gemm g, const Sched& S, const Epi& E) {
;     ...
;             PG8_LDA(At, 1, 1); PG8_STAGE(PG8_SB(1, 0), b3, voffB); PG8_STAGE(PG8_SB(1, 1), b3 + hstep, voffB); PG8_STAGE(PG8_SA(1, 0), a3, voffA);
;             PG8_WAIT_V(8); PG8_WAIT_L(0); PG8_BAR; PG8_MMA(1, 0, At, B0); PG8_MMA(1, 1, At, B1); PG8_BAR; PG8_SCHED;
;     ...
;         if constexpr (ALIGN_EPI) { if (wr == 0) PG8_BAR; }
	s_setprio 0
	s_add_i32 s10, s42, s6
	v_lshl_add_u64 v[140:141], v[140:141], 0, s[28:29]
	s_mov_b32 m0, s10
	ds_read_b128 v[192:195], v145 offset:49152
	ds_read_b128 v[196:199], v145 offset:50176
	ds_read_b128 v[200:203], v145 offset:51200
	ds_read_b128 v[204:207], v145 offset:52224
	ds_read_b128 v[208:211], v145 offset:53248
	ds_read_b128 v[212:215], v145 offset:54272
	ds_read_b128 v[216:219], v145 offset:55296
	ds_read_b128 v[220:223], v145 offset:56320
	global_load_lds_dwordx4 v[140:141], off
	s_add_i32 m0, s10, 0x2000
	s_add_u32 s10, s46, 0xb0080
	v_lshl_add_u64 v[140:141], v[224:225], 0, s[28:29]
	s_addc_u32 s11, s47, 0
	s_add_i32 s42, s43, s6
	global_load_lds_dwordx4 v[140:141], off
	v_lshl_add_u64 v[140:141], s[10:11], 0, v[0:1]
	s_mov_b32 m0, s42
	s_nop 0
	global_load_lds_dwordx4 v[140:141], off
	v_lshl_add_u64 v[140:141], s[10:11], 0, v[130:131]
	s_add_i32 m0, s42, 0x2000
	s_nop 0
	global_load_lds_dwordx4 v[140:141], off
	v_lshl_add_u64 v[140:141], v[226:227], 0, s[28:29]
	s_mov_b32 m0, s57
	s_nop 0
	global_load_lds_dwordx4 v[140:141], off
	v_lshl_add_u64 v[140:141], v[238:239], 0, s[28:29]
	s_mov_b32 m0, s58
	s_nop 0
	global_load_lds_dwordx4 v[140:141], off
	s_waitcnt vmcnt(8)
	s_waitcnt lgkmcnt(0)
	s_setprio 1
	s_barrier
	v_mfma_f32_16x16x32_bf16 v[62:65], v[146:149], v[192:195], v[62:65]
	v_mfma_f32_16x16x32_bf16 v[58:61], v[154:157], v[192:195], v[58:61]
	v_mfma_f32_16x16x32_bf16 v[50:53], v[146:149], v[200:203], v[50:53]
	v_mfma_f32_16x16x32_bf16 v[46:49], v[154:157], v[200:203], v[46:49]
	v_mfma_f32_16x16x32_bf16 v[34:37], v[146:149], v[208:211], v[34:37]
	v_mfma_f32_16x16x32_bf16 v[30:33], v[154:157], v[208:211], v[30:33]
	v_mfma_f32_16x16x32_bf16 v[18:21], v[146:149], v[216:219], v[18:21]
	v_mfma_f32_16x16x32_bf16 v[14:17], v[154:157], v[216:219], v[14:17]
	v_mfma_f32_16x16x32_bf16 v[62:65], v[150:153], v[196:199], v[62:65]
	v_mfma_f32_16x16x32_bf16 v[58:61], v[158:161], v[196:199], v[58:61]
	v_mfma_f32_16x16x32_bf16 v[50:53], v[150:153], v[204:207], v[50:53]
	v_mfma_f32_16x16x32_bf16 v[46:49], v[158:161], v[204:207], v[46:49]
	v_mfma_f32_16x16x32_bf16 v[34:37], v[150:153], v[212:215], v[34:37]
	v_mfma_f32_16x16x32_bf16 v[30:33], v[158:161], v[212:215], v[30:33]
	v_mfma_f32_16x16x32_bf16 v[18:21], v[150:153], v[220:223], v[18:21]
	v_mfma_f32_16x16x32_bf16 v[14:17], v[158:161], v[220:223], v[14:17]
	s_setprio 0
	s_setprio 1
	v_mfma_f32_16x16x32_bf16 v[54:57], v[176:179], v[192:195], v[54:57]
	v_mfma_f32_16x16x32_bf16 v[42:45], v[184:187], v[192:195], v[42:45]
	v_mfma_f32_16x16x32_bf16 v[38:41], v[176:179], v[200:203], v[38:41]
	v_mfma_f32_16x16x32_bf16 v[26:29], v[184:187], v[200:203], v[26:29]
	v_mfma_f32_16x16x32_bf16 v[22:25], v[176:179], v[208:211], v[22:25]
	v_mfma_f32_16x16x32_bf16 v[10:13], v[184:187], v[208:211], v[10:13]
	v_mfma_f32_16x16x32_bf16 v[6:9], v[176:179], v[216:219], v[6:9]
	v_mfma_f32_16x16x32_bf16 v[2:5], v[184:187], v[216:219], v[2:5]
	v_mfma_f32_16x16x32_bf16 v[54:57], v[180:183], v[196:199], v[54:57]
	v_mfma_f32_16x16x32_bf16 v[42:45], v[188:191], v[196:199], v[42:45]
	v_mfma_f32_16x16x32_bf16 v[38:41], v[180:183], v[204:207], v[38:41]
	v_mfma_f32_16x16x32_bf16 v[26:29], v[188:191], v[204:207], v[26:29]
	v_mfma_f32_16x16x32_bf16 v[22:25], v[180:183], v[212:215], v[22:25]
	v_mfma_f32_16x16x32_bf16 v[10:13], v[188:191], v[212:215], v[10:13]
	v_mfma_f32_16x16x32_bf16 v[6:9], v[180:183], v[220:223], v[6:9]
	v_mfma_f32_16x16x32_bf16 v[2:5], v[188:191], v[220:223], v[2:5]
	s_barrier
	s_setprio 0
	s_add_i32 s68, s68, 2
	s_add_u32 s66, s66, 0x100
	s_addc_u32 s67, s67, 0
	s_cmp_gt_u32 s68, 41
	s_mov_b64 s[42:43], s[40:41]
	s_cbranch_scc0 .LBB0_1295
	s_and_b64 vcc, exec, s[22:23]
	s_cbranch_vccz .LBB0_1298
	s_barrier
